# HGRN/mLSTM chunk loops: packed f32 VOP3P ops split into scalar pairs (bit-identical) to see which form issues cheaper in the VALU-bound loops
# baseline (speedup 1.0000x reference)
; DI size_t kblk(int row, int col, int nrows) { return ((size_t)(col >> 5) * nrows + row) * 32 + (col & 31); }
; DI unsigned pk2(float a, float b) { hwf32x2 f = {a, b}; hwbf16x2 r = __builtin_convertvector(f, hwbf16x2); return __builtin_bit_cast(unsigned, r); }
; #define MFMA16(a, b, c) __builtin_amdgcn_mfma_f32_16x16x32_bf16((a), (b), (c), 0, 0, 0)
; template <int MX, bool OUT>
; DI void rec_chunk(const Params& p, int l, int b, int h, int dir, int T0, unsigned char* smem, f32x4 (&St)[4], float& nst, float& dtot, int tid, const RecRaw& raw) {
;     ...
; #pragma unroll
;     for (int ks = 0; ks < 2; ++ks) {
;       const bf16x8 fb = *(const bf16x8*)(smem + L_QS + swz(t, ks * 4 + g));
; #pragma unroll
;       for (int a = 0; a < 4; ++a) {
;         const bf16x8 fa = *(const bf16x8*)(smem + L_STT + swz(16 * a + col, ks * 4 + g));
;         O[a] = MFMA16(fa, fb, O[a]);
;       }
;     }
;     if (MX == 1) {
;       const float inv = 1.f / fmaxf(fabsf(den), 1.f);
; #pragma unroll
;       for (int a = 0; a < 4; ++a)
; #pragma unroll
;         for (int j = 0; j < 4; ++j) O[a][j] *= inv;
;     }
;     if (dir == 0) {
; #pragma unroll
;       for (int a = 0; a < 4; ++a) *(uint2*)(MIX + kblk((int)orow, cb + 16 * a + 4 * g, ROWS)) = make_uint2(pk2(O[a][0], O[a][1]), pk2(O[a][2], O[a][3]));
;     } else {
;       float ss = 0.f;
; #pragma unroll
;       for (int a = 0; a < 4; ++a) {
;         const uint2 u = *(const uint2*)(MIX + kblk((int)orow, cb + 16 * a + 4 * g, ROWS));
;         O[a][0] += __uint_as_float(u.x << 16); O[a][1] += __uint_as_float(u.x & 0xffff0000u);
;         O[a][2] += __uint_as_float(u.y << 16); O[a][3] += __uint_as_float(u.y & 0xffff0000u);
; #pragma unroll
;         for (int j = 0; j < 4; ++j) ss += O[a][j] * O[a][j];
;       }
;       ss += __shfl_xor(ss, 16);
;       ss += __shfl_xor(ss, 32);
.LBB0_683:
	s_or_b64 exec, exec, s[0:1]
	ds_read_b128 v[42:45], v240 offset:32768
	ds_read_b128 v[46:49], v238 offset:57344
	ds_read_b128 v[50:53], v238 offset:59392
	s_add_i32 s0, s13, -1
	v_mov_b32_e32 v40, s0
	v_cndmask_b32_e64 v40, v91, v40, s[24:25]
	s_waitcnt lgkmcnt(1)
	v_mfma_f32_16x16x32_bf16 v[46:49], v[46:49], v[42:45], v[56:59]
	v_lshlrev_b32_e32 v40, 6, v40
	v_add_u32_e32 v160, s12, v40
	v_lshl_add_u64 v[40:41], v[160:161], 0, v[82:83]
	ds_read_b128 v[54:57], v238 offset:61440
	s_waitcnt lgkmcnt(1)
	v_mfma_f32_16x16x32_bf16 v[50:53], v[50:53], v[42:45], v[60:63]
	s_nop 2
	ds_read_b128 v[58:61], v238 offset:63488
	s_waitcnt lgkmcnt(1)
	v_mfma_f32_16x16x32_bf16 v[54:57], v[54:57], v[42:45], v[64:67]
	s_waitcnt lgkmcnt(0)
	v_mfma_f32_16x16x32_bf16 v[42:45], v[58:61], v[42:45], v[72:75]
	ds_read_b128 v[58:61], v239 offset:32768
	ds_read_b128 v[62:65], v237 offset:57344
	s_waitcnt lgkmcnt(0)
	v_mfma_f32_16x16x32_bf16 v[46:49], v[62:65], v[58:61], v[46:49]
	ds_read_b128 v[62:65], v237 offset:59392
	s_waitcnt lgkmcnt(0)
	v_mfma_f32_16x16x32_bf16 v[50:53], v[62:65], v[58:61], v[50:53]
	ds_read_b128 v[62:65], v237 offset:61440
	s_waitcnt lgkmcnt(0)
	v_mfma_f32_16x16x32_bf16 v[62:65], v[62:65], v[58:61], v[54:57]
	s_nop 2
	ds_read_b128 v[54:57], v237 offset:63488
	s_waitcnt lgkmcnt(0)
	v_mfma_f32_16x16x32_bf16 v[42:45], v[54:57], v[58:61], v[42:45]
	v_add_f32_e32 v54, v93, v96
	v_max_f32_e64 v54, |v54|, 1.0
	v_rcp_f32_e32 v56, v54
	s_mov_b64 s[0:1], -1
	v_fma_f32 v57, -v54, v56, 1.0
	v_fmac_f32_e32 v56, v57, v56
	v_mov_b32_e64 v57, 1.0
	v_mul_f32_e32 v58, v57, v56
	v_fma_f32 v59, -v54, v58, v57
	v_fmac_f32_e32 v58, v59, v56
	v_fma_f32 v55, -v54, v58, v57
	v_fma_f32 v55, v55, v56, v58
	v_div_fixup_f32 v60, v55, v54, 1.0
	v_mul_f32_e32 v54, v60, v46
	v_mul_f32_e32 v55, v60, v47
	v_mul_f32_e32 v46, v60, v42
	v_mul_f32_e32 v47, v60, v43
	v_ashrrev_i32_e32 v43, 31, v40
	v_mov_b32_e32 v42, v40
	v_mul_f32_e32 v58, v60, v48
	v_mul_f32_e32 v59, v60, v49
	v_mul_f32_e32 v50, v60, v50
	v_mul_f32_e32 v51, v60, v51
	v_mul_f32_e32 v56, v60, v52
	v_mul_f32_e32 v57, v60, v53
	v_mul_f32_e32 v48, v60, v62
	v_mul_f32_e32 v49, v60, v63
	v_mul_f32_e32 v52, v60, v64
	v_mul_f32_e32 v53, v60, v65
	v_mul_f32_e32 v44, v60, v44
	v_mul_f32_e32 v45, v60, v45
	v_lshl_add_u64 v[60:61], v[42:43], 0, s[28:29]
	v_lshl_add_u64 v[62:63], v[42:43], 0, s[30:31]
	v_lshl_add_u64 v[42:43], v[42:43], 0, s[42:43]
	s_andn2_b64 vcc, exec, s[44:45]
	v_lshlrev_b64 v[64:65], 6, v[60:61]
	v_lshlrev_b64 v[62:63], 6, v[62:63]
	v_lshlrev_b64 v[60:61], 6, v[42:43]
	s_cbranch_vccnz .LBB0_685
	v_lshl_add_u64 v[98:99], v[88:89], 0, v[62:63]
	global_load_dwordx2 v[66:67], v[98:99], off
	v_mov_b64_e32 v[42:43], s[18:19]
	v_mad_u64_u32 v[42:43], s[0:1], v40, s33, v[42:43]
	v_mad_i32_i24 v43, v41, s33, v43
	s_mov_b64 s[0:1], 0x1a20
	v_mov_b32_e32 v91, v161
	v_lshl_add_u64 v[74:75], v[42:43], 0, s[0:1]
	v_lshl_add_u64 v[100:101], v[74:75], 0, s[2:3]
	v_lshl_add_u64 v[74:75], v[74:75], 0, v[90:91]
	v_lshl_add_u64 v[102:103], v[84:85], 0, v[64:65]
	v_lshl_add_u64 v[74:75], v[74:75], 0, s[2:3]
	global_load_dwordx2 v[40:41], v[102:103], off
	s_mov_b32 s21, s3
	v_lshl_add_u64 v[42:43], v[42:43], 0, s[20:21]
	v_lshl_add_u64 v[42:43], v[42:43], 0, v[90:91]
	s_mov_b64 s[0:1], 0x1820
	v_lshl_add_u64 v[100:101], v[100:101], 0, v[90:91]
	global_load_dwordx2 v[74:75], v[74:75], off
	s_waitcnt vmcnt(0) lgkmcnt(0)
	v_lshlrev_b32_e32 v96, 16, v66
	v_and_b32_e32 v97, 0xffff0000, v66
	v_lshlrev_b32_e32 v104, 16, v67
	v_and_b32_e32 v105, 0xffff0000, v67
	v_lshl_add_u64 v[66:67], s[22:23], 0, v[60:61]
	v_lshl_add_u64 v[72:73], v[66:67], 0, v[90:91]
	global_load_dwordx2 v[68:69], v[72:73], off
	v_add_f32_e32 v246, v50, v96
	v_add_f32_e32 v247, v51, v97
	v_lshlrev_b32_e32 v124, 16, v40
	v_and_b32_e32 v125, 0xffff0000, v40
	v_lshlrev_b32_e32 v40, 16, v41
	v_and_b32_e32 v41, 0xffff0000, v41
	v_add_f32_e32 v124, v54, v124
	v_add_f32_e32 v125, v55, v125
	v_mul_f32_e32 v96, v246, v246
	v_mul_f32_e32 v97, v247, v247
	v_lshlrev_b32_e32 v93, 16, v74
	v_and_b32_e32 v160, 0xffff0000, v74
	v_lshlrev_b32_e32 v126, 16, v75
	v_and_b32_e32 v127, 0xffff0000, v75
	v_lshl_add_u64 v[74:75], v[42:43], 0, s[0:1]
	v_add_co_u32_e32 v42, vcc, s16, v42
	v_mul_f32_e32 v116, 0xbfb8aa3b, v126
	s_nop 0
	v_addc_co_u32_e32 v43, vcc, 0, v43, vcc
	v_mul_f32_e32 v117, 0xbfb8aa3b, v127
	global_load_dwordx2 v[42:43], v[42:43], off offset:2080
	v_exp_f32_e32 v116, v116
	v_exp_f32_e32 v117, v117
	s_waitcnt vmcnt(0) lgkmcnt(0)
; DI size_t kblk(int row, int col, int nrows) { return ((size_t)(col >> 5) * nrows + row) * 32 + (col & 31); }
; DI unsigned pk2(float a, float b) { hwf32x2 f = {a, b}; hwbf16x2 r = __builtin_convertvector(f, hwbf16x2); return __builtin_bit_cast(unsigned, r); }
; DI float sigmoidf_(float z) { return 1.f / (1.f + __expf(-z)); }
; DI float siluf_(float z) { return z / (1.f + __expf(-z)); }
; template <int MX, bool OUT>
; DI void rec_chunk(const Params& p, int l, int b, int h, int dir, int T0, unsigned char* smem, f32x4 (&St)[4], float& nst, float& dtot, int tid, const RecRaw& raw) {
;     ...
;       float ss = 0.f;
; #pragma unroll
;       for (int a = 0; a < 4; ++a) {
;         const uint2 u = *(const uint2*)(MIX + kblk((int)orow, cb + 16 * a + 4 * g, ROWS));
;         O[a][0] += __uint_as_float(u.x << 16); O[a][1] += __uint_as_float(u.x & 0xffff0000u);
;         O[a][2] += __uint_as_float(u.y << 16); O[a][3] += __uint_as_float(u.y & 0xffff0000u);
; #pragma unroll
;         for (int j = 0; j < 4; ++j) ss += O[a][j] * O[a][j];
;       }
;       ss += __shfl_xor(ss, 16);
;       ss += __shfl_xor(ss, 32);
;       const float rstd = rsqrtf(ss * (1.f / 64.f) + EPS);
;       const float* gvec = (MX ? p.ml_g : p.hg_g) + l * 64;
; #pragma unroll
;       for (int a = 0; a < 4; ++a) {
;         const int v0 = 16 * a + 4 * g;
;         const uint2 gt = *(const uint2*)(prow + GATE + cb + v0);
;         const float4 gg = *(const float4*)(gvec + v0);
;         float y0 = O[a][0] * rstd * gg.x * siluf_(__uint_as_float(gt.x << 16));
;         float y1 = O[a][1] * rstd * gg.y * siluf_(__uint_as_float(gt.x & 0xffff0000u));
;         float y2 = O[a][2] * rstd * gg.z * siluf_(__uint_as_float(gt.y << 16));
;         float y3 = O[a][3] * rstd * gg.w * siluf_(__uint_as_float(gt.y & 0xffff0000u));
;         if (MX == 1) {
;           const uint2 og = *(const uint2*)(prow + D_OG + h * 64 + v0);
;           y0 *= sigmoidf_(__uint_as_float(og.x << 16)); y1 *= sigmoidf_(__uint_as_float(og.x & 0xffff0000u));
;           y2 *= sigmoidf_(__uint_as_float(og.y << 16)); y3 *= sigmoidf_(__uint_as_float(og.y & 0xffff0000u));
;         }
;         *(uint2*)(MIX + kblk((int)orow, cb + v0, ROWS)) = make_uint2(pk2(y0, y1), pk2(y2, y3));
	v_lshlrev_b32_e32 v106, 16, v68
	v_and_b32_e32 v107, 0xffff0000, v68
	v_add_f32_e32 v116, 1.0, v116
	v_add_f32_e32 v117, 1.0, v117
	v_lshlrev_b32_e32 v108, 16, v69
	v_rcp_f32_e32 v129, v117
	v_and_b32_e32 v109, 0xffff0000, v69
	global_load_dwordx2 v[68:69], v[72:73], off offset:32
	v_add_f32_e32 v106, v48, v106
	v_add_f32_e32 v107, v49, v107
	v_fma_f32 v241, -v117, v129, 1.0
	v_fmac_f32_e32 v129, v241, v129
	v_mul_f32_e32 v242, v127, v129
	v_fma_f32 v243, -v117, v242, v127
	v_fmac_f32_e32 v242, v243, v129
	v_fma_f32 v128, -v117, v242, v127
	v_fma_f32 v128, v128, v129, v242
	v_div_fixup_f32 v117, v128, v117, v127
	v_rcp_f32_e32 v128, v116
	v_mul_f32_e32 v248, v106, v106
	v_mul_f32_e32 v249, v107, v107
	v_lshlrev_b32_e32 v114, 16, v42
	v_and_b32_e32 v42, 0xffff0000, v42
	v_fma_f32 v129, -v116, v128, 1.0
	v_fmac_f32_e32 v128, v129, v128
	v_mul_f32_e32 v241, v126, v128
	v_fma_f32 v242, -v116, v241, v126
	v_fmac_f32_e32 v241, v242, v128
	v_fma_f32 v127, -v116, v241, v126
	v_fma_f32 v127, v127, v128, v241
	v_mul_f32_e32 v128, 0xbfb8aa3b, v93
	v_mul_f32_e32 v129, 0xbfb8aa3b, v160
	v_exp_f32_e32 v128, v128
	v_exp_f32_e32 v129, v129
	v_div_fixup_f32 v116, v127, v116, v126
	v_mul_f32_e32 v126, v124, v124
	v_mul_f32_e32 v127, v125, v125
	v_mul_f32_e32 v114, 0xbfb8aa3b, v114
	v_add_f32_e32 v128, 1.0, v128
	v_add_f32_e32 v129, 1.0, v129
	v_mul_f32_e32 v42, 0xbfb8aa3b, v42
	v_rcp_f32_e32 v242, v129
	v_add_f32_e32 v91, v126, v127
	v_exp_f32_e32 v122, v114
	v_exp_f32_e32 v123, v42
	v_fma_f32 v243, -v129, v242, 1.0
	v_fmac_f32_e32 v242, v243, v242
	v_mul_f32_e32 v244, v160, v242
	v_fma_f32 v245, -v129, v244, v160
	v_fmac_f32_e32 v244, v245, v242
	v_fma_f32 v241, -v129, v244, v160
	v_fma_f32 v241, v241, v242, v244
	v_div_fixup_f32 v129, v241, v129, v160
	v_rcp_f32_e32 v241, v128
	v_lshlrev_b32_e32 v42, 16, v43
	v_add_f32_e32 v114, v58, v40
	v_add_f32_e32 v115, v59, v41
	v_mul_f32_e32 v42, 0xbfb8aa3b, v42
	v_fma_f32 v242, -v128, v241, 1.0
	v_fmac_f32_e32 v241, v242, v241
	v_mul_f32_e32 v243, v93, v241
	v_fma_f32 v244, -v128, v243, v93
	v_fmac_f32_e32 v243, v244, v241
	v_fma_f32 v160, -v128, v243, v93
	v_fma_f32 v160, v160, v241, v243
	v_div_fixup_f32 v128, v160, v128, v93
	v_mul_f32_e32 v118, v114, v114
	v_mul_f32_e32 v119, v115, v115
	v_exp_f32_e32 v120, v42
	v_and_b32_e32 v42, 0xffff0000, v43
	v_add_f32_e32 v91, v91, v118
	v_mul_f32_e32 v42, 0xbfb8aa3b, v42
	v_add_f32_e32 v91, v119, v91
	v_add_f32_e32 v122, 1.0, v122
	v_add_f32_e32 v123, 1.0, v123
	v_exp_f32_e32 v121, v42
	global_load_dwordx4 v[40:43], v[86:87], off
	v_rcp_f32_e32 v160, v123
	v_add_f32_e32 v120, 1.0, v120
	v_add_f32_e32 v121, 1.0, v121
	v_add_f32_e32 v91, v96, v91
	v_add_f32_e32 v91, v97, v91
	v_fma_f32 v241, -v123, v160, 1.0
	v_fmac_f32_e32 v160, v241, v160
	v_mov_b32_e64 v241, 1.0
	v_mul_f32_e32 v242, v241, v160
	v_fma_f32 v243, -v123, v242, v241
	v_fmac_f32_e32 v242, v243, v160
	v_fma_f32 v93, -v123, v242, v241
	v_fma_f32 v93, v93, v160, v242
	v_div_fixup_f32 v123, v93, v123, 1.0
	v_rcp_f32_e32 v160, v122
	s_waitcnt vmcnt(0) lgkmcnt(0)
	v_lshlrev_b32_e32 v70, 16, v68
	v_and_b32_e32 v71, 0xffff0000, v68
	v_add_f32_e32 v70, v46, v70
	v_add_f32_e32 v71, v47, v71
	v_fma_f32 v241, -v122, v160, 1.0
	v_fmac_f32_e32 v160, v241, v160
	v_mov_b32_e64 v241, 1.0
	v_mul_f32_e32 v242, v241, v160
	v_fma_f32 v243, -v122, v242, v241
	v_fmac_f32_e32 v242, v243, v160
	v_fma_f32 v93, -v122, v242, v241
	v_fma_f32 v93, v93, v160, v242
	v_div_fixup_f32 v122, v93, v122, 1.0
	v_rcp_f32_e32 v160, v121
	v_lshlrev_b32_e32 v68, 16, v69
	v_and_b32_e32 v69, 0xffff0000, v69
	v_mul_f32_e32 v110, v70, v70
	v_mul_f32_e32 v111, v71, v71
	v_fma_f32 v241, -v121, v160, 1.0
	v_fmac_f32_e32 v160, v241, v160
	v_mov_b32_e64 v241, 1.0
	v_mul_f32_e32 v242, v241, v160
	v_fma_f32 v243, -v121, v242, v241
	v_fmac_f32_e32 v242, v243, v160
	v_fma_f32 v93, -v121, v242, v241
	v_fma_f32 v93, v93, v160, v242
	v_div_fixup_f32 v121, v93, v121, 1.0
	v_rcp_f32_e32 v160, v120
	v_add_f32_e32 v68, v44, v68
	v_add_f32_e32 v69, v45, v69
	v_fma_f32 v241, -v120, v160, 1.0
	v_fmac_f32_e32 v160, v241, v160
	v_mov_b32_e64 v241, 1.0
	v_mul_f32_e32 v242, v241, v160
	v_fma_f32 v243, -v120, v242, v241
	v_fmac_f32_e32 v242, v243, v160
	v_fma_f32 v93, -v120, v242, v241
	v_fma_f32 v93, v93, v160, v242
	v_add_f32_e32 v242, v56, v104
	v_add_f32_e32 v243, v57, v105
	v_add_f32_e32 v104, v52, v108
	v_add_f32_e32 v105, v53, v109
	v_mul_f32_e32 v244, v242, v242
	v_mul_f32_e32 v245, v243, v243
	v_mul_f32_e32 v108, v104, v104
	v_mul_f32_e32 v109, v105, v105
	v_add_f32_e32 v91, v244, v91
	v_add_f32_e32 v91, v245, v91
	v_add_f32_e32 v91, v248, v91
	v_add_f32_e32 v91, v249, v91
	v_add_f32_e32 v91, v108, v91
	v_add_f32_e32 v91, v109, v91
	v_add_f32_e32 v91, v110, v91
	v_mul_f32_e32 v112, v68, v68
	v_mul_f32_e32 v113, v69, v69
	v_add_f32_e32 v91, v111, v91
	v_add_f32_e32 v91, v112, v91
	v_add_f32_e32 v91, v113, v91
	v_div_fixup_f32 v120, v93, v120, 1.0
	ds_bpermute_b32 v93, v145, v91
	s_waitcnt lgkmcnt(0)
	v_add_f32_e32 v91, v91, v93
	ds_bpermute_b32 v93, v146, v91
	s_waitcnt lgkmcnt(0)
	v_add_f32_e32 v91, v91, v93
	v_fmamk_f32 v91, v91, 0x3c800000, v162
	v_cmp_gt_f32_e32 vcc, s38, v91
	v_mul_f32_e32 v93, 0x4b800000, v91
	s_nop 0
	v_cndmask_b32_e32 v91, v91, v93, vcc
	v_rsq_f32_e32 v91, v91
	s_nop 0
	v_mul_f32_e32 v93, 0x45800000, v91
	v_cndmask_b32_e32 v96, v91, v93, vcc
	v_mul_f32_e32 v108, v124, v96
	v_mul_f32_e32 v109, v125, v96
	s_nop 0
	v_mul_f32_e32 v40, v40, v108
	v_mul_f32_e32 v41, v41, v109
	v_mul_f32_e32 v108, v114, v96
	v_mul_f32_e32 v109, v115, v96
	v_mul_f32_e32 v40, v128, v40
	v_mul_f32_e32 v41, v129, v41
	v_mul_f32_e32 v42, v42, v108
	v_mul_f32_e32 v43, v43, v109
	v_mul_f32_e32 v40, v122, v40
	v_mul_f32_e32 v41, v123, v41
	v_mul_f32_e32 v42, v116, v42
	v_mul_f32_e32 v43, v117, v43
	v_cvt_pk_bf16_f32 v40, v40, v41
	v_mul_f32_e32 v42, v120, v42
	v_mul_f32_e32 v43, v121, v43
	s_nop 0
	v_cvt_pk_bf16_f32 v41, v42, v43
	global_store_dwordx2 v[102:103], v[40:41], off
	global_load_dwordx2 v[40:41], v[100:101], off offset:32
	s_nop 0
	global_load_dwordx4 v[108:111], v[86:87], off offset:64
	v_mul_f32_e32 v102, v246, v96
	v_mul_f32_e32 v103, v247, v96
	s_waitcnt vmcnt(0) lgkmcnt(0)
; DI size_t kblk(int row, int col, int nrows) { return ((size_t)(col >> 5) * nrows + row) * 32 + (col & 31); }
; DI unsigned pk2(float a, float b) { hwf32x2 f = {a, b}; hwbf16x2 r = __builtin_convertvector(f, hwbf16x2); return __builtin_bit_cast(unsigned, r); }
; DI float sigmoidf_(float z) { return 1.f / (1.f + __expf(-z)); }
; DI float siluf_(float z) { return z / (1.f + __expf(-z)); }
; template <int MX, bool OUT>
; DI void rec_chunk(const Params& p, int l, int b, int h, int dir, int T0, unsigned char* smem, f32x4 (&St)[4], float& nst, float& dtot, int tid, const RecRaw& raw) {
;     ...
; #pragma unroll
;       for (int a = 0; a < 4; ++a) {
;         const int v0 = 16 * a + 4 * g;
;         const uint2 gt = *(const uint2*)(prow + GATE + cb + v0);
;         const float4 gg = *(const float4*)(gvec + v0);
;         float y0 = O[a][0] * rstd * gg.x * siluf_(__uint_as_float(gt.x << 16));
;         float y1 = O[a][1] * rstd * gg.y * siluf_(__uint_as_float(gt.x & 0xffff0000u));
;         float y2 = O[a][2] * rstd * gg.z * siluf_(__uint_as_float(gt.y << 16));
;         float y3 = O[a][3] * rstd * gg.w * siluf_(__uint_as_float(gt.y & 0xffff0000u));
;         if (MX == 1) {
;           const uint2 og = *(const uint2*)(prow + D_OG + h * 64 + v0);
;           y0 *= sigmoidf_(__uint_as_float(og.x << 16)); y1 *= sigmoidf_(__uint_as_float(og.x & 0xffff0000u));
;           y2 *= sigmoidf_(__uint_as_float(og.y << 16)); y3 *= sigmoidf_(__uint_as_float(og.y & 0xffff0000u));
;         }
;         *(uint2*)(MIX + kblk((int)orow, cb + v0, ROWS)) = make_uint2(pk2(y0, y1), pk2(y2, y3));
	v_lshlrev_b32_e32 v91, 16, v40
	v_and_b32_e32 v40, 0xffff0000, v40
	v_mul_f32_e32 v42, 0xbfb8aa3b, v91
	v_mul_f32_e32 v43, 0xbfb8aa3b, v40
	v_exp_f32_e32 v42, v42
	v_exp_f32_e32 v43, v43
	v_mul_f32_e32 v102, v108, v102
	v_mul_f32_e32 v103, v109, v103
	v_add_f32_e32 v42, 1.0, v42
	v_add_f32_e32 v43, 1.0, v43
	s_nop 0
	v_rcp_f32_e32 v97, v43
	s_nop 0
	v_fma_f32 v108, -v43, v97, 1.0
	v_fmac_f32_e32 v97, v108, v97
	v_mul_f32_e32 v109, v40, v97
	v_fma_f32 v112, -v43, v109, v40
	v_fmac_f32_e32 v109, v112, v97
	v_fma_f32 v93, -v43, v109, v40
	v_fma_f32 v93, v93, v97, v109
	v_div_fixup_f32 v43, v93, v43, v40
	v_rcp_f32_e32 v93, v42
	s_nop 0
	v_fma_f32 v97, -v42, v93, 1.0
	v_fmac_f32_e32 v93, v97, v93
	v_mul_f32_e32 v108, v91, v93
	v_fma_f32 v109, -v42, v108, v91
	v_fmac_f32_e32 v108, v109, v93
	v_fma_f32 v40, -v42, v108, v91
	v_fma_f32 v40, v40, v93, v108
	v_div_fixup_f32 v42, v40, v42, v91
	v_lshlrev_b32_e32 v91, 16, v41
	v_and_b32_e32 v93, 0xffff0000, v41
	v_mul_f32_e32 v40, 0xbfb8aa3b, v91
	v_mul_f32_e32 v41, 0xbfb8aa3b, v93
	v_exp_f32_e32 v40, v40
	v_exp_f32_e32 v41, v41
	v_mul_f32_e32 v42, v42, v102
	v_mul_f32_e32 v43, v43, v103
	v_mul_f32_e32 v102, v242, v96
	v_mul_f32_e32 v103, v243, v96
	v_add_f32_e32 v40, 1.0, v40
	v_add_f32_e32 v41, 1.0, v41
	s_nop 0
	v_rcp_f32_e32 v108, v41
	v_mul_f32_e32 v102, v110, v102
	v_mul_f32_e32 v103, v111, v103
	v_fma_f32 v109, -v41, v108, 1.0
	v_fmac_f32_e32 v108, v109, v108
	v_mul_f32_e32 v110, v93, v108
	v_fma_f32 v111, -v41, v110, v93
	v_fmac_f32_e32 v110, v111, v108
	v_fma_f32 v97, -v41, v110, v93
	v_fma_f32 v97, v97, v108, v110
	v_div_fixup_f32 v41, v97, v41, v93
	v_rcp_f32_e32 v97, v40
	s_nop 0
	v_fma_f32 v108, -v40, v97, 1.0
	v_fmac_f32_e32 v97, v108, v97
	v_mul_f32_e32 v109, v91, v97
	v_fma_f32 v110, -v40, v109, v91
	v_fmac_f32_e32 v109, v110, v97
	v_fma_f32 v93, -v40, v109, v91
	v_fma_f32 v93, v93, v97, v109
	v_div_fixup_f32 v40, v93, v40, v91
	v_mul_f32_e32 v40, v40, v102
	v_mul_f32_e32 v41, v41, v103
	global_load_dwordx2 v[102:103], v[74:75], off offset:32
	s_waitcnt vmcnt(0) lgkmcnt(0)
	v_lshlrev_b32_e32 v91, 16, v102
	v_mul_f32_e32 v91, 0xbfb8aa3b, v91
	v_exp_f32_e32 v108, v91
	v_and_b32_e32 v91, 0xffff0000, v102
	v_mul_f32_e32 v91, 0xbfb8aa3b, v91
	v_exp_f32_e32 v109, v91
	s_nop 0
	v_add_f32_e32 v108, 1.0, v108
	v_add_f32_e32 v109, 1.0, v109
	s_nop 0
	v_rcp_f32_e32 v93, v109
	s_nop 0
	v_fma_f32 v97, -v109, v93, 1.0
	v_fmac_f32_e32 v93, v97, v93
	v_mov_b32_e64 v97, 1.0
	v_mul_f32_e32 v102, v97, v93
	v_fma_f32 v110, -v109, v102, v97
	v_fmac_f32_e32 v102, v110, v93
	v_fma_f32 v91, -v109, v102, v97
	v_fma_f32 v91, v91, v93, v102
	v_div_fixup_f32 v109, v91, v109, 1.0
	v_rcp_f32_e32 v93, v108
	s_nop 0
	v_fma_f32 v97, -v108, v93, 1.0
	v_fmac_f32_e32 v93, v97, v93
	v_mov_b32_e64 v97, 1.0
	v_mul_f32_e32 v102, v97, v93
	v_fma_f32 v110, -v108, v102, v97
	v_fmac_f32_e32 v102, v110, v93
	v_fma_f32 v91, -v108, v102, v97
	v_fma_f32 v91, v91, v93, v102
	v_div_fixup_f32 v108, v91, v108, 1.0
	v_lshlrev_b32_e32 v91, 16, v103
	v_mul_f32_e32 v91, 0xbfb8aa3b, v91
	v_exp_f32_e32 v102, v91
	v_and_b32_e32 v91, 0xffff0000, v103
	v_mul_f32_e32 v91, 0xbfb8aa3b, v91
	v_exp_f32_e32 v103, v91
	v_mul_f32_e32 v42, v42, v108
	v_mul_f32_e32 v43, v43, v109
	v_add_f32_e32 v102, 1.0, v102
	v_add_f32_e32 v103, 1.0, v103
	s_nop 0
	v_rcp_f32_e32 v93, v103
	v_cvt_pk_bf16_f32 v42, v42, v43
	v_fma_f32 v97, -v103, v93, 1.0
	v_fmac_f32_e32 v93, v97, v93
	v_mov_b32_e64 v97, 1.0
	v_mul_f32_e32 v108, v97, v93
	v_fma_f32 v109, -v103, v108, v97
	v_fmac_f32_e32 v108, v109, v93
	v_fma_f32 v91, -v103, v108, v97
	v_fma_f32 v91, v91, v93, v108
	v_div_fixup_f32 v103, v91, v103, 1.0
	v_rcp_f32_e32 v93, v102
	s_nop 0
	v_fma_f32 v97, -v102, v93, 1.0
	v_fmac_f32_e32 v93, v97, v93
	v_mov_b32_e64 v97, 1.0
	v_mul_f32_e32 v108, v97, v93
	v_fma_f32 v109, -v102, v108, v97
	v_fmac_f32_e32 v108, v109, v93
	v_fma_f32 v91, -v102, v108, v97
	v_fma_f32 v91, v91, v93, v108
	v_div_fixup_f32 v102, v91, v102, 1.0
	v_mul_f32_e32 v40, v40, v102
	v_mul_f32_e32 v41, v41, v103
	s_nop 0
	v_cvt_pk_bf16_f32 v43, v40, v41
	global_store_dwordx2 v[98:99], v[42:43], off
	global_load_dwordx2 v[40:41], v[100:101], off offset:64
	global_load_dwordx4 v[108:111], v[86:87], off offset:128
	v_mul_f32_e32 v98, v106, v96
	v_mul_f32_e32 v99, v107, v96
	s_waitcnt vmcnt(0) lgkmcnt(0)
	v_lshlrev_b32_e32 v91, 16, v40
	v_and_b32_e32 v40, 0xffff0000, v40
	v_mul_f32_e32 v42, 0xbfb8aa3b, v91
	v_mul_f32_e32 v43, 0xbfb8aa3b, v40
	v_exp_f32_e32 v42, v42
	v_exp_f32_e32 v43, v43
	v_mul_f32_e32 v98, v98, v108
	v_mul_f32_e32 v99, v99, v109
	v_add_f32_e32 v42, 1.0, v42
	v_add_f32_e32 v43, 1.0, v43
	s_nop 0
	v_rcp_f32_e32 v97, v43
	s_nop 0
	v_fma_f32 v102, -v43, v97, 1.0
	v_fmac_f32_e32 v97, v102, v97
	v_mul_f32_e32 v103, v40, v97
	v_fma_f32 v106, -v43, v103, v40
	v_fmac_f32_e32 v103, v106, v97
	v_fma_f32 v93, -v43, v103, v40
	v_fma_f32 v93, v93, v97, v103
	v_div_fixup_f32 v43, v93, v43, v40
	v_rcp_f32_e32 v93, v42
	s_nop 0
	v_fma_f32 v97, -v42, v93, 1.0
	v_fmac_f32_e32 v93, v97, v93
	v_mul_f32_e32 v102, v91, v93
	v_fma_f32 v103, -v42, v102, v91
	v_fmac_f32_e32 v102, v103, v93
	v_fma_f32 v40, -v42, v102, v91
	v_fma_f32 v40, v40, v93, v102
	v_div_fixup_f32 v42, v40, v42, v91
	v_lshlrev_b32_e32 v91, 16, v41
	v_and_b32_e32 v93, 0xffff0000, v41
	v_mul_f32_e32 v40, 0xbfb8aa3b, v91
	v_mul_f32_e32 v41, 0xbfb8aa3b, v93
	v_exp_f32_e32 v40, v40
	v_exp_f32_e32 v41, v41
	v_mul_f32_e32 v42, v98, v42
	v_mul_f32_e32 v43, v99, v43
	v_mul_f32_e32 v98, v104, v96
	v_mul_f32_e32 v99, v105, v96
	v_add_f32_e32 v40, 1.0, v40
	v_add_f32_e32 v41, 1.0, v41
	s_nop 0
	v_rcp_f32_e32 v102, v41
	v_mul_f32_e32 v98, v98, v110
	v_mul_f32_e32 v99, v99, v111
	v_fma_f32 v103, -v41, v102, 1.0
	v_fmac_f32_e32 v102, v103, v102
	v_mul_f32_e32 v104, v93, v102
	v_fma_f32 v105, -v41, v104, v93
	v_fmac_f32_e32 v104, v105, v102
	v_fma_f32 v97, -v41, v104, v93
	v_fma_f32 v97, v97, v102, v104
	v_div_fixup_f32 v41, v97, v41, v93
	v_rcp_f32_e32 v97, v40
	s_nop 0
	v_fma_f32 v102, -v40, v97, 1.0
	v_fmac_f32_e32 v97, v102, v97
	v_mul_f32_e32 v103, v91, v97
	v_fma_f32 v104, -v40, v103, v91
	v_fmac_f32_e32 v103, v104, v97
	v_fma_f32 v93, -v40, v103, v91
	v_fma_f32 v93, v93, v97, v103
	v_div_fixup_f32 v40, v93, v40, v91
	v_mul_f32_e32 v40, v98, v40
	v_mul_f32_e32 v41, v99, v41
	global_load_dwordx2 v[98:99], v[74:75], off offset:64
	s_waitcnt vmcnt(0) lgkmcnt(0)
; DI size_t kblk(int row, int col, int nrows) { return ((size_t)(col >> 5) * nrows + row) * 32 + (col & 31); }
; DI unsigned pk2(float a, float b) { hwf32x2 f = {a, b}; hwbf16x2 r = __builtin_convertvector(f, hwbf16x2); return __builtin_bit_cast(unsigned, r); }
; DI float sigmoidf_(float z) { return 1.f / (1.f + __expf(-z)); }
; DI float siluf_(float z) { return z / (1.f + __expf(-z)); }
; template <int MX, bool OUT>
; DI void rec_chunk(const Params& p, int l, int b, int h, int dir, int T0, unsigned char* smem, f32x4 (&St)[4], float& nst, float& dtot, int tid, const RecRaw& raw) {
;     ...
; #pragma unroll
;       for (int a = 0; a < 4; ++a) {
;         const int v0 = 16 * a + 4 * g;
;         const uint2 gt = *(const uint2*)(prow + GATE + cb + v0);
;         const float4 gg = *(const float4*)(gvec + v0);
;         float y0 = O[a][0] * rstd * gg.x * siluf_(__uint_as_float(gt.x << 16));
;         float y1 = O[a][1] * rstd * gg.y * siluf_(__uint_as_float(gt.x & 0xffff0000u));
;         float y2 = O[a][2] * rstd * gg.z * siluf_(__uint_as_float(gt.y << 16));
;         float y3 = O[a][3] * rstd * gg.w * siluf_(__uint_as_float(gt.y & 0xffff0000u));
;         if (MX == 1) {
;           const uint2 og = *(const uint2*)(prow + D_OG + h * 64 + v0);
;           y0 *= sigmoidf_(__uint_as_float(og.x << 16)); y1 *= sigmoidf_(__uint_as_float(og.x & 0xffff0000u));
;           y2 *= sigmoidf_(__uint_as_float(og.y << 16)); y3 *= sigmoidf_(__uint_as_float(og.y & 0xffff0000u));
;         }
;         *(uint2*)(MIX + kblk((int)orow, cb + v0, ROWS)) = make_uint2(pk2(y0, y1), pk2(y2, y3));
	v_lshlrev_b32_e32 v91, 16, v98
	v_mul_f32_e32 v91, 0xbfb8aa3b, v91
	v_exp_f32_e32 v102, v91
	v_and_b32_e32 v91, 0xffff0000, v98
	v_mul_f32_e32 v91, 0xbfb8aa3b, v91
	v_exp_f32_e32 v103, v91
	s_nop 0
	v_add_f32_e32 v102, 1.0, v102
	v_add_f32_e32 v103, 1.0, v103
	s_nop 0
	v_rcp_f32_e32 v93, v103
	s_nop 0
	v_fma_f32 v97, -v103, v93, 1.0
	v_fmac_f32_e32 v93, v97, v93
	v_mov_b32_e64 v97, 1.0
	v_mul_f32_e32 v98, v97, v93
	v_fma_f32 v104, -v103, v98, v97
	v_fmac_f32_e32 v98, v104, v93
	v_fma_f32 v91, -v103, v98, v97
	v_fma_f32 v91, v91, v93, v98
	v_div_fixup_f32 v103, v91, v103, 1.0
	v_rcp_f32_e32 v93, v102
	s_nop 0
	v_fma_f32 v97, -v102, v93, 1.0
	v_fmac_f32_e32 v93, v97, v93
	v_mov_b32_e64 v97, 1.0
	v_mul_f32_e32 v98, v97, v93
	v_fma_f32 v104, -v102, v98, v97
	v_fmac_f32_e32 v98, v104, v93
	v_fma_f32 v91, -v102, v98, v97
	v_fma_f32 v91, v91, v93, v98
	v_div_fixup_f32 v102, v91, v102, 1.0
	v_lshlrev_b32_e32 v91, 16, v99
	v_mul_f32_e32 v91, 0xbfb8aa3b, v91
	v_exp_f32_e32 v98, v91
	v_and_b32_e32 v91, 0xffff0000, v99
	v_mul_f32_e32 v91, 0xbfb8aa3b, v91
	v_exp_f32_e32 v99, v91
	v_mul_f32_e32 v42, v42, v102
	v_mul_f32_e32 v43, v43, v103
	v_add_f32_e32 v98, 1.0, v98
	v_add_f32_e32 v99, 1.0, v99
	s_nop 0
	v_rcp_f32_e32 v93, v99
	v_cvt_pk_bf16_f32 v42, v42, v43
	v_fma_f32 v97, -v99, v93, 1.0
	v_fmac_f32_e32 v93, v97, v93
	v_mov_b32_e64 v97, 1.0
	v_mul_f32_e32 v102, v97, v93
	v_fma_f32 v103, -v99, v102, v97
	v_fmac_f32_e32 v102, v103, v93
	v_fma_f32 v91, -v99, v102, v97
	v_fma_f32 v91, v91, v93, v102
	v_div_fixup_f32 v99, v91, v99, 1.0
	v_rcp_f32_e32 v93, v98
	s_nop 0
	v_fma_f32 v97, -v98, v93, 1.0
	v_fmac_f32_e32 v93, v97, v93
	v_mov_b32_e64 v97, 1.0
	v_mul_f32_e32 v102, v97, v93
	v_fma_f32 v103, -v98, v102, v97
	v_fmac_f32_e32 v102, v103, v93
	v_fma_f32 v91, -v98, v102, v97
	v_fma_f32 v91, v91, v93, v102
	v_div_fixup_f32 v98, v91, v98, 1.0
	v_mul_f32_e32 v40, v40, v98
	v_mul_f32_e32 v41, v41, v99
	s_nop 0
	v_cvt_pk_bf16_f32 v43, v40, v41
	global_store_dwordx2 v[72:73], v[42:43], off
	global_load_dwordx2 v[40:41], v[100:101], off offset:96
	s_nop 0
	global_load_dwordx2 v[74:75], v[74:75], off offset:96
	s_waitcnt vmcnt(0) lgkmcnt(0)
	v_lshlrev_b32_e32 v73, 16, v40
	v_and_b32_e32 v91, 0xffff0000, v40
	v_lshlrev_b32_e32 v40, 16, v41
	v_mul_f32_e32 v42, 0xbfb8aa3b, v40
	v_exp_f32_e32 v42, v42
	s_nop 0
	v_add_f32_e32 v42, 1.0, v42
	v_rcp_f32_e32 v72, v42
	s_nop 0
	v_fma_f32 v93, -v42, v72, 1.0
	v_fmac_f32_e32 v72, v93, v72
	v_mul_f32_e32 v97, v40, v72
	v_fma_f32 v98, -v42, v97, v40
	v_fmac_f32_e32 v97, v98, v72
	v_fma_f32 v43, -v42, v97, v40
	v_fma_f32 v43, v43, v72, v97
	v_and_b32_e32 v93, 0xffff0000, v41
	v_div_fixup_f32 v72, v43, v42, v40
	v_mul_f32_e32 v40, 0xbfb8aa3b, v93
	v_exp_f32_e32 v98, v40
	v_lshlrev_b32_e32 v40, 16, v74
	v_mul_f32_e32 v40, 0xbfb8aa3b, v40
	v_exp_f32_e32 v100, v40
	v_and_b32_e32 v40, 0xffff0000, v74
	v_mul_f32_e32 v40, 0xbfb8aa3b, v40
	v_exp_f32_e32 v101, v40
	global_load_dwordx4 v[40:43], v[86:87], off offset:192
	v_mul_f32_e32 v70, v70, v96
	v_mul_f32_e32 v71, v71, v96
	v_mul_f32_e32 v74, 0xbfb8aa3b, v73
	v_exp_f32_e32 v102, v74
	s_waitcnt vmcnt(0)
	v_mul_f32_e32 v40, v70, v40
	v_mul_f32_e32 v41, v71, v41
	v_mul_f32_e32 v70, 0xbfb8aa3b, v91
	v_exp_f32_e32 v103, v70
	s_nop 0
	v_add_f32_e32 v70, 1.0, v102
	v_add_f32_e32 v71, 1.0, v103
	s_nop 0
	v_rcp_f32_e32 v97, v71
	s_nop 0
	v_fma_f32 v99, -v71, v97, 1.0
	v_fmac_f32_e32 v97, v99, v97
	v_mul_f32_e32 v102, v91, v97
	v_fma_f32 v103, -v71, v102, v91
	v_fmac_f32_e32 v102, v103, v97
	v_fma_f32 v74, -v71, v102, v91
	v_fma_f32 v74, v74, v97, v102
	v_div_fixup_f32 v71, v74, v71, v91
	v_rcp_f32_e32 v91, v70
	s_nop 0
	v_fma_f32 v97, -v70, v91, 1.0
	v_fmac_f32_e32 v91, v97, v91
	v_mul_f32_e32 v99, v73, v91
	v_fma_f32 v102, -v70, v99, v73
	v_fmac_f32_e32 v99, v102, v91
	v_fma_f32 v74, -v70, v99, v73
	v_fma_f32 v74, v74, v91, v99
	v_div_fixup_f32 v70, v74, v70, v73
	v_mul_f32_e32 v40, v40, v70
	v_mul_f32_e32 v41, v41, v71
	v_add_f32_e32 v70, 1.0, v100
	v_add_f32_e32 v71, 1.0, v101
	s_nop 0
	v_rcp_f32_e32 v74, v71
	s_nop 0
	v_fma_f32 v91, -v71, v74, 1.0
	v_fmac_f32_e32 v74, v91, v74
	v_mov_b32_e64 v91, 1.0
	v_mul_f32_e32 v97, v91, v74
	v_fma_f32 v99, -v71, v97, v91
	v_fmac_f32_e32 v97, v99, v74
	v_fma_f32 v73, -v71, v97, v91
	v_fma_f32 v73, v73, v74, v97
	v_div_fixup_f32 v71, v73, v71, 1.0
	v_rcp_f32_e32 v74, v70
	s_nop 0
	v_fma_f32 v91, -v70, v74, 1.0
	v_fmac_f32_e32 v74, v91, v74
	v_mov_b32_e64 v91, 1.0
	v_mul_f32_e32 v97, v91, v74
	v_fma_f32 v99, -v70, v97, v91
	v_fmac_f32_e32 v97, v99, v74
	v_fma_f32 v73, -v70, v97, v91
	v_fma_f32 v73, v73, v74, v97
	v_div_fixup_f32 v70, v73, v70, 1.0
	v_mul_f32_e32 v40, v40, v70
	v_mul_f32_e32 v41, v41, v71
	v_lshlrev_b32_e32 v70, 16, v75
	v_mul_f32_e32 v70, 0xbfb8aa3b, v70
	v_exp_f32_e32 v70, v70
	v_cvt_pk_bf16_f32 v40, v40, v41
	v_add_f32_e32 v70, 1.0, v70
	v_rcp_f32_e32 v73, v70
	s_nop 0
	v_fma_f32 v74, -v70, v73, 1.0
	v_fmac_f32_e32 v73, v74, v73
	v_mov_b32_e64 v74, 1.0
	v_mul_f32_e32 v91, v74, v73
	v_fma_f32 v97, -v70, v91, v74
	v_fmac_f32_e32 v91, v97, v73
	v_fma_f32 v71, -v70, v91, v74
	v_fma_f32 v71, v71, v73, v91
	v_div_fixup_f32 v70, v71, v70, 1.0
	v_and_b32_e32 v71, 0xffff0000, v75
	v_mul_f32_e32 v71, 0xbfb8aa3b, v71
	v_exp_f32_e32 v99, v71
	s_nop 0
	v_add_f32_e32 v74, 1.0, v98
	v_add_f32_e32 v75, 1.0, v99
	s_nop 0
	v_rcp_f32_e32 v73, v75
	s_nop 0
	v_fma_f32 v91, -v75, v73, 1.0
	v_fmac_f32_e32 v73, v91, v73
	v_mov_b32_e64 v91, 1.0
	v_mul_f32_e32 v97, v91, v73
	v_fma_f32 v98, -v75, v97, v91
	v_fmac_f32_e32 v97, v98, v73
	v_fma_f32 v71, -v75, v97, v91
	v_fma_f32 v71, v71, v73, v97
	v_div_fixup_f32 v71, v71, v75, 1.0
	v_rcp_f32_e32 v75, v74
	s_mov_b64 s[0:1], 0
	v_fma_f32 v91, -v74, v75, 1.0
	v_fmac_f32_e32 v75, v91, v75
	v_mul_f32_e32 v97, v93, v75
	v_fma_f32 v98, -v74, v97, v93
	v_fmac_f32_e32 v97, v98, v75
	v_fma_f32 v73, -v74, v97, v93
	v_fma_f32 v73, v73, v75, v97
	v_mul_f32_e32 v68, v68, v96
	v_mul_f32_e32 v69, v69, v96
	v_div_fixup_f32 v73, v73, v74, v93
	v_mul_f32_e32 v42, v68, v42
	v_mul_f32_e32 v43, v69, v43
	v_mov_b32_e32 v93, v161
	v_mul_f32_e32 v42, v42, v72
	v_mul_f32_e32 v43, v43, v73
	v_lshl_add_u64 v[66:67], v[66:67], 0, v[92:93]
	v_mul_f32_e32 v42, v42, v70
	v_mul_f32_e32 v43, v43, v71
	global_store_dword v[66:67], v40, off

; #define MFMA16(a, b, c) __builtin_amdgcn_mfma_f32_16x16x32_bf16((a), (b), (c), 0, 0, 0)
; template <int MX, bool OUT>
; DI void rec_chunk(const Params& p, int l, int b, int h, int dir, int T0, unsigned char* smem, f32x4 (&St)[4], float& nst, float& dtot, int tid, const RecRaw& raw) {
;     ...
;   {
; #pragma unroll
;     for (int c = 0; c < 4; ++c) {
;       const float d = DEC[16 * c + col];
; #pragma unroll
;       for (int j = 0; j < 4; ++j) St[c][j] *= d;
;     }
; #pragma unroll
;     for (int ks = 0; ks < 2; ++ks) {
;       const bf16x8 fa = *(const bf16x8*)(smem + L_VT + swz(16 * w + col, ks * 4 + g));
; #pragma unroll
;       for (int c = 0; c < 4; ++c) {
;         const bf16x8 fb = *(const bf16x8*)(smem + L_KET + swz(16 * c + col, ks * 4 + g));
;         St[c] = MFMA16(fa, fb, St[c]);
;       }
;     }
;     if (tid < 64) {
;       const float d = DEC[tid];
;       dtot *= d;
;       if (MX == 1) {
;         float s = 0.f;
; #pragma unroll
;         for (int cc = 0; cc < 8; ++cc) {
;           const uint4 u = *(const uint4*)(smem + L_KET + swz(tid, cc));
;           s += __uint_as_float(u.x << 16) + __uint_as_float(u.x & 0xffff0000u) + __uint_as_float(u.y << 16) + __uint_as_float(u.y & 0xffff0000u)
;              + __uint_as_float(u.z << 16) + __uint_as_float(u.z & 0xffff0000u) + __uint_as_float(u.w << 16) + __uint_as_float(u.w & 0xffff0000u);
;         }
;         nst = d * nst + s;
;       }
.LBB0_687:
	v_cvt_pk_bf16_f32 v40, v42, v43
	global_store_dword v[66:67], v40, off offset:4
	ds_read2_b32 v[40:41], v149 offset1:16
	s_waitcnt lgkmcnt(0)
	v_mul_f32_e32 v0, v0, v40
	v_mul_f32_e32 v1, v1, v40
	v_mul_f32_e32 v2, v2, v40
	v_mul_f32_e32 v3, v3, v40
	v_mov_b32_e32 v40, v41
	v_mul_f32_e32 v4, v4, v40
	v_mul_f32_e32 v5, v5, v40
	v_mul_f32_e32 v6, v6, v40
	v_mul_f32_e32 v7, v7, v40
	ds_read2_b32 v[40:41], v149 offset0:32 offset1:48
	s_waitcnt lgkmcnt(0)
	v_mul_f32_e32 v24, v24, v40
	v_mul_f32_e32 v25, v25, v40
	v_mul_f32_e32 v26, v26, v40
	v_mul_f32_e32 v27, v27, v40
	v_mov_b32_e32 v40, v41
	v_mul_f32_e32 v36, v36, v40
	v_mul_f32_e32 v37, v37, v40
	v_mul_f32_e32 v38, v38, v40
	v_mul_f32_e32 v39, v39, v40
	ds_read_b128 v[40:43], v240 offset:49152
	ds_read_b128 v[44:47], v238 offset:40960
	s_waitcnt lgkmcnt(0)
	v_mfma_f32_16x16x32_bf16 v[0:3], v[40:43], v[44:47], v[0:3]
	ds_read_b128 v[44:47], v238 offset:43008
	s_waitcnt lgkmcnt(0)
	v_mfma_f32_16x16x32_bf16 v[4:7], v[40:43], v[44:47], v[4:7]
	ds_read_b128 v[44:47], v238 offset:45056
	s_waitcnt lgkmcnt(0)
	v_mfma_f32_16x16x32_bf16 v[24:27], v[40:43], v[44:47], v[24:27]
	ds_read_b128 v[44:47], v238 offset:47104
	s_waitcnt lgkmcnt(0)
	v_mfma_f32_16x16x32_bf16 v[36:39], v[40:43], v[44:47], v[36:39]
	ds_read_b128 v[40:43], v239 offset:49152
	ds_read_b128 v[44:47], v237 offset:40960
	s_waitcnt lgkmcnt(0)
	v_mfma_f32_16x16x32_bf16 v[0:3], v[40:43], v[44:47], v[0:3]
	ds_read_b128 v[44:47], v237 offset:43008
	s_waitcnt lgkmcnt(0)
	v_mfma_f32_16x16x32_bf16 v[4:7], v[40:43], v[44:47], v[4:7]
	ds_read_b128 v[44:47], v237 offset:45056
	s_waitcnt lgkmcnt(0)
	v_mfma_f32_16x16x32_bf16 v[24:27], v[40:43], v[44:47], v[24:27]
	ds_read_b128 v[44:47], v237 offset:47104
	s_waitcnt lgkmcnt(0)
	v_mfma_f32_16x16x32_bf16 v[36:39], v[40:43], v[44:47], v[36:39]
	s_and_saveexec_b64 s[0:1], s[10:11]
	s_cbranch_execz .LBB0_689
	v_add_u32_e32 v41, v152, v153
	ds_read_b32 v40, v151
	ds_read_b128 v[42:45], v41 offset:40960
	ds_read_b128 v[46:49], v215 offset:40960
	s_waitcnt lgkmcnt(0)
	v_lshlrev_b32_e32 v50, 16, v42
	v_lshlrev_b32_e32 v51, 16, v46
	v_and_b32_e32 v53, 0xffff0000, v46
	v_and_b32_e32 v52, 0xffff0000, v42
	v_add_f32_e32 v50, v50, v52
	v_add_f32_e32 v51, v51, v53
	v_lshlrev_b32_e32 v53, 16, v47
	v_lshlrev_b32_e32 v52, 16, v43
	v_add_f32_e32 v50, v50, v52
	v_add_f32_e32 v51, v51, v53
	v_and_b32_e32 v47, 0xffff0000, v47
	v_and_b32_e32 v46, 0xffff0000, v43
	v_add_f32_e32 v42, v50, v46
	v_add_f32_e32 v43, v51, v47
	v_lshlrev_b32_e32 v47, 16, v48
	v_lshlrev_b32_e32 v46, 16, v44
	v_add_f32_e32 v42, v42, v46
	v_add_f32_e32 v43, v43, v47
	v_and_b32_e32 v47, 0xffff0000, v48
	v_and_b32_e32 v46, 0xffff0000, v44
	v_add_f32_e32 v42, v42, v46
	v_add_f32_e32 v43, v43, v47
	v_lshlrev_b32_e32 v47, 16, v49
	v_lshlrev_b32_e32 v46, 16, v45
	v_add_f32_e32 v42, v42, v46
	v_add_f32_e32 v43, v43, v47
	v_and_b32_e32 v47, 0xffff0000, v49
	v_and_b32_e32 v46, 0xffff0000, v45
	v_add_f32_e32 v42, v42, v46
	v_add_f32_e32 v43, v43, v47
	s_nop 0
	v_add_f32_e32 v41, 0, v42
	v_add_f32_e32 v41, v41, v43
	ds_read_b128 v[42:45], v216 offset:40960
	ds_read_b128 v[46:49], v217 offset:40960
	s_waitcnt lgkmcnt(0)
	v_lshlrev_b32_e32 v50, 16, v42
	v_lshlrev_b32_e32 v51, 16, v46
	v_and_b32_e32 v53, 0xffff0000, v46
	v_and_b32_e32 v52, 0xffff0000, v42
	v_add_f32_e32 v50, v50, v52
	v_add_f32_e32 v51, v51, v53
	v_lshlrev_b32_e32 v53, 16, v47
	v_lshlrev_b32_e32 v52, 16, v43
	v_add_f32_e32 v50, v50, v52
	v_add_f32_e32 v51, v51, v53
	v_and_b32_e32 v47, 0xffff0000, v47
	v_and_b32_e32 v46, 0xffff0000, v43
	v_add_f32_e32 v42, v50, v46
	v_add_f32_e32 v43, v51, v47
	v_lshlrev_b32_e32 v47, 16, v48
	v_lshlrev_b32_e32 v46, 16, v44
	v_add_f32_e32 v42, v42, v46
	v_add_f32_e32 v43, v43, v47
	v_and_b32_e32 v47, 0xffff0000, v48
	v_and_b32_e32 v46, 0xffff0000, v44
	v_add_f32_e32 v42, v42, v46
	v_add_f32_e32 v43, v43, v47
	v_lshlrev_b32_e32 v47, 16, v49
	v_lshlrev_b32_e32 v46, 16, v45
	v_add_f32_e32 v42, v42, v46
	v_add_f32_e32 v43, v43, v47
	v_and_b32_e32 v47, 0xffff0000, v49
	v_and_b32_e32 v46, 0xffff0000, v45
	v_add_f32_e32 v42, v42, v46
	v_add_f32_e32 v43, v43, v47
	s_nop 0
	v_add_f32_e32 v41, v41, v42
	v_add_f32_e32 v41, v41, v43
	ds_read_b128 v[42:45], v218 offset:40960
	ds_read_b128 v[46:49], v219 offset:40960
	s_waitcnt lgkmcnt(0)
	v_lshlrev_b32_e32 v50, 16, v42
	v_lshlrev_b32_e32 v51, 16, v46
	v_and_b32_e32 v53, 0xffff0000, v46
	v_and_b32_e32 v52, 0xffff0000, v42
	v_add_f32_e32 v50, v50, v52
	v_add_f32_e32 v51, v51, v53
	v_lshlrev_b32_e32 v53, 16, v47
	v_lshlrev_b32_e32 v52, 16, v43
	v_add_f32_e32 v50, v50, v52
	v_add_f32_e32 v51, v51, v53
	v_and_b32_e32 v47, 0xffff0000, v47
	v_and_b32_e32 v46, 0xffff0000, v43
	v_add_f32_e32 v42, v50, v46
	v_add_f32_e32 v43, v51, v47
	v_lshlrev_b32_e32 v47, 16, v48
	v_lshlrev_b32_e32 v46, 16, v44
	v_add_f32_e32 v42, v42, v46
	v_add_f32_e32 v43, v43, v47
	v_and_b32_e32 v47, 0xffff0000, v48
	v_and_b32_e32 v46, 0xffff0000, v44
	v_add_f32_e32 v42, v42, v46
	v_add_f32_e32 v43, v43, v47
	v_lshlrev_b32_e32 v47, 16, v49
	v_lshlrev_b32_e32 v46, 16, v45
	v_add_f32_e32 v42, v42, v46
	v_add_f32_e32 v43, v43, v47
	v_and_b32_e32 v47, 0xffff0000, v49
	v_and_b32_e32 v46, 0xffff0000, v45
	v_add_f32_e32 v42, v42, v46
	v_add_f32_e32 v43, v43, v47
	s_nop 0
	v_add_f32_e32 v41, v41, v42
	v_add_f32_e32 v41, v41, v43
	ds_read_b128 v[42:45], v220 offset:40960
	ds_read_b128 v[46:49], v221 offset:40960
	s_waitcnt lgkmcnt(0)
	v_lshlrev_b32_e32 v50, 16, v42
	v_lshlrev_b32_e32 v51, 16, v46
	v_and_b32_e32 v53, 0xffff0000, v46
	v_and_b32_e32 v52, 0xffff0000, v42
	v_add_f32_e32 v50, v50, v52
	v_add_f32_e32 v51, v51, v53
	v_lshlrev_b32_e32 v53, 16, v47
	v_lshlrev_b32_e32 v52, 16, v43
	v_add_f32_e32 v50, v50, v52
	v_add_f32_e32 v51, v51, v53
	v_and_b32_e32 v47, 0xffff0000, v47
	v_and_b32_e32 v46, 0xffff0000, v43
	v_add_f32_e32 v42, v50, v46
	v_add_f32_e32 v43, v51, v47
	v_lshlrev_b32_e32 v47, 16, v48
	v_lshlrev_b32_e32 v46, 16, v44
	v_add_f32_e32 v42, v42, v46
	v_add_f32_e32 v43, v43, v47
	v_and_b32_e32 v47, 0xffff0000, v48
	v_and_b32_e32 v46, 0xffff0000, v44
	v_add_f32_e32 v42, v42, v46
	v_add_f32_e32 v43, v43, v47
	v_lshlrev_b32_e32 v47, 16, v49
	v_lshlrev_b32_e32 v46, 16, v45
	v_add_f32_e32 v42, v42, v46
	v_add_f32_e32 v43, v43, v47
	v_and_b32_e32 v47, 0xffff0000, v49
	v_and_b32_e32 v46, 0xffff0000, v45
	v_add_f32_e32 v42, v42, v46
	v_add_f32_e32 v43, v43, v47
	s_nop 0
	v_add_f32_e32 v41, v41, v42
	v_add_f32_e32 v41, v41, v43
	v_fmac_f32_e32 v41, v234, v40
	v_mov_b32_e32 v234, v41

; DI bf16_t f2bf(float f) { return (bf16_t)(pk2(f, 0.f) & 0xffffu); }
; #define MFMA16(a, b, c) __builtin_amdgcn_mfma_f32_16x16x32_bf16((a), (b), (c), 0, 0, 0)
; template <int MX, bool OUT>
; DI void rec_chunk(const Params& p, int l, int b, int h, int dir, int T0, unsigned char* smem, f32x4 (&St)[4], float& nst, float& dtot, int tid, const RecRaw& raw) {
;     ...
;   {
; #pragma unroll
;     for (int c = 0; c < 4; ++c) {
;       const float d = DEC[16 * c + col];
; #pragma unroll
;       for (int j = 0; j < 4; ++j) St[c][j] *= d;
;     }
; #pragma unroll
;     for (int ks = 0; ks < 2; ++ks) {
;       const bf16x8 fa = *(const bf16x8*)(smem + L_VT + swz(16 * w + col, ks * 4 + g));
; #pragma unroll
;       for (int c = 0; c < 4; ++c) {
;         const bf16x8 fb = *(const bf16x8*)(smem + L_KET + swz(16 * c + col, ks * 4 + g));
;         St[c] = MFMA16(fa, fb, St[c]);
;       }
;     }
;     if (tid < 64) {
;       const float d = DEC[tid];
;       dtot *= d;
;       if (MX == 1) {
;         float s = 0.f;
; #pragma unroll
;         for (int cc = 0; cc < 8; ++cc) {
;           const uint4 u = *(const uint4*)(smem + L_KET + swz(tid, cc));
;           s += __uint_as_float(u.x << 16) + __uint_as_float(u.x & 0xffff0000u) + __uint_as_float(u.y << 16) + __uint_as_float(u.y & 0xffff0000u)
;              + __uint_as_float(u.z << 16) + __uint_as_float(u.z & 0xffff0000u) + __uint_as_float(u.w << 16) + __uint_as_float(u.w & 0xffff0000u);
;         }
;         nst = d * nst + s;
;       }
;     }
;     __syncthreads();
;     if (OUT) {
; #pragma unroll
;       for (int c = 0; c < 4; ++c)
; #pragma unroll
;         for (int j = 0; j < 4; ++j) {
;           const int v = 16 * w + 4 * g + j, k = 16 * c + col;
;           *(bf16_t*)(smem + L_STT + swz(v, k >> 3) + (k & 7) * 2) = f2bf(St[c][j]);
;         }
.LBB0_700:
	v_cvt_pk_bf16_f32 v40, v56, v57
	global_store_dword v[58:59], v40, off offset:4
	ds_read2_b32 v[40:41], v137 offset1:16
	s_add_i32 s81, s81, -1
	s_add_i32 s13, s13, 1
	s_cmp_eq_u32 s81, -2
	s_waitcnt vmcnt(0)
	v_mov_b64_e32 v[60:61], v[4:5]
	s_waitcnt lgkmcnt(0)
	v_mul_f32_e32 v24, v24, v40
	v_mul_f32_e32 v25, v25, v40
	v_mul_f32_e32 v26, v26, v40
	v_mul_f32_e32 v27, v27, v40
	v_mov_b32_e32 v40, v41
	v_mul_f32_e32 v28, v28, v40
	v_mul_f32_e32 v29, v29, v40
	v_mul_f32_e32 v30, v30, v40
	v_mul_f32_e32 v31, v31, v40
	ds_read2_b32 v[40:41], v137 offset0:32 offset1:48
	v_mov_b64_e32 v[62:63], v[6:7]
	v_mov_b64_e32 v[56:57], v[0:1]
	v_mov_b64_e32 v[58:59], v[2:3]
	v_mov_b64_e32 v[52:53], v[12:13]
	s_waitcnt lgkmcnt(0)
	v_mul_f32_e32 v32, v32, v40
	v_mul_f32_e32 v33, v33, v40
	v_mul_f32_e32 v34, v34, v40
	v_mul_f32_e32 v35, v35, v40
	v_mov_b32_e32 v40, v41
	v_mul_f32_e32 v36, v36, v40
	v_mul_f32_e32 v37, v37, v40
	v_mul_f32_e32 v38, v38, v40
	v_mul_f32_e32 v39, v39, v40
	ds_read_b128 v[40:43], v202 offset:49152
	ds_read_b128 v[44:47], v200 offset:40960
	s_waitcnt lgkmcnt(0)
	v_mfma_f32_16x16x32_bf16 v[24:27], v[40:43], v[44:47], v[24:27]
	ds_read_b128 v[44:47], v200 offset:43008
	v_mov_b64_e32 v[54:55], v[14:15]
	v_mov_b64_e32 v[48:49], v[8:9]
	s_waitcnt lgkmcnt(0)
	v_mfma_f32_16x16x32_bf16 v[28:31], v[40:43], v[44:47], v[28:31]
	ds_read_b128 v[44:47], v200 offset:45056
	v_mov_b64_e32 v[50:51], v[10:11]
	s_waitcnt lgkmcnt(0)
	v_mfma_f32_16x16x32_bf16 v[32:35], v[40:43], v[44:47], v[32:35]
	ds_read_b128 v[44:47], v200 offset:47104
	s_waitcnt lgkmcnt(0)
	v_mfma_f32_16x16x32_bf16 v[36:39], v[40:43], v[44:47], v[36:39]
	ds_read_b128 v[40:43], v201 offset:49152
	ds_read_b128 v[44:47], v199 offset:40960
	s_waitcnt lgkmcnt(0)
	v_mfma_f32_16x16x32_bf16 v[24:27], v[40:43], v[44:47], v[24:27]
	ds_read_b128 v[44:47], v199 offset:43008
	s_waitcnt lgkmcnt(0)
	v_mfma_f32_16x16x32_bf16 v[28:31], v[40:43], v[44:47], v[28:31]
	ds_read_b128 v[44:47], v199 offset:45056
	s_waitcnt lgkmcnt(0)
	v_mfma_f32_16x16x32_bf16 v[32:35], v[40:43], v[44:47], v[32:35]
	ds_read_b128 v[44:47], v199 offset:47104
	s_waitcnt lgkmcnt(0)
	s_barrier
	v_mfma_f32_16x16x32_bf16 v[36:39], v[40:43], v[44:47], v[36:39]
	v_cvt_pk_bf16_f32 v40, v24, s0
	ds_write_b16 v155, v40 offset:57344
	v_cvt_pk_bf16_f32 v40, v25, s0
	ds_write_b16 v155, v40 offset:57472
	v_cvt_pk_bf16_f32 v40, v26, s0
	ds_write_b16 v156, v40 offset:57344
	v_cvt_pk_bf16_f32 v40, v27, s0
	ds_write_b16 v157, v40 offset:57344
	v_cvt_pk_bf16_f32 v40, v28, s0
	ds_write_b16 v158, v40 offset:57344
	v_cvt_pk_bf16_f32 v40, v29, s0
	ds_write_b16 v158, v40 offset:57472
	v_cvt_pk_bf16_f32 v40, v30, s0
	ds_write_b16 v159, v40 offset:57344
	v_cvt_pk_bf16_f32 v40, v31, s0
	ds_write_b16 v164, v40 offset:57344
	v_cvt_pk_bf16_f32 v40, v32, s0
	ds_write_b16 v165, v40 offset:57344
	v_cvt_pk_bf16_f32 v40, v33, s0
	ds_write_b16 v165, v40 offset:57472
	v_cvt_pk_bf16_f32 v40, v34, s0
	ds_write_b16 v166, v40 offset:57344
	v_cvt_pk_bf16_f32 v40, v35, s0
	ds_write_b16 v167, v40 offset:57344
	v_cvt_pk_bf16_f32 v40, v36, s0
	ds_write_b16 v170, v40 offset:57344
	v_cvt_pk_bf16_f32 v40, v37, s0
	ds_write_b16 v170, v40 offset:57472
	v_cvt_pk_bf16_f32 v40, v38, s0
	ds_write_b16 v171, v40 offset:57344
	v_cvt_pk_bf16_f32 v40, v39, s0
	ds_write_b16 v196, v40 offset:57344
	v_mov_b64_e32 v[40:41], v[20:21]
	v_mov_b64_e32 v[42:43], v[22:23]
	v_mov_b64_e32 v[44:45], v[16:17]
	v_mov_b64_e32 v[46:47], v[18:19]
	s_cbranch_scc1 .LBB0_698

; DI size_t kblk(int row, int col, int nrows) { return ((size_t)(col >> 5) * nrows + row) * 32 + (col & 31); }
; DI float siluf_(float z) { return z / (1.f + __expf(-z)); }
; template <int MX, bool OUT>
; DI void rec_chunk(const Params& p, int l, int b, int h, int dir, int T0, unsigned char* smem, f32x4 (&St)[4], float& nst, float& dtot, int tid, const RecRaw& raw) {
;     ...
; #pragma unroll
;     for (int ks = 0; ks < 2; ++ks) {
;       const bf16x8 fb = *(const bf16x8*)(smem + L_QS + swz(t, ks * 4 + g));
; #pragma unroll
;       for (int a = 0; a < 4; ++a) {
;         const bf16x8 fa = *(const bf16x8*)(smem + L_STT + swz(16 * a + col, ks * 4 + g));
;         O[a] = MFMA16(fa, fb, O[a]);
;       }
;     }
;     if (MX == 1) {
;       const float inv = 1.f / fmaxf(fabsf(den), 1.f);
; #pragma unroll
;       for (int a = 0; a < 4; ++a)
; #pragma unroll
;         for (int j = 0; j < 4; ++j) O[a][j] *= inv;
;     }
;     if (dir == 0) {
; #pragma unroll
;       for (int a = 0; a < 4; ++a) *(uint2*)(MIX + kblk((int)orow, cb + 16 * a + 4 * g, ROWS)) = make_uint2(pk2(O[a][0], O[a][1]), pk2(O[a][2], O[a][3]));
;     } else {
;       float ss = 0.f;
; #pragma unroll
;       for (int a = 0; a < 4; ++a) {
;         const uint2 u = *(const uint2*)(MIX + kblk((int)orow, cb + 16 * a + 4 * g, ROWS));
;         O[a][0] += __uint_as_float(u.x << 16); O[a][1] += __uint_as_float(u.x & 0xffff0000u);
;         O[a][2] += __uint_as_float(u.y << 16); O[a][3] += __uint_as_float(u.y & 0xffff0000u);
; #pragma unroll
;         for (int j = 0; j < 4; ++j) ss += O[a][j] * O[a][j];
;       }
;       ss += __shfl_xor(ss, 16);
;       ss += __shfl_xor(ss, 32);
;       const float rstd = rsqrtf(ss * (1.f / 64.f) + EPS);
;       const float* gvec = (MX ? p.ml_g : p.hg_g) + l * 64;
; #pragma unroll
;       for (int a = 0; a < 4; ++a) {
;         const int v0 = 16 * a + 4 * g;
;         const uint2 gt = *(const uint2*)(prow + GATE + cb + v0);
;         const float4 gg = *(const float4*)(gvec + v0);
;         float y0 = O[a][0] * rstd * gg.x * siluf_(__uint_as_float(gt.x << 16));
;         float y1 = O[a][1] * rstd * gg.y * siluf_(__uint_as_float(gt.x & 0xffff0000u));
;         float y2 = O[a][2] * rstd * gg.z * siluf_(__uint_as_float(gt.y << 16));
;         float y3 = O[a][3] * rstd * gg.w * siluf_(__uint_as_float(gt.y & 0xffff0000u));
.LBB0_765:
	s_or_b64 exec, exec, vcc
	s_add_i32 s10, s13, -1
	v_mov_b32_e32 v40, s10
	v_cndmask_b32_e64 v40, v91, v40, s[6:7]
	v_lshlrev_b32_e32 v40, 6, v40
	v_add_u32_e32 v40, s12, v40
	v_mov_b32_e32 v41, v161
	v_lshl_add_u64 v[68:69], v[40:41], 0, v[82:83]
	ds_read_b128 v[40:43], v202 offset:32768
	ds_read_b128 v[44:47], v200 offset:57344
	ds_read_b128 v[48:51], v200 offset:59392
	ds_read_b128 v[52:55], v200 offset:61440
	s_waitcnt lgkmcnt(0)
	v_mfma_f32_16x16x32_bf16 v[44:47], v[44:47], v[40:43], v[56:59]
	s_mov_b64 s[10:11], -1
	s_nop 1
	ds_read_b128 v[56:59], v200 offset:63488
	s_and_b64 vcc, exec, s[78:79]
	v_mfma_f32_16x16x32_bf16 v[48:51], v[48:51], v[40:43], v[60:63]
	v_ashrrev_i32_e32 v203, 31, v68
	v_mfma_f32_16x16x32_bf16 v[52:55], v[52:55], v[40:43], v[64:67]
	s_waitcnt lgkmcnt(0)
	v_mfma_f32_16x16x32_bf16 v[56:59], v[56:59], v[40:43], v[72:75]
	ds_read_b128 v[60:63], v201 offset:32768
	ds_read_b128 v[40:43], v199 offset:57344
	s_waitcnt lgkmcnt(0)
	v_mfma_f32_16x16x32_bf16 v[40:43], v[40:43], v[60:63], v[44:47]
	s_nop 2
	ds_read_b128 v[44:47], v199 offset:59392
	s_waitcnt lgkmcnt(0)
	v_mfma_f32_16x16x32_bf16 v[48:51], v[44:47], v[60:63], v[48:51]
	ds_read_b128 v[44:47], v199 offset:61440
	s_waitcnt lgkmcnt(0)
	v_mfma_f32_16x16x32_bf16 v[52:55], v[44:47], v[60:63], v[52:55]
	ds_read_b128 v[44:47], v199 offset:63488
	s_waitcnt lgkmcnt(0)
	v_mfma_f32_16x16x32_bf16 v[44:47], v[44:47], v[60:63], v[56:59]
	s_cbranch_vccnz .LBB0_767
	s_nop 1
	v_mov_b64_e32 v[56:57], s[40:41]
	v_mad_u64_u32 v[56:57], s[10:11], v68, s33, v[56:57]
	v_mad_i32_i24 v57, v69, s33, v57
	v_mov_b32_e32 v69, v203
	v_lshl_add_u64 v[60:61], v[68:69], 0, s[30:31]
	v_lshlrev_b64 v[60:61], 6, v[60:61]
	v_lshl_add_u64 v[70:71], v[88:89], 0, v[60:61]
	global_load_dwordx2 v[60:61], v[70:71], off
	v_lshl_add_u64 v[58:59], v[68:69], 0, s[28:29]
	v_lshlrev_b64 v[58:59], 6, v[58:59]
	v_mov_b32_e32 v91, v161
	v_lshl_add_u64 v[96:97], v[84:85], 0, v[58:59]
	global_load_dwordx2 v[58:59], v[96:97], off
	s_mov_b64 s[10:11], 0x41c7a20
	v_lshl_add_u64 v[56:57], v[56:57], 0, s[10:11]
	s_waitcnt vmcnt(0) lgkmcnt(0)
	v_lshlrev_b32_e32 v74, 16, v60
	v_and_b32_e32 v75, 0xffff0000, v60
	v_lshlrev_b32_e32 v98, 16, v61
	v_and_b32_e32 v99, 0xffff0000, v61
	v_lshl_add_u64 v[60:61], v[68:69], 0, s[42:43]
	v_lshlrev_b64 v[60:61], 6, v[60:61]
	v_lshl_add_u64 v[60:61], s[34:35], 0, v[60:61]
	v_lshl_add_u64 v[66:67], v[60:61], 0, v[90:91]
	global_load_dwordx2 v[62:63], v[66:67], off
	v_mbcnt_hi_u32_b32 v69, -1, v185
	v_and_b32_e32 v73, 64, v69
	v_xor_b32_e32 v72, 16, v69
	v_add_u32_e32 v73, 64, v73
	v_cmp_lt_i32_e32 vcc, v72, v73
	v_lshlrev_b32_e32 v112, 16, v58
	v_and_b32_e32 v113, 0xffff0000, v58
	v_cndmask_b32_e32 v72, v69, v72, vcc
	v_lshlrev_b32_e32 v93, 2, v72
	v_xor_b32_e32 v72, 32, v69
	v_cmp_lt_i32_e32 vcc, v72, v73
	v_lshlrev_b32_e32 v58, 16, v59
	v_and_b32_e32 v59, 0xffff0000, v59
	v_cndmask_b32_e32 v69, v69, v72, vcc
	v_lshl_add_u64 v[72:73], v[56:57], 0, s[2:3]
	v_lshl_add_u64 v[56:57], v[56:57], 0, v[90:91]
	v_lshl_add_u64 v[56:57], v[56:57], 0, s[2:3]
	global_load_dwordx2 v[56:57], v[56:57], off
	v_add_f32_e32 v108, v42, v58
	v_add_f32_e32 v109, v43, v59
	v_add_f32_e32 v112, v40, v112
	v_add_f32_e32 v113, v41, v113
	v_mul_f32_e32 v110, v108, v108
	v_mul_f32_e32 v111, v109, v109
	v_mul_f32_e32 v116, v112, v112
	v_mul_f32_e32 v117, v113, v113
	v_lshl_add_u64 v[72:73], v[72:73], 0, v[90:91]
	v_add_f32_e32 v91, v116, v117
	v_add_f32_e32 v91, v91, v110
	v_add_f32_e32 v91, v111, v91
	v_lshlrev_b32_e32 v69, 2, v69
	s_waitcnt vmcnt(0) lgkmcnt(0)
	v_lshlrev_b32_e32 v104, 16, v62
	v_and_b32_e32 v105, 0xffff0000, v62
	v_lshlrev_b32_e32 v106, 16, v63
	v_and_b32_e32 v107, 0xffff0000, v63
	global_load_dwordx2 v[62:63], v[66:67], off offset:32
	v_add_f32_e32 v104, v52, v104
	v_add_f32_e32 v105, v53, v105
	v_lshlrev_b32_e32 v204, 16, v56
	v_and_b32_e32 v205, 0xffff0000, v56
	v_mul_f32_e32 v114, 0xbfb8aa3b, v204
	v_mul_f32_e32 v115, 0xbfb8aa3b, v205
	v_exp_f32_e32 v114, v114
	v_exp_f32_e32 v115, v115
	v_lshlrev_b32_e32 v206, 16, v57
	v_and_b32_e32 v207, 0xffff0000, v57
	global_load_dwordx4 v[56:59], v[86:87], off
	v_add_f32_e32 v114, 1.0, v114
	v_add_f32_e32 v115, 1.0, v115
	s_waitcnt vmcnt(0) lgkmcnt(0)
	v_lshlrev_b32_e32 v64, 16, v62
	v_rcp_f32_e32 v209, v115
	v_and_b32_e32 v65, 0xffff0000, v62
	v_add_f32_e32 v64, v44, v64
	v_add_f32_e32 v65, v45, v65
	v_lshlrev_b32_e32 v62, 16, v63
	v_fma_f32 v210, -v115, v209, 1.0
	v_fmac_f32_e32 v209, v210, v209
	v_mul_f32_e32 v211, v205, v209
	v_fma_f32 v212, -v115, v211, v205
	v_fmac_f32_e32 v211, v212, v209
	v_fma_f32 v208, -v115, v211, v205
	v_fma_f32 v208, v208, v209, v211
	v_div_fixup_f32 v115, v208, v115, v205
	v_rcp_f32_e32 v208, v114
	v_and_b32_e32 v63, 0xffff0000, v63
	v_mul_f32_e32 v100, v64, v64
	v_mul_f32_e32 v101, v65, v65
	v_add_f32_e32 v62, v46, v62
	v_add_f32_e32 v63, v47, v63
	v_fma_f32 v209, -v114, v208, 1.0
	v_fmac_f32_e32 v208, v209, v208
	v_mul_f32_e32 v210, v204, v208
	v_fma_f32 v211, -v114, v210, v204
	v_fmac_f32_e32 v210, v211, v208
	v_fma_f32 v205, -v114, v210, v204
	v_fma_f32 v205, v205, v208, v210
	v_div_fixup_f32 v114, v205, v114, v204
	v_mul_f32_e32 v204, 0xbfb8aa3b, v206
	v_mul_f32_e32 v205, 0xbfb8aa3b, v207
	v_exp_f32_e32 v204, v204
	v_exp_f32_e32 v205, v205
	v_mul_f32_e32 v102, v62, v62
	v_mul_f32_e32 v103, v63, v63
	v_add_f32_e32 v204, 1.0, v204
	v_add_f32_e32 v205, 1.0, v205
	s_nop 0
	v_rcp_f32_e32 v209, v205
	s_nop 0
	v_fma_f32 v210, -v205, v209, 1.0
	v_fmac_f32_e32 v209, v210, v209
	v_mul_f32_e32 v211, v207, v209
	v_fma_f32 v212, -v205, v211, v207
	v_fmac_f32_e32 v211, v212, v209
	v_fma_f32 v208, -v205, v211, v207
	v_fma_f32 v208, v208, v209, v211
	v_div_fixup_f32 v205, v208, v205, v207
	v_rcp_f32_e32 v208, v204
	v_mul_f32_e32 v212, v104, v104
	v_mul_f32_e32 v213, v105, v105
	v_fma_f32 v209, -v204, v208, 1.0
	v_fmac_f32_e32 v208, v209, v208
	v_mul_f32_e32 v210, v206, v208
	v_fma_f32 v211, -v204, v210, v206
	v_fmac_f32_e32 v210, v211, v208
	v_fma_f32 v207, -v204, v210, v206
	v_fma_f32 v207, v207, v208, v210
	v_add_f32_e32 v210, v48, v74
	v_add_f32_e32 v211, v49, v75
	v_div_fixup_f32 v204, v207, v204, v206
	v_mul_f32_e32 v74, v210, v210
	v_mul_f32_e32 v75, v211, v211
	v_add_f32_e32 v206, v50, v98
	v_add_f32_e32 v207, v51, v99
	v_add_f32_e32 v74, v74, v91
	v_mul_f32_e32 v208, v206, v206
	v_mul_f32_e32 v209, v207, v207
	v_add_f32_e32 v74, v75, v74
	v_add_f32_e32 v74, v208, v74
	v_add_f32_e32 v74, v209, v74
	v_add_f32_e32 v98, v54, v106
	v_add_f32_e32 v99, v55, v107
	v_add_f32_e32 v74, v212, v74
	v_mul_f32_e32 v106, v98, v98
	v_mul_f32_e32 v107, v99, v99
	v_add_f32_e32 v74, v213, v74
	v_add_f32_e32 v74, v106, v74
	v_add_f32_e32 v74, v107, v74
	v_add_f32_e32 v74, v100, v74
	v_add_f32_e32 v74, v101, v74
	v_add_f32_e32 v74, v102, v74
	v_add_f32_e32 v74, v103, v74
	ds_bpermute_b32 v75, v93, v74
	s_waitcnt lgkmcnt(0)
; DI size_t kblk(int row, int col, int nrows) { return ((size_t)(col >> 5) * nrows + row) * 32 + (col & 31); }
; DI unsigned pk2(float a, float b) { hwf32x2 f = {a, b}; hwbf16x2 r = __builtin_convertvector(f, hwbf16x2); return __builtin_bit_cast(unsigned, r); }
; DI float sigmoidf_(float z) { return 1.f / (1.f + __expf(-z)); }
; DI float siluf_(float z) { return z / (1.f + __expf(-z)); }
; template <int MX, bool OUT>
; DI void rec_chunk(const Params& p, int l, int b, int h, int dir, int T0, unsigned char* smem, f32x4 (&St)[4], float& nst, float& dtot, int tid, const RecRaw& raw) {
;     ...
;       ss += __shfl_xor(ss, 16);
;       ss += __shfl_xor(ss, 32);
;       const float rstd = rsqrtf(ss * (1.f / 64.f) + EPS);
;       const float* gvec = (MX ? p.ml_g : p.hg_g) + l * 64;
; #pragma unroll
;       for (int a = 0; a < 4; ++a) {
;         const int v0 = 16 * a + 4 * g;
;         const uint2 gt = *(const uint2*)(prow + GATE + cb + v0);
;         const float4 gg = *(const float4*)(gvec + v0);
;         float y0 = O[a][0] * rstd * gg.x * siluf_(__uint_as_float(gt.x << 16));
;         float y1 = O[a][1] * rstd * gg.y * siluf_(__uint_as_float(gt.x & 0xffff0000u));
;         float y2 = O[a][2] * rstd * gg.z * siluf_(__uint_as_float(gt.y << 16));
;         float y3 = O[a][3] * rstd * gg.w * siluf_(__uint_as_float(gt.y & 0xffff0000u));
;         if (MX == 1) {
;           const uint2 og = *(const uint2*)(prow + D_OG + h * 64 + v0);
;           y0 *= sigmoidf_(__uint_as_float(og.x << 16)); y1 *= sigmoidf_(__uint_as_float(og.x & 0xffff0000u));
;           y2 *= sigmoidf_(__uint_as_float(og.y << 16)); y3 *= sigmoidf_(__uint_as_float(og.y & 0xffff0000u));
;         }
;         *(uint2*)(MIX + kblk((int)orow, cb + v0, ROWS)) = make_uint2(pk2(y0, y1), pk2(y2, y3));
	v_add_f32_e32 v74, v74, v75
	ds_bpermute_b32 v69, v69, v74
	s_waitcnt lgkmcnt(0)
	v_add_f32_e32 v69, v74, v69
	v_fmamk_f32 v69, v69, 0x3c800000, v162
	v_cmp_gt_f32_e32 vcc, s38, v69
	v_mul_f32_e32 v74, 0x4b800000, v69
	s_nop 0
	v_cndmask_b32_e32 v69, v69, v74, vcc
	v_rsq_f32_e32 v69, v69
	s_nop 0
	v_mul_f32_e32 v74, 0x45800000, v69
	v_cndmask_b32_e32 v74, v69, v74, vcc
	v_mul_f32_e32 v100, v112, v74
	v_mul_f32_e32 v101, v113, v74
	s_nop 0
	v_mul_f32_e32 v56, v56, v100
	v_mul_f32_e32 v57, v57, v101
	v_mul_f32_e32 v100, v108, v74
	v_mul_f32_e32 v101, v109, v74
	v_mul_f32_e32 v56, v114, v56
	v_mul_f32_e32 v57, v115, v57
	v_mul_f32_e32 v58, v58, v100
	v_mul_f32_e32 v59, v59, v101
	v_cvt_pk_bf16_f32 v56, v56, v57
	v_mul_f32_e32 v58, v204, v58
	v_mul_f32_e32 v59, v205, v59
	s_nop 0
	v_cvt_pk_bf16_f32 v57, v58, v59
	global_store_dwordx2 v[96:97], v[56:57], off
	global_load_dwordx2 v[96:97], v[72:73], off offset:32
	s_nop 0
	global_load_dwordx4 v[56:59], v[86:87], off offset:64
	s_waitcnt vmcnt(0) lgkmcnt(0)
	v_lshlrev_b32_e32 v69, 16, v96
	v_and_b32_e32 v75, 0xffff0000, v96
	v_mul_f32_e32 v91, 0xbfb8aa3b, v69
	v_exp_f32_e32 v100, v91
	v_mul_f32_e32 v91, 0xbfb8aa3b, v75
	v_exp_f32_e32 v101, v91
	v_mul_f32_e32 v102, v210, v74
	v_mul_f32_e32 v103, v211, v74
	v_add_f32_e32 v100, 1.0, v100
	v_add_f32_e32 v101, 1.0, v101
	s_nop 0
	v_rcp_f32_e32 v93, v101
	v_mul_f32_e32 v56, v56, v102
	v_mul_f32_e32 v57, v57, v103
	v_fma_f32 v96, -v101, v93, 1.0
	v_fmac_f32_e32 v93, v96, v93
	v_mul_f32_e32 v102, v75, v93
	v_fma_f32 v103, -v101, v102, v75
	v_fmac_f32_e32 v102, v103, v93
	v_fma_f32 v91, -v101, v102, v75
	v_fma_f32 v91, v91, v93, v102
	v_div_fixup_f32 v101, v91, v101, v75
	v_rcp_f32_e32 v91, v100
	s_nop 0
	v_fma_f32 v93, -v100, v91, 1.0
	v_fmac_f32_e32 v91, v93, v91
	v_mul_f32_e32 v96, v69, v91
	v_fma_f32 v102, -v100, v96, v69
	v_fmac_f32_e32 v96, v102, v91
	v_fma_f32 v75, -v100, v96, v69
	v_fma_f32 v75, v75, v91, v96
	v_div_fixup_f32 v100, v75, v100, v69
	v_lshlrev_b32_e32 v69, 16, v97
	v_and_b32_e32 v75, 0xffff0000, v97
	v_mul_f32_e32 v91, 0xbfb8aa3b, v69
	v_exp_f32_e32 v96, v91
	v_mul_f32_e32 v91, 0xbfb8aa3b, v75
	v_exp_f32_e32 v97, v91
	v_mul_f32_e32 v56, v100, v56
	v_mul_f32_e32 v57, v101, v57
	v_mul_f32_e32 v100, v206, v74
	v_mul_f32_e32 v101, v207, v74
	v_cvt_pk_bf16_f32 v56, v56, v57
	v_add_f32_e32 v96, 1.0, v96
	v_add_f32_e32 v97, 1.0, v97
	v_mul_f32_e32 v58, v58, v100
	v_mul_f32_e32 v59, v59, v101
	v_rcp_f32_e32 v93, v97
	s_nop 0
	v_fma_f32 v100, -v97, v93, 1.0
	v_fmac_f32_e32 v93, v100, v93
	v_mul_f32_e32 v101, v75, v93
	v_fma_f32 v102, -v97, v101, v75
	v_fmac_f32_e32 v101, v102, v93
	v_fma_f32 v91, -v97, v101, v75
	v_fma_f32 v91, v91, v93, v101
	v_div_fixup_f32 v97, v91, v97, v75
	v_rcp_f32_e32 v91, v96
	s_nop 0
	v_fma_f32 v93, -v96, v91, 1.0
	v_fmac_f32_e32 v91, v93, v91
	v_mul_f32_e32 v100, v69, v91
	v_fma_f32 v101, -v96, v100, v69
	v_fmac_f32_e32 v100, v101, v91
	v_fma_f32 v75, -v96, v100, v69
	v_fma_f32 v75, v75, v91, v100
	v_div_fixup_f32 v96, v75, v96, v69
	v_mul_f32_e32 v58, v96, v58
	v_mul_f32_e32 v59, v97, v59
	s_nop 0
	v_cvt_pk_bf16_f32 v57, v58, v59
	global_store_dwordx2 v[70:71], v[56:57], off
	global_load_dwordx2 v[70:71], v[72:73], off offset:64
	s_nop 0
	global_load_dwordx4 v[56:59], v[86:87], off offset:128
	s_waitcnt vmcnt(0) lgkmcnt(0)
; DI size_t kblk(int row, int col, int nrows) { return ((size_t)(col >> 5) * nrows + row) * 32 + (col & 31); }
; DI unsigned pk2(float a, float b) { hwf32x2 f = {a, b}; hwbf16x2 r = __builtin_convertvector(f, hwbf16x2); return __builtin_bit_cast(unsigned, r); }
; DI float sigmoidf_(float z) { return 1.f / (1.f + __expf(-z)); }
; DI float siluf_(float z) { return z / (1.f + __expf(-z)); }
; template <int MX, bool OUT>
; DI void rec_chunk(const Params& p, int l, int b, int h, int dir, int T0, unsigned char* smem, f32x4 (&St)[4], float& nst, float& dtot, int tid, const RecRaw& raw) {
;     ...
; #pragma unroll
;       for (int a = 0; a < 4; ++a) {
;         const int v0 = 16 * a + 4 * g;
;         const uint2 gt = *(const uint2*)(prow + GATE + cb + v0);
;         const float4 gg = *(const float4*)(gvec + v0);
;         float y0 = O[a][0] * rstd * gg.x * siluf_(__uint_as_float(gt.x << 16));
;         float y1 = O[a][1] * rstd * gg.y * siluf_(__uint_as_float(gt.x & 0xffff0000u));
;         float y2 = O[a][2] * rstd * gg.z * siluf_(__uint_as_float(gt.y << 16));
;         float y3 = O[a][3] * rstd * gg.w * siluf_(__uint_as_float(gt.y & 0xffff0000u));
;         if (MX == 1) {
;           const uint2 og = *(const uint2*)(prow + D_OG + h * 64 + v0);
;           y0 *= sigmoidf_(__uint_as_float(og.x << 16)); y1 *= sigmoidf_(__uint_as_float(og.x & 0xffff0000u));
;           y2 *= sigmoidf_(__uint_as_float(og.y << 16)); y3 *= sigmoidf_(__uint_as_float(og.y & 0xffff0000u));
;         }
;         *(uint2*)(MIX + kblk((int)orow, cb + v0, ROWS)) = make_uint2(pk2(y0, y1), pk2(y2, y3));
	v_lshlrev_b32_e32 v69, 16, v70
	v_and_b32_e32 v70, 0xffff0000, v70
	v_mul_f32_e32 v75, 0xbfb8aa3b, v69
	v_exp_f32_e32 v96, v75
	v_mul_f32_e32 v100, v104, v74
	v_mul_f32_e32 v101, v105, v74
	v_mul_f32_e32 v75, 0xbfb8aa3b, v70
	v_exp_f32_e32 v97, v75
	v_mul_f32_e32 v56, v100, v56
	v_mul_f32_e32 v57, v101, v57
	v_add_f32_e32 v96, 1.0, v96
	v_add_f32_e32 v97, 1.0, v97
	s_nop 0
	v_rcp_f32_e32 v91, v97
	s_nop 0
	v_fma_f32 v93, -v97, v91, 1.0
	v_fmac_f32_e32 v91, v93, v91
	v_mul_f32_e32 v100, v70, v91
	v_fma_f32 v101, -v97, v100, v70
	v_fmac_f32_e32 v100, v101, v91
	v_fma_f32 v75, -v97, v100, v70
	v_fma_f32 v75, v75, v91, v100
	v_div_fixup_f32 v97, v75, v97, v70
	v_rcp_f32_e32 v75, v96
	s_nop 0
	v_fma_f32 v91, -v96, v75, 1.0
	v_fmac_f32_e32 v75, v91, v75
	v_mul_f32_e32 v93, v69, v75
	v_fma_f32 v100, -v96, v93, v69
	v_fmac_f32_e32 v93, v100, v75
	v_fma_f32 v70, -v96, v93, v69
	v_fma_f32 v70, v70, v75, v93
	v_div_fixup_f32 v96, v70, v96, v69
	v_lshlrev_b32_e32 v69, 16, v71
	v_and_b32_e32 v75, 0xffff0000, v71
	v_mul_f32_e32 v70, 0xbfb8aa3b, v69
	v_mul_f32_e32 v71, 0xbfb8aa3b, v75
	v_exp_f32_e32 v70, v70
	v_exp_f32_e32 v71, v71
	v_mul_f32_e32 v56, v56, v96
	v_mul_f32_e32 v57, v57, v97
	v_mul_f32_e32 v96, v98, v74
	v_mul_f32_e32 v97, v99, v74
	v_cvt_pk_bf16_f32 v56, v56, v57
	v_add_f32_e32 v70, 1.0, v70
	v_add_f32_e32 v71, 1.0, v71
	v_mul_f32_e32 v58, v96, v58
	v_mul_f32_e32 v59, v97, v59
	v_rcp_f32_e32 v93, v71
	s_nop 0
	v_fma_f32 v96, -v71, v93, 1.0
	v_fmac_f32_e32 v93, v96, v93
	v_mul_f32_e32 v97, v75, v93
	v_fma_f32 v98, -v71, v97, v75
	v_fmac_f32_e32 v97, v98, v93
	v_fma_f32 v91, -v71, v97, v75
	v_fma_f32 v91, v91, v93, v97
	v_div_fixup_f32 v71, v91, v71, v75
	v_rcp_f32_e32 v91, v70
	s_nop 0
	v_fma_f32 v93, -v70, v91, 1.0
	v_fmac_f32_e32 v91, v93, v91
	v_mul_f32_e32 v96, v69, v91
	v_fma_f32 v97, -v70, v96, v69
	v_fmac_f32_e32 v96, v97, v91
	v_fma_f32 v75, -v70, v96, v69
	v_fma_f32 v75, v75, v91, v96
	v_div_fixup_f32 v70, v75, v70, v69
	v_mul_f32_e32 v58, v58, v70
	v_mul_f32_e32 v59, v59, v71
	v_mul_f32_e32 v64, v64, v74
	v_mul_f32_e32 v65, v65, v74
	v_cvt_pk_bf16_f32 v57, v58, v59
	global_store_dwordx2 v[66:67], v[56:57], off
	global_load_dwordx2 v[66:67], v[72:73], off offset:96
	v_mov_b32_e32 v93, v161
	global_load_dwordx4 v[56:59], v[86:87], off offset:192
	s_waitcnt vmcnt(0) lgkmcnt(0)
	v_lshlrev_b32_e32 v69, 16, v66
	v_and_b32_e32 v66, 0xffff0000, v66
	v_mul_f32_e32 v70, 0xbfb8aa3b, v69
	v_mul_f32_e32 v56, v64, v56
	v_mul_f32_e32 v57, v65, v57
	v_mul_f32_e32 v64, 0xbfb8aa3b, v66
	v_exp_f32_e32 v70, v70
	v_exp_f32_e32 v71, v64
	s_nop 0
	v_add_f32_e32 v64, 1.0, v70
	v_add_f32_e32 v65, 1.0, v71
	s_nop 0
	v_rcp_f32_e32 v71, v65
	s_nop 0
	v_fma_f32 v72, -v65, v71, 1.0
	v_fmac_f32_e32 v71, v72, v71
	v_mul_f32_e32 v73, v66, v71
	v_fma_f32 v75, -v65, v73, v66
	v_fmac_f32_e32 v73, v75, v71
	v_fma_f32 v70, -v65, v73, v66
	v_fma_f32 v70, v70, v71, v73
	v_div_fixup_f32 v65, v70, v65, v66
	v_rcp_f32_e32 v70, v64
	v_mul_f32_e32 v62, v62, v74
	v_mul_f32_e32 v63, v63, v74
	v_fma_f32 v71, -v64, v70, 1.0
	v_fmac_f32_e32 v70, v71, v70
	v_mul_f32_e32 v72, v69, v70
	v_fma_f32 v73, -v64, v72, v69
	v_fmac_f32_e32 v72, v73, v70
	v_fma_f32 v66, -v64, v72, v69
	v_fma_f32 v66, v66, v70, v72
	v_div_fixup_f32 v64, v66, v64, v69
	v_lshlrev_b32_e32 v66, 16, v67
	v_and_b32_e32 v67, 0xffff0000, v67
	v_mul_f32_e32 v64, v56, v64
	v_mul_f32_e32 v65, v57, v65
	v_mul_f32_e32 v56, 0xbfb8aa3b, v66
	v_mul_f32_e32 v57, 0xbfb8aa3b, v67
	v_exp_f32_e32 v56, v56
	v_exp_f32_e32 v57, v57
	v_mul_f32_e32 v58, v62, v58
	v_mul_f32_e32 v59, v63, v59
	v_add_f32_e32 v56, 1.0, v56
	v_add_f32_e32 v57, 1.0, v57
	s_nop 0
	v_rcp_f32_e32 v63, v57
	s_nop 0
	v_fma_f32 v69, -v57, v63, 1.0
	v_fmac_f32_e32 v63, v69, v63
	v_mul_f32_e32 v70, v67, v63
	v_fma_f32 v71, -v57, v70, v67
	v_fmac_f32_e32 v70, v71, v63
	v_fma_f32 v62, -v57, v70, v67
	v_fma_f32 v62, v62, v63, v70
	v_div_fixup_f32 v57, v62, v57, v67
	v_rcp_f32_e32 v63, v56
	s_mov_b64 s[10:11], 0
	v_fma_f32 v67, -v56, v63, 1.0
	v_fmac_f32_e32 v63, v67, v63
	v_mul_f32_e32 v69, v66, v63
	v_fma_f32 v70, -v56, v69, v66
	v_fmac_f32_e32 v69, v70, v63
	v_fma_f32 v62, -v56, v69, v66
	v_fma_f32 v62, v62, v63, v69
	v_div_fixup_f32 v56, v62, v56, v66
	v_mul_f32_e32 v56, v58, v56
	v_mul_f32_e32 v57, v59, v57
	v_cvt_pk_bf16_f32 v62, v64, v65
	v_lshl_add_u64 v[58:59], v[60:61], 0, v[92:93]
	global_store_dword v[58:59], v62, off

; template <int MX>
; DI void rec_output(const Params& p, int l, int b, int h, int sc, unsigned char* smem) {
;     ...
;     SumRegs cur = rec_ldsum<MX>(p, b, h, dir, 0, w, g, col, tid);
; #pragma unroll 1
;     for (int i = 0; i < npre; ++i) {
;       const SumRegs nxt = rec_ldsum<MX>(p, b, h, dir, (i + 1 < npre) ? i + 1 : i, w, g, col, tid);
;       St[0] = cur.d[0] * St[0] + cur.E0;
;       St[1] = cur.d[1] * St[1] + cur.E1;
;       St[2] = cur.d[2] * St[2] + cur.E2;
;       St[3] = cur.d[3] * St[3] + cur.E3;
;       if (MX == 1 && tid < 64) nst = cur.nd * nst + cur.nn;
;       cur = nxt;
;     }
.LBB0_840:
	s_or_b64 exec, exec, s[26:27]
	s_waitcnt vmcnt(0) lgkmcnt(0)
	v_fma_f32 v14, v14, v16, v26
	v_fma_f32 v15, v15, v16, v27
	v_fma_f32 v12, v12, v16, v20
	v_fma_f32 v13, v13, v16, v21
	v_fmac_f32_e32 v17, v236, v19
	v_fma_f32 v2, v2, v28, v38
	v_fma_f32 v3, v3, v28, v39
	v_fma_f32 v0, v0, v28, v34
	v_fma_f32 v1, v1, v28, v35
	v_fma_f32 v6, v6, v22, v36
	v_fma_f32 v7, v7, v22, v37
	v_fma_f32 v4, v4, v22, v32
	v_fma_f32 v5, v5, v22, v33
	v_fma_f32 v10, v10, v18, v30
	v_fma_f32 v11, v11, v18, v31
	v_fma_f32 v8, v8, v18, v24
	v_fma_f32 v9, v9, v18, v25
	s_cmp_eq_u32 s44, s45
	v_cndmask_b32_e64 v236, v236, v17, s[10:11]
	s_cbranch_scc1 .LBB0_842
	v_mov_b32_e32 v17, v59
	v_mov_b32_e32 v19, v58
	v_mov_b32_e32 v28, v42
	v_mov_b32_e32 v22, v43
	v_mov_b32_e32 v18, v44
	v_mov_b32_e32 v16, v45
	v_mov_b32_e32 v20, v55
	v_mov_b32_e32 v21, v52
	v_mov_b32_e32 v26, v57
	v_mov_b32_e32 v27, v56
	v_mov_b32_e32 v24, v48
	v_mov_b32_e32 v25, v49
	v_mov_b32_e32 v30, v53
	v_mov_b32_e32 v31, v54
	v_mov_b32_e32 v34, v23
	v_mov_b32_e32 v35, v29
	v_mov_b32_e32 v38, v50
	v_mov_b32_e32 v39, v51
	v_mov_b32_e32 v32, v40
	v_mov_b32_e32 v33, v41
	v_mov_b32_e32 v36, v46
	v_mov_b32_e32 v37, v47
	s_branch .LBB0_838

; DI size_t kblk(int row, int col, int nrows) { return ((size_t)(col >> 5) * nrows + row) * 32 + (col & 31); }
; DI unsigned pk2(float a, float b) { hwf32x2 f = {a, b}; hwbf16x2 r = __builtin_convertvector(f, hwbf16x2); return __builtin_bit_cast(unsigned, r); }
; #define MFMA16(a, b, c) __builtin_amdgcn_mfma_f32_16x16x32_bf16((a), (b), (c), 0, 0, 0)
; template <int MX, bool OUT>
; DI void rec_chunk(const Params& p, int l, int b, int h, int dir, int T0, unsigned char* smem, f32x4 (&St)[4], float& nst, float& dtot, int tid, const RecRaw& raw) {
;     ...
; #pragma unroll
;     for (int ks = 0; ks < 2; ++ks) {
;       const bf16x8 fb = *(const bf16x8*)(smem + L_QS + swz(t, ks * 4 + g));
; #pragma unroll
;       for (int a = 0; a < 4; ++a) {
;         const bf16x8 fa = *(const bf16x8*)(smem + L_STT + swz(16 * a + col, ks * 4 + g));
;         O[a] = MFMA16(fa, fb, O[a]);
;       }
;     }
;     if (MX == 1) {
;       const float inv = 1.f / fmaxf(fabsf(den), 1.f);
; #pragma unroll
;       for (int a = 0; a < 4; ++a)
; #pragma unroll
;         for (int j = 0; j < 4; ++j) O[a][j] *= inv;
;     }
;     if (dir == 0) {
; #pragma unroll
;       for (int a = 0; a < 4; ++a) *(uint2*)(MIX + kblk((int)orow, cb + 16 * a + 4 * g, ROWS)) = make_uint2(pk2(O[a][0], O[a][1]), pk2(O[a][2], O[a][3]));
;     } else {
;       float ss = 0.f;
; #pragma unroll
;       for (int a = 0; a < 4; ++a) {
;         const uint2 u = *(const uint2*)(MIX + kblk((int)orow, cb + 16 * a + 4 * g, ROWS));
;         O[a][0] += __uint_as_float(u.x << 16); O[a][1] += __uint_as_float(u.x & 0xffff0000u);
;         O[a][2] += __uint_as_float(u.y << 16); O[a][3] += __uint_as_float(u.y & 0xffff0000u);
; #pragma unroll
;         for (int j = 0; j < 4; ++j) ss += O[a][j] * O[a][j];
;       }
;       ss += __shfl_xor(ss, 16);
;       ss += __shfl_xor(ss, 32);
.LBB0_928:
	s_or_b64 exec, exec, s[0:1]
	ds_read_b128 v[42:45], v242 offset:32768
	ds_read_b128 v[46:49], v240 offset:57344
	ds_read_b128 v[50:53], v240 offset:59392
	s_add_i32 s0, s54, -1
	v_mov_b32_e32 v40, s0
	v_cndmask_b32_e64 v40, v93, v40, s[40:41]
	s_waitcnt lgkmcnt(1)
	v_mfma_f32_16x16x32_bf16 v[46:49], v[46:49], v[42:45], v[56:59]
	v_lshlrev_b32_e32 v40, 6, v40
	v_add_u32_e32 v40, s49, v40
	v_mov_b32_e32 v41, v161
	ds_read_b128 v[54:57], v240 offset:61440
	s_waitcnt lgkmcnt(1)
	v_mfma_f32_16x16x32_bf16 v[50:53], v[50:53], v[42:45], v[60:63]
	v_lshl_add_u64 v[40:41], v[40:41], 0, v[84:85]
	s_nop 1
	ds_read_b128 v[58:61], v240 offset:63488
	s_waitcnt lgkmcnt(1)
	v_mfma_f32_16x16x32_bf16 v[54:57], v[54:57], v[42:45], v[64:67]
	s_waitcnt lgkmcnt(0)
	v_mfma_f32_16x16x32_bf16 v[42:45], v[58:61], v[42:45], v[72:75]
	ds_read_b128 v[58:61], v241 offset:32768
	ds_read_b128 v[62:65], v239 offset:57344
	s_waitcnt lgkmcnt(0)
	v_mfma_f32_16x16x32_bf16 v[46:49], v[62:65], v[58:61], v[46:49]
	ds_read_b128 v[62:65], v239 offset:59392
	s_waitcnt lgkmcnt(0)
	v_mfma_f32_16x16x32_bf16 v[50:53], v[62:65], v[58:61], v[50:53]
	ds_read_b128 v[62:65], v239 offset:61440
	s_waitcnt lgkmcnt(0)
	v_mfma_f32_16x16x32_bf16 v[62:65], v[62:65], v[58:61], v[54:57]
	s_nop 2
	ds_read_b128 v[54:57], v239 offset:63488
	s_waitcnt lgkmcnt(0)
	v_mfma_f32_16x16x32_bf16 v[42:45], v[54:57], v[58:61], v[42:45]
	v_add_f32_e32 v54, v95, v100
	v_max_f32_e64 v54, |v54|, 1.0
	v_rcp_f32_e32 v56, v54
	s_mov_b64 s[0:1], -1
	v_fma_f32 v57, -v54, v56, 1.0
	v_fmac_f32_e32 v56, v57, v56
	v_mov_b32_e64 v57, 1.0
	v_mul_f32_e32 v58, v57, v56
	v_fma_f32 v59, -v54, v58, v57
	v_fmac_f32_e32 v58, v59, v56
	v_fma_f32 v55, -v54, v58, v57
	v_fma_f32 v55, v55, v56, v58
	v_div_fixup_f32 v60, v55, v54, 1.0
	v_mul_f32_e32 v54, v60, v46
	v_mul_f32_e32 v55, v60, v47
	v_mul_f32_e32 v46, v60, v42
	v_mul_f32_e32 v47, v60, v43
	v_ashrrev_i32_e32 v43, 31, v40
	v_mov_b32_e32 v42, v40
	v_mul_f32_e32 v58, v60, v48
	v_mul_f32_e32 v59, v60, v49
	v_mul_f32_e32 v50, v60, v50
	v_mul_f32_e32 v51, v60, v51
	v_mul_f32_e32 v56, v60, v52
	v_mul_f32_e32 v57, v60, v53
	v_mul_f32_e32 v48, v60, v62
	v_mul_f32_e32 v49, v60, v63
	v_mul_f32_e32 v52, v60, v64
	v_mul_f32_e32 v53, v60, v65
	v_mul_f32_e32 v44, v60, v44
	v_mul_f32_e32 v45, v60, v45
	v_lshl_add_u64 v[60:61], v[42:43], 0, s[42:43]
	v_lshl_add_u64 v[62:63], v[42:43], 0, s[28:29]
	v_lshl_add_u64 v[42:43], v[42:43], 0, s[30:31]
	s_andn2_b64 vcc, exec, s[12:13]
	v_lshlrev_b64 v[64:65], 6, v[60:61]
	v_lshlrev_b64 v[62:63], 6, v[62:63]
	v_lshlrev_b64 v[60:61], 6, v[42:43]
	s_cbranch_vccnz .LBB0_930
	v_lshl_add_u64 v[102:103], v[90:91], 0, v[62:63]
	global_load_dwordx2 v[66:67], v[102:103], off
	v_mov_b64_e32 v[42:43], s[24:25]
	v_mad_u64_u32 v[42:43], s[0:1], v40, s33, v[42:43]
	v_mad_i32_i24 v43, v41, s33, v43
	s_mov_b64 s[0:1], 0x1a20
	v_mov_b32_e32 v93, v161
	v_lshl_add_u64 v[74:75], v[42:43], 0, s[0:1]
	v_lshl_add_u64 v[104:105], v[74:75], 0, s[2:3]
	v_lshl_add_u64 v[74:75], v[74:75], 0, v[92:93]
	v_lshl_add_u64 v[106:107], v[86:87], 0, v[64:65]
	v_lshl_add_u64 v[74:75], v[74:75], 0, s[2:3]
	global_load_dwordx2 v[40:41], v[106:107], off
	s_mov_b32 s21, s3
	v_lshl_add_u64 v[42:43], v[42:43], 0, s[20:21]
	v_lshl_add_u64 v[42:43], v[42:43], 0, v[92:93]
	s_mov_b64 s[0:1], 0x1820
	v_lshl_add_u64 v[104:105], v[104:105], 0, v[92:93]
	global_load_dwordx2 v[74:75], v[74:75], off
	s_waitcnt vmcnt(0) lgkmcnt(0)
	v_lshlrev_b32_e32 v100, 16, v66
	v_and_b32_e32 v101, 0xffff0000, v66
	v_lshlrev_b32_e32 v108, 16, v67
	v_and_b32_e32 v109, 0xffff0000, v67
	v_lshl_add_u64 v[66:67], s[22:23], 0, v[60:61]
	v_lshl_add_u64 v[72:73], v[66:67], 0, v[92:93]
	global_load_dwordx2 v[68:69], v[72:73], off
	v_lshlrev_b32_e32 v128, 16, v40
	v_and_b32_e32 v129, 0xffff0000, v40
	v_lshlrev_b32_e32 v40, 16, v41
	v_and_b32_e32 v41, 0xffff0000, v41
	v_add_f32_e32 v128, v54, v128
	v_add_f32_e32 v129, v55, v129
	v_lshlrev_b32_e32 v95, 16, v74
	v_and_b32_e32 v243, 0xffff0000, v74
	v_lshlrev_b32_e32 v130, 16, v75
	v_and_b32_e32 v131, 0xffff0000, v75
	v_lshl_add_u64 v[74:75], v[42:43], 0, s[0:1]
	v_add_co_u32_e32 v42, vcc, s16, v42
	v_mul_f32_e32 v120, 0xbfb8aa3b, v130
	s_nop 0
	v_addc_co_u32_e32 v43, vcc, 0, v43, vcc
	v_mul_f32_e32 v121, 0xbfb8aa3b, v131
	global_load_dwordx2 v[42:43], v[42:43], off offset:2080
	v_exp_f32_e32 v120, v120
	v_exp_f32_e32 v121, v121
	s_waitcnt vmcnt(0) lgkmcnt(0)
; DI size_t kblk(int row, int col, int nrows) { return ((size_t)(col >> 5) * nrows + row) * 32 + (col & 31); }
; DI unsigned pk2(float a, float b) { hwf32x2 f = {a, b}; hwbf16x2 r = __builtin_convertvector(f, hwbf16x2); return __builtin_bit_cast(unsigned, r); }
; DI float sigmoidf_(float z) { return 1.f / (1.f + __expf(-z)); }
; DI float siluf_(float z) { return z / (1.f + __expf(-z)); }
; template <int MX, bool OUT>
; DI void rec_chunk(const Params& p, int l, int b, int h, int dir, int T0, unsigned char* smem, f32x4 (&St)[4], float& nst, float& dtot, int tid, const RecRaw& raw) {
;     ...
;       float ss = 0.f;
; #pragma unroll
;       for (int a = 0; a < 4; ++a) {
;         const uint2 u = *(const uint2*)(MIX + kblk((int)orow, cb + 16 * a + 4 * g, ROWS));
;         O[a][0] += __uint_as_float(u.x << 16); O[a][1] += __uint_as_float(u.x & 0xffff0000u);
;         O[a][2] += __uint_as_float(u.y << 16); O[a][3] += __uint_as_float(u.y & 0xffff0000u);
; #pragma unroll
;         for (int j = 0; j < 4; ++j) ss += O[a][j] * O[a][j];
;       }
;       ss += __shfl_xor(ss, 16);
;       ss += __shfl_xor(ss, 32);
;       const float rstd = rsqrtf(ss * (1.f / 64.f) + EPS);
;       const float* gvec = (MX ? p.ml_g : p.hg_g) + l * 64;
; #pragma unroll
;       for (int a = 0; a < 4; ++a) {
;         const int v0 = 16 * a + 4 * g;
;         const uint2 gt = *(const uint2*)(prow + GATE + cb + v0);
;         const float4 gg = *(const float4*)(gvec + v0);
;         float y0 = O[a][0] * rstd * gg.x * siluf_(__uint_as_float(gt.x << 16));
;         float y1 = O[a][1] * rstd * gg.y * siluf_(__uint_as_float(gt.x & 0xffff0000u));
;         float y2 = O[a][2] * rstd * gg.z * siluf_(__uint_as_float(gt.y << 16));
;         float y3 = O[a][3] * rstd * gg.w * siluf_(__uint_as_float(gt.y & 0xffff0000u));
;         if (MX == 1) {
;           const uint2 og = *(const uint2*)(prow + D_OG + h * 64 + v0);
;           y0 *= sigmoidf_(__uint_as_float(og.x << 16)); y1 *= sigmoidf_(__uint_as_float(og.x & 0xffff0000u));
;           y2 *= sigmoidf_(__uint_as_float(og.y << 16)); y3 *= sigmoidf_(__uint_as_float(og.y & 0xffff0000u));
;         }
;         *(uint2*)(MIX + kblk((int)orow, cb + v0, ROWS)) = make_uint2(pk2(y0, y1), pk2(y2, y3));
	v_lshlrev_b32_e32 v110, 16, v68
	v_and_b32_e32 v111, 0xffff0000, v68
	v_add_f32_e32 v120, 1.0, v120
	v_add_f32_e32 v121, 1.0, v121
	v_lshlrev_b32_e32 v112, 16, v69
	v_rcp_f32_e32 v133, v121
	v_and_b32_e32 v113, 0xffff0000, v69
	global_load_dwordx2 v[68:69], v[72:73], off offset:32
	v_add_f32_e32 v110, v48, v110
	v_add_f32_e32 v111, v49, v111
	v_fma_f32 v244, -v121, v133, 1.0
	v_fmac_f32_e32 v133, v244, v133
	v_mul_f32_e32 v245, v131, v133
	v_fma_f32 v246, -v121, v245, v131
	v_fmac_f32_e32 v245, v246, v133
	v_fma_f32 v132, -v121, v245, v131
	v_fma_f32 v132, v132, v133, v245
	v_div_fixup_f32 v121, v132, v121, v131
	v_rcp_f32_e32 v132, v120
	v_mul_f32_e32 v250, v110, v110
	v_mul_f32_e32 v251, v111, v111
	v_lshlrev_b32_e32 v118, 16, v42
	v_and_b32_e32 v42, 0xffff0000, v42
	v_fma_f32 v133, -v120, v132, 1.0
	v_fmac_f32_e32 v132, v133, v132
	v_mul_f32_e32 v244, v130, v132
	v_fma_f32 v245, -v120, v244, v130
	v_fmac_f32_e32 v244, v245, v132
	v_fma_f32 v131, -v120, v244, v130
	v_fma_f32 v131, v131, v132, v244
	v_mul_f32_e32 v132, 0xbfb8aa3b, v95
	v_mul_f32_e32 v133, 0xbfb8aa3b, v243
	v_exp_f32_e32 v132, v132
	v_exp_f32_e32 v133, v133
	v_div_fixup_f32 v120, v131, v120, v130
	v_mul_f32_e32 v130, v128, v128
	v_mul_f32_e32 v131, v129, v129
	v_mul_f32_e32 v118, 0xbfb8aa3b, v118
	v_add_f32_e32 v132, 1.0, v132
	v_add_f32_e32 v133, 1.0, v133
	v_mul_f32_e32 v42, 0xbfb8aa3b, v42
	v_rcp_f32_e32 v245, v133
	v_add_f32_e32 v93, v130, v131
	v_exp_f32_e32 v126, v118
	v_exp_f32_e32 v127, v42
	v_fma_f32 v246, -v133, v245, 1.0
	v_fmac_f32_e32 v245, v246, v245
	v_mul_f32_e32 v247, v243, v245
	v_fma_f32 v248, -v133, v247, v243
	v_fmac_f32_e32 v247, v248, v245
	v_fma_f32 v244, -v133, v247, v243
	v_fma_f32 v244, v244, v245, v247
	v_div_fixup_f32 v133, v244, v133, v243
	v_rcp_f32_e32 v244, v132
	v_lshlrev_b32_e32 v42, 16, v43
	v_add_f32_e32 v118, v58, v40
	v_add_f32_e32 v119, v59, v41
	v_add_f32_e32 v248, v50, v100
	v_add_f32_e32 v249, v51, v101
	v_fma_f32 v245, -v132, v244, 1.0
	v_fmac_f32_e32 v244, v245, v244
	v_mul_f32_e32 v246, v95, v244
	v_fma_f32 v247, -v132, v246, v95
	v_fmac_f32_e32 v246, v247, v244
	v_fma_f32 v243, -v132, v246, v95
	v_fma_f32 v243, v243, v244, v246
	v_div_fixup_f32 v132, v243, v132, v95
	v_mul_f32_e32 v100, v248, v248
	v_mul_f32_e32 v101, v249, v249
	v_mul_f32_e32 v42, 0xbfb8aa3b, v42
	v_mul_f32_e32 v122, v118, v118
	v_mul_f32_e32 v123, v119, v119
	v_exp_f32_e32 v124, v42
	v_and_b32_e32 v42, 0xffff0000, v43
	v_add_f32_e32 v93, v93, v122
	v_mul_f32_e32 v42, 0xbfb8aa3b, v42
	v_add_f32_e32 v93, v123, v93
	v_add_f32_e32 v126, 1.0, v126
	v_add_f32_e32 v127, 1.0, v127
	v_exp_f32_e32 v125, v42
	global_load_dwordx4 v[40:43], v[88:89], off
	v_rcp_f32_e32 v243, v127
	v_add_f32_e32 v124, 1.0, v124
	v_add_f32_e32 v125, 1.0, v125
	v_add_f32_e32 v93, v100, v93
	v_add_f32_e32 v93, v101, v93
	v_fma_f32 v244, -v127, v243, 1.0
	v_fmac_f32_e32 v243, v244, v243
	v_mov_b32_e64 v244, 1.0
	v_mul_f32_e32 v245, v244, v243
	v_fma_f32 v246, -v127, v245, v244
	v_fmac_f32_e32 v245, v246, v243
	v_fma_f32 v95, -v127, v245, v244
	v_fma_f32 v95, v95, v243, v245
	v_div_fixup_f32 v127, v95, v127, 1.0
	v_rcp_f32_e32 v243, v126
	s_waitcnt vmcnt(0) lgkmcnt(0)
	v_lshlrev_b32_e32 v70, 16, v68
	v_and_b32_e32 v71, 0xffff0000, v68
	v_add_f32_e32 v70, v46, v70
	v_add_f32_e32 v71, v47, v71
	v_fma_f32 v244, -v126, v243, 1.0
	v_fmac_f32_e32 v243, v244, v243
	v_mov_b32_e64 v244, 1.0
	v_mul_f32_e32 v245, v244, v243
	v_fma_f32 v246, -v126, v245, v244
	v_fmac_f32_e32 v245, v246, v243
	v_fma_f32 v95, -v126, v245, v244
	v_fma_f32 v95, v95, v243, v245
	v_div_fixup_f32 v126, v95, v126, 1.0
	v_rcp_f32_e32 v243, v125
	v_lshlrev_b32_e32 v68, 16, v69
	v_and_b32_e32 v69, 0xffff0000, v69
	v_mul_f32_e32 v114, v70, v70
	v_mul_f32_e32 v115, v71, v71
	v_fma_f32 v244, -v125, v243, 1.0
	v_fmac_f32_e32 v243, v244, v243
	v_mov_b32_e64 v244, 1.0
	v_mul_f32_e32 v245, v244, v243
	v_fma_f32 v246, -v125, v245, v244
	v_fmac_f32_e32 v245, v246, v243
	v_fma_f32 v95, -v125, v245, v244
	v_fma_f32 v95, v95, v243, v245
	v_div_fixup_f32 v125, v95, v125, 1.0
	v_rcp_f32_e32 v243, v124
	v_add_f32_e32 v68, v44, v68
	v_add_f32_e32 v69, v45, v69
	v_fma_f32 v244, -v124, v243, 1.0
	v_fmac_f32_e32 v243, v244, v243
	v_mov_b32_e64 v244, 1.0
	v_mul_f32_e32 v245, v244, v243
	v_fma_f32 v246, -v124, v245, v244
	v_fmac_f32_e32 v245, v246, v243
	v_fma_f32 v95, -v124, v245, v244
	v_fma_f32 v95, v95, v243, v245
	v_add_f32_e32 v244, v56, v108
	v_add_f32_e32 v245, v57, v109
	v_add_f32_e32 v108, v52, v112
	v_add_f32_e32 v109, v53, v113
	v_mul_f32_e32 v246, v244, v244
	v_mul_f32_e32 v247, v245, v245
	v_mul_f32_e32 v112, v108, v108
	v_mul_f32_e32 v113, v109, v109
	v_add_f32_e32 v93, v246, v93
	v_add_f32_e32 v93, v247, v93
	v_add_f32_e32 v93, v250, v93
	v_add_f32_e32 v93, v251, v93
	v_add_f32_e32 v93, v112, v93
	v_add_f32_e32 v93, v113, v93
	v_add_f32_e32 v93, v114, v93
	v_mul_f32_e32 v116, v68, v68
	v_mul_f32_e32 v117, v69, v69
	v_add_f32_e32 v93, v115, v93
	v_add_f32_e32 v93, v116, v93
	v_add_f32_e32 v93, v117, v93
	v_div_fixup_f32 v124, v95, v124, 1.0
	ds_bpermute_b32 v95, v149, v93
	s_waitcnt lgkmcnt(0)
	v_add_f32_e32 v93, v93, v95
	ds_bpermute_b32 v95, v150, v93
	s_waitcnt lgkmcnt(0)
; DI size_t kblk(int row, int col, int nrows) { return ((size_t)(col >> 5) * nrows + row) * 32 + (col & 31); }
; DI unsigned pk2(float a, float b) { hwf32x2 f = {a, b}; hwbf16x2 r = __builtin_convertvector(f, hwbf16x2); return __builtin_bit_cast(unsigned, r); }
; DI float sigmoidf_(float z) { return 1.f / (1.f + __expf(-z)); }
; DI float siluf_(float z) { return z / (1.f + __expf(-z)); }
; template <int MX, bool OUT>
; DI void rec_chunk(const Params& p, int l, int b, int h, int dir, int T0, unsigned char* smem, f32x4 (&St)[4], float& nst, float& dtot, int tid, const RecRaw& raw) {
;     ...
;       ss += __shfl_xor(ss, 16);
;       ss += __shfl_xor(ss, 32);
;       const float rstd = rsqrtf(ss * (1.f / 64.f) + EPS);
;       const float* gvec = (MX ? p.ml_g : p.hg_g) + l * 64;
; #pragma unroll
;       for (int a = 0; a < 4; ++a) {
;         const int v0 = 16 * a + 4 * g;
;         const uint2 gt = *(const uint2*)(prow + GATE + cb + v0);
;         const float4 gg = *(const float4*)(gvec + v0);
;         float y0 = O[a][0] * rstd * gg.x * siluf_(__uint_as_float(gt.x << 16));
;         float y1 = O[a][1] * rstd * gg.y * siluf_(__uint_as_float(gt.x & 0xffff0000u));
;         float y2 = O[a][2] * rstd * gg.z * siluf_(__uint_as_float(gt.y << 16));
;         float y3 = O[a][3] * rstd * gg.w * siluf_(__uint_as_float(gt.y & 0xffff0000u));
;         if (MX == 1) {
;           const uint2 og = *(const uint2*)(prow + D_OG + h * 64 + v0);
;           y0 *= sigmoidf_(__uint_as_float(og.x << 16)); y1 *= sigmoidf_(__uint_as_float(og.x & 0xffff0000u));
;           y2 *= sigmoidf_(__uint_as_float(og.y << 16)); y3 *= sigmoidf_(__uint_as_float(og.y & 0xffff0000u));
;         }
;         *(uint2*)(MIX + kblk((int)orow, cb + v0, ROWS)) = make_uint2(pk2(y0, y1), pk2(y2, y3));
	v_add_f32_e32 v93, v93, v95
	v_fmamk_f32 v93, v93, 0x3c800000, v162
	v_cmp_gt_f32_e32 vcc, s38, v93
	v_mul_f32_e32 v95, 0x4b800000, v93
	s_nop 0
	v_cndmask_b32_e32 v93, v93, v95, vcc
	v_rsq_f32_e32 v93, v93
	s_nop 0
	v_mul_f32_e32 v95, 0x45800000, v93
	v_cndmask_b32_e32 v100, v93, v95, vcc
	v_mul_f32_e32 v112, v128, v100
	v_mul_f32_e32 v113, v129, v100
	s_nop 0
	v_mul_f32_e32 v40, v40, v112
	v_mul_f32_e32 v41, v41, v113
	v_mul_f32_e32 v112, v118, v100
	v_mul_f32_e32 v113, v119, v100
	v_mul_f32_e32 v40, v132, v40
	v_mul_f32_e32 v41, v133, v41
	v_mul_f32_e32 v42, v42, v112
	v_mul_f32_e32 v43, v43, v113
	v_mul_f32_e32 v40, v126, v40
	v_mul_f32_e32 v41, v127, v41
	v_mul_f32_e32 v42, v120, v42
	v_mul_f32_e32 v43, v121, v43
	v_cvt_pk_bf16_f32 v40, v40, v41
	v_mul_f32_e32 v42, v124, v42
	v_mul_f32_e32 v43, v125, v43
	s_nop 0
	v_cvt_pk_bf16_f32 v41, v42, v43
	global_store_dwordx2 v[106:107], v[40:41], off
	global_load_dwordx2 v[40:41], v[104:105], off offset:32
	s_nop 0
	global_load_dwordx4 v[112:115], v[88:89], off offset:64
	v_mul_f32_e32 v106, v248, v100
	v_mul_f32_e32 v107, v249, v100
	s_waitcnt vmcnt(0) lgkmcnt(0)
	v_lshlrev_b32_e32 v93, 16, v40
	v_and_b32_e32 v40, 0xffff0000, v40
	v_mul_f32_e32 v42, 0xbfb8aa3b, v93
	v_mul_f32_e32 v43, 0xbfb8aa3b, v40
	v_exp_f32_e32 v42, v42
	v_exp_f32_e32 v43, v43
	v_mul_f32_e32 v106, v112, v106
	v_mul_f32_e32 v107, v113, v107
	v_add_f32_e32 v42, 1.0, v42
	v_add_f32_e32 v43, 1.0, v43
	s_nop 0
	v_rcp_f32_e32 v101, v43
	s_nop 0
	v_fma_f32 v112, -v43, v101, 1.0
	v_fmac_f32_e32 v101, v112, v101
	v_mul_f32_e32 v113, v40, v101
	v_fma_f32 v116, -v43, v113, v40
	v_fmac_f32_e32 v113, v116, v101
	v_fma_f32 v95, -v43, v113, v40
	v_fma_f32 v95, v95, v101, v113
	v_div_fixup_f32 v43, v95, v43, v40
	v_rcp_f32_e32 v95, v42
	s_nop 0
	v_fma_f32 v101, -v42, v95, 1.0
	v_fmac_f32_e32 v95, v101, v95
	v_mul_f32_e32 v112, v93, v95
	v_fma_f32 v113, -v42, v112, v93
	v_fmac_f32_e32 v112, v113, v95
	v_fma_f32 v40, -v42, v112, v93
	v_fma_f32 v40, v40, v95, v112
	v_div_fixup_f32 v42, v40, v42, v93
	v_lshlrev_b32_e32 v93, 16, v41
	v_and_b32_e32 v95, 0xffff0000, v41
	v_mul_f32_e32 v40, 0xbfb8aa3b, v93
	v_mul_f32_e32 v41, 0xbfb8aa3b, v95
	v_exp_f32_e32 v40, v40
	v_exp_f32_e32 v41, v41
	v_mul_f32_e32 v42, v42, v106
	v_mul_f32_e32 v43, v43, v107
	v_mul_f32_e32 v106, v244, v100
	v_mul_f32_e32 v107, v245, v100
	v_add_f32_e32 v40, 1.0, v40
	v_add_f32_e32 v41, 1.0, v41
	s_nop 0
	v_rcp_f32_e32 v112, v41
	v_mul_f32_e32 v106, v114, v106
	v_mul_f32_e32 v107, v115, v107
	v_fma_f32 v113, -v41, v112, 1.0
	v_fmac_f32_e32 v112, v113, v112
	v_mul_f32_e32 v114, v95, v112
	v_fma_f32 v115, -v41, v114, v95
	v_fmac_f32_e32 v114, v115, v112
	v_fma_f32 v101, -v41, v114, v95
	v_fma_f32 v101, v101, v112, v114
	v_div_fixup_f32 v41, v101, v41, v95
	v_rcp_f32_e32 v101, v40
	s_nop 0
	v_fma_f32 v112, -v40, v101, 1.0
	v_fmac_f32_e32 v101, v112, v101
	v_mul_f32_e32 v113, v93, v101
	v_fma_f32 v114, -v40, v113, v93
	v_fmac_f32_e32 v113, v114, v101
	v_fma_f32 v95, -v40, v113, v93
	v_fma_f32 v95, v95, v101, v113
	v_div_fixup_f32 v40, v95, v40, v93
	v_mul_f32_e32 v40, v40, v106
	v_mul_f32_e32 v41, v41, v107
	global_load_dwordx2 v[106:107], v[74:75], off offset:32
	s_waitcnt vmcnt(0) lgkmcnt(0)
	v_lshlrev_b32_e32 v93, 16, v106
	v_mul_f32_e32 v93, 0xbfb8aa3b, v93
	v_exp_f32_e32 v112, v93
	v_and_b32_e32 v93, 0xffff0000, v106
	v_mul_f32_e32 v93, 0xbfb8aa3b, v93
	v_exp_f32_e32 v113, v93
	s_nop 0
	v_add_f32_e32 v112, 1.0, v112
	v_add_f32_e32 v113, 1.0, v113
	s_nop 0
	v_rcp_f32_e32 v95, v113
	s_nop 0
	v_fma_f32 v101, -v113, v95, 1.0
	v_fmac_f32_e32 v95, v101, v95
	v_mov_b32_e64 v101, 1.0
	v_mul_f32_e32 v106, v101, v95
	v_fma_f32 v114, -v113, v106, v101
	v_fmac_f32_e32 v106, v114, v95
	v_fma_f32 v93, -v113, v106, v101
	v_fma_f32 v93, v93, v95, v106
	v_div_fixup_f32 v113, v93, v113, 1.0
	v_rcp_f32_e32 v95, v112
	s_nop 0
	v_fma_f32 v101, -v112, v95, 1.0
	v_fmac_f32_e32 v95, v101, v95
	v_mov_b32_e64 v101, 1.0
	v_mul_f32_e32 v106, v101, v95
	v_fma_f32 v114, -v112, v106, v101
	v_fmac_f32_e32 v106, v114, v95
	v_fma_f32 v93, -v112, v106, v101
	v_fma_f32 v93, v93, v95, v106
	v_div_fixup_f32 v112, v93, v112, 1.0
	v_lshlrev_b32_e32 v93, 16, v107
	v_mul_f32_e32 v93, 0xbfb8aa3b, v93
	v_exp_f32_e32 v106, v93
	v_and_b32_e32 v93, 0xffff0000, v107
	v_mul_f32_e32 v93, 0xbfb8aa3b, v93
	v_exp_f32_e32 v107, v93
	v_mul_f32_e32 v42, v42, v112
	v_mul_f32_e32 v43, v43, v113
	v_add_f32_e32 v106, 1.0, v106
	v_add_f32_e32 v107, 1.0, v107
	s_nop 0
	v_rcp_f32_e32 v95, v107
	v_cvt_pk_bf16_f32 v42, v42, v43
	v_fma_f32 v101, -v107, v95, 1.0
	v_fmac_f32_e32 v95, v101, v95
	v_mov_b32_e64 v101, 1.0
	v_mul_f32_e32 v112, v101, v95
	v_fma_f32 v113, -v107, v112, v101
	v_fmac_f32_e32 v112, v113, v95
	v_fma_f32 v93, -v107, v112, v101
	v_fma_f32 v93, v93, v95, v112
	v_div_fixup_f32 v107, v93, v107, 1.0
	v_rcp_f32_e32 v95, v106
	s_nop 0
	v_fma_f32 v101, -v106, v95, 1.0
	v_fmac_f32_e32 v95, v101, v95
	v_mov_b32_e64 v101, 1.0
	v_mul_f32_e32 v112, v101, v95
	v_fma_f32 v113, -v106, v112, v101
	v_fmac_f32_e32 v112, v113, v95
	v_fma_f32 v93, -v106, v112, v101
	v_fma_f32 v93, v93, v95, v112
	v_div_fixup_f32 v106, v93, v106, 1.0
	v_mul_f32_e32 v40, v40, v106
	v_mul_f32_e32 v41, v41, v107
	s_nop 0
	v_cvt_pk_bf16_f32 v43, v40, v41
	global_store_dwordx2 v[102:103], v[42:43], off
	global_load_dwordx2 v[40:41], v[104:105], off offset:64
	global_load_dwordx4 v[112:115], v[88:89], off offset:128
	v_mul_f32_e32 v102, v110, v100
	v_mul_f32_e32 v103, v111, v100
	s_waitcnt vmcnt(0) lgkmcnt(0)
; DI size_t kblk(int row, int col, int nrows) { return ((size_t)(col >> 5) * nrows + row) * 32 + (col & 31); }
; DI unsigned pk2(float a, float b) { hwf32x2 f = {a, b}; hwbf16x2 r = __builtin_convertvector(f, hwbf16x2); return __builtin_bit_cast(unsigned, r); }
; DI float sigmoidf_(float z) { return 1.f / (1.f + __expf(-z)); }
; DI float siluf_(float z) { return z / (1.f + __expf(-z)); }
; template <int MX, bool OUT>
; DI void rec_chunk(const Params& p, int l, int b, int h, int dir, int T0, unsigned char* smem, f32x4 (&St)[4], float& nst, float& dtot, int tid, const RecRaw& raw) {
;     ...
; #pragma unroll
;       for (int a = 0; a < 4; ++a) {
;         const int v0 = 16 * a + 4 * g;
;         const uint2 gt = *(const uint2*)(prow + GATE + cb + v0);
;         const float4 gg = *(const float4*)(gvec + v0);
;         float y0 = O[a][0] * rstd * gg.x * siluf_(__uint_as_float(gt.x << 16));
;         float y1 = O[a][1] * rstd * gg.y * siluf_(__uint_as_float(gt.x & 0xffff0000u));
;         float y2 = O[a][2] * rstd * gg.z * siluf_(__uint_as_float(gt.y << 16));
;         float y3 = O[a][3] * rstd * gg.w * siluf_(__uint_as_float(gt.y & 0xffff0000u));
;         if (MX == 1) {
;           const uint2 og = *(const uint2*)(prow + D_OG + h * 64 + v0);
;           y0 *= sigmoidf_(__uint_as_float(og.x << 16)); y1 *= sigmoidf_(__uint_as_float(og.x & 0xffff0000u));
;           y2 *= sigmoidf_(__uint_as_float(og.y << 16)); y3 *= sigmoidf_(__uint_as_float(og.y & 0xffff0000u));
;         }
;         *(uint2*)(MIX + kblk((int)orow, cb + v0, ROWS)) = make_uint2(pk2(y0, y1), pk2(y2, y3));
	v_lshlrev_b32_e32 v93, 16, v40
	v_and_b32_e32 v40, 0xffff0000, v40
	v_mul_f32_e32 v42, 0xbfb8aa3b, v93
	v_mul_f32_e32 v43, 0xbfb8aa3b, v40
	v_exp_f32_e32 v42, v42
	v_exp_f32_e32 v43, v43
	v_mul_f32_e32 v102, v102, v112
	v_mul_f32_e32 v103, v103, v113
	v_add_f32_e32 v42, 1.0, v42
	v_add_f32_e32 v43, 1.0, v43
	s_nop 0
	v_rcp_f32_e32 v101, v43
	s_nop 0
	v_fma_f32 v106, -v43, v101, 1.0
	v_fmac_f32_e32 v101, v106, v101
	v_mul_f32_e32 v107, v40, v101
	v_fma_f32 v110, -v43, v107, v40
	v_fmac_f32_e32 v107, v110, v101
	v_fma_f32 v95, -v43, v107, v40
	v_fma_f32 v95, v95, v101, v107
	v_div_fixup_f32 v43, v95, v43, v40
	v_rcp_f32_e32 v95, v42
	s_nop 0
	v_fma_f32 v101, -v42, v95, 1.0
	v_fmac_f32_e32 v95, v101, v95
	v_mul_f32_e32 v106, v93, v95
	v_fma_f32 v107, -v42, v106, v93
	v_fmac_f32_e32 v106, v107, v95
	v_fma_f32 v40, -v42, v106, v93
	v_fma_f32 v40, v40, v95, v106
	v_div_fixup_f32 v42, v40, v42, v93
	v_lshlrev_b32_e32 v93, 16, v41
	v_and_b32_e32 v95, 0xffff0000, v41
	v_mul_f32_e32 v40, 0xbfb8aa3b, v93
	v_mul_f32_e32 v41, 0xbfb8aa3b, v95
	v_exp_f32_e32 v40, v40
	v_exp_f32_e32 v41, v41
	v_mul_f32_e32 v42, v102, v42
	v_mul_f32_e32 v43, v103, v43
	v_mul_f32_e32 v102, v108, v100
	v_mul_f32_e32 v103, v109, v100
	v_add_f32_e32 v40, 1.0, v40
	v_add_f32_e32 v41, 1.0, v41
	s_nop 0
	v_rcp_f32_e32 v106, v41
	v_mul_f32_e32 v102, v102, v114
	v_mul_f32_e32 v103, v103, v115
	v_fma_f32 v107, -v41, v106, 1.0
	v_fmac_f32_e32 v106, v107, v106
	v_mul_f32_e32 v108, v95, v106
	v_fma_f32 v109, -v41, v108, v95
	v_fmac_f32_e32 v108, v109, v106
	v_fma_f32 v101, -v41, v108, v95
	v_fma_f32 v101, v101, v106, v108
	v_div_fixup_f32 v41, v101, v41, v95
	v_rcp_f32_e32 v101, v40
	s_nop 0
	v_fma_f32 v106, -v40, v101, 1.0
	v_fmac_f32_e32 v101, v106, v101
	v_mul_f32_e32 v107, v93, v101
	v_fma_f32 v108, -v40, v107, v93
	v_fmac_f32_e32 v107, v108, v101
	v_fma_f32 v95, -v40, v107, v93
	v_fma_f32 v95, v95, v101, v107
	v_div_fixup_f32 v40, v95, v40, v93
	v_mul_f32_e32 v40, v102, v40
	v_mul_f32_e32 v41, v103, v41
	global_load_dwordx2 v[102:103], v[74:75], off offset:64
	s_waitcnt vmcnt(0) lgkmcnt(0)
	v_lshlrev_b32_e32 v93, 16, v102
	v_mul_f32_e32 v93, 0xbfb8aa3b, v93
	v_exp_f32_e32 v106, v93
	v_and_b32_e32 v93, 0xffff0000, v102
	v_mul_f32_e32 v93, 0xbfb8aa3b, v93
	v_exp_f32_e32 v107, v93
	s_nop 0
	v_add_f32_e32 v106, 1.0, v106
	v_add_f32_e32 v107, 1.0, v107
	s_nop 0
	v_rcp_f32_e32 v95, v107
	s_nop 0
	v_fma_f32 v101, -v107, v95, 1.0
	v_fmac_f32_e32 v95, v101, v95
	v_mov_b32_e64 v101, 1.0
	v_mul_f32_e32 v102, v101, v95
	v_fma_f32 v108, -v107, v102, v101
	v_fmac_f32_e32 v102, v108, v95
	v_fma_f32 v93, -v107, v102, v101
	v_fma_f32 v93, v93, v95, v102
	v_div_fixup_f32 v107, v93, v107, 1.0
	v_rcp_f32_e32 v95, v106
	s_nop 0
	v_fma_f32 v101, -v106, v95, 1.0
	v_fmac_f32_e32 v95, v101, v95
	v_mov_b32_e64 v101, 1.0
	v_mul_f32_e32 v102, v101, v95
	v_fma_f32 v108, -v106, v102, v101
	v_fmac_f32_e32 v102, v108, v95
	v_fma_f32 v93, -v106, v102, v101
	v_fma_f32 v93, v93, v95, v102
	v_div_fixup_f32 v106, v93, v106, 1.0
	v_lshlrev_b32_e32 v93, 16, v103
	v_mul_f32_e32 v93, 0xbfb8aa3b, v93
	v_exp_f32_e32 v102, v93
	v_and_b32_e32 v93, 0xffff0000, v103
	v_mul_f32_e32 v93, 0xbfb8aa3b, v93
	v_exp_f32_e32 v103, v93
	v_mul_f32_e32 v42, v42, v106
	v_mul_f32_e32 v43, v43, v107
	v_add_f32_e32 v102, 1.0, v102
	v_add_f32_e32 v103, 1.0, v103
	s_nop 0
	v_rcp_f32_e32 v95, v103
	v_cvt_pk_bf16_f32 v42, v42, v43
	v_fma_f32 v101, -v103, v95, 1.0
	v_fmac_f32_e32 v95, v101, v95
	v_mov_b32_e64 v101, 1.0
	v_mul_f32_e32 v106, v101, v95
	v_fma_f32 v107, -v103, v106, v101
	v_fmac_f32_e32 v106, v107, v95
	v_fma_f32 v93, -v103, v106, v101
	v_fma_f32 v93, v93, v95, v106
	v_div_fixup_f32 v103, v93, v103, 1.0
	v_rcp_f32_e32 v95, v102
	s_nop 0
	v_fma_f32 v101, -v102, v95, 1.0
	v_fmac_f32_e32 v95, v101, v95
	v_mov_b32_e64 v101, 1.0
	v_mul_f32_e32 v106, v101, v95
	v_fma_f32 v107, -v102, v106, v101
	v_fmac_f32_e32 v106, v107, v95
	v_fma_f32 v93, -v102, v106, v101
	v_fma_f32 v93, v93, v95, v106
	v_div_fixup_f32 v102, v93, v102, 1.0
	v_mul_f32_e32 v40, v40, v102
	v_mul_f32_e32 v41, v41, v103
	s_nop 0
	v_cvt_pk_bf16_f32 v43, v40, v41
	global_store_dwordx2 v[72:73], v[42:43], off
	global_load_dwordx2 v[40:41], v[104:105], off offset:96
	s_nop 0
	global_load_dwordx2 v[74:75], v[74:75], off offset:96
	s_waitcnt vmcnt(0) lgkmcnt(0)
; DI size_t kblk(int row, int col, int nrows) { return ((size_t)(col >> 5) * nrows + row) * 32 + (col & 31); }
; DI unsigned pk2(float a, float b) { hwf32x2 f = {a, b}; hwbf16x2 r = __builtin_convertvector(f, hwbf16x2); return __builtin_bit_cast(unsigned, r); }
; DI float sigmoidf_(float z) { return 1.f / (1.f + __expf(-z)); }
; DI float siluf_(float z) { return z / (1.f + __expf(-z)); }
; template <int MX, bool OUT>
; DI void rec_chunk(const Params& p, int l, int b, int h, int dir, int T0, unsigned char* smem, f32x4 (&St)[4], float& nst, float& dtot, int tid, const RecRaw& raw) {
;     ...
; #pragma unroll
;       for (int a = 0; a < 4; ++a) {
;         const int v0 = 16 * a + 4 * g;
;         const uint2 gt = *(const uint2*)(prow + GATE + cb + v0);
;         const float4 gg = *(const float4*)(gvec + v0);
;         float y0 = O[a][0] * rstd * gg.x * siluf_(__uint_as_float(gt.x << 16));
;         float y1 = O[a][1] * rstd * gg.y * siluf_(__uint_as_float(gt.x & 0xffff0000u));
;         float y2 = O[a][2] * rstd * gg.z * siluf_(__uint_as_float(gt.y << 16));
;         float y3 = O[a][3] * rstd * gg.w * siluf_(__uint_as_float(gt.y & 0xffff0000u));
;         if (MX == 1) {
;           const uint2 og = *(const uint2*)(prow + D_OG + h * 64 + v0);
;           y0 *= sigmoidf_(__uint_as_float(og.x << 16)); y1 *= sigmoidf_(__uint_as_float(og.x & 0xffff0000u));
;           y2 *= sigmoidf_(__uint_as_float(og.y << 16)); y3 *= sigmoidf_(__uint_as_float(og.y & 0xffff0000u));
;         }
;         *(uint2*)(MIX + kblk((int)orow, cb + v0, ROWS)) = make_uint2(pk2(y0, y1), pk2(y2, y3));
	v_lshlrev_b32_e32 v73, 16, v40
	v_and_b32_e32 v93, 0xffff0000, v40
	v_lshlrev_b32_e32 v40, 16, v41
	v_mul_f32_e32 v42, 0xbfb8aa3b, v40
	v_exp_f32_e32 v42, v42
	s_nop 0
	v_add_f32_e32 v42, 1.0, v42
	v_rcp_f32_e32 v72, v42
	s_nop 0
	v_fma_f32 v95, -v42, v72, 1.0
	v_fmac_f32_e32 v72, v95, v72
	v_mul_f32_e32 v101, v40, v72
	v_fma_f32 v102, -v42, v101, v40
	v_fmac_f32_e32 v101, v102, v72
	v_fma_f32 v43, -v42, v101, v40
	v_fma_f32 v43, v43, v72, v101
	v_and_b32_e32 v95, 0xffff0000, v41
	v_div_fixup_f32 v72, v43, v42, v40
	v_mul_f32_e32 v40, 0xbfb8aa3b, v95
	v_exp_f32_e32 v102, v40
	v_lshlrev_b32_e32 v40, 16, v74
	v_mul_f32_e32 v40, 0xbfb8aa3b, v40
	v_exp_f32_e32 v104, v40
	v_and_b32_e32 v40, 0xffff0000, v74
	v_mul_f32_e32 v40, 0xbfb8aa3b, v40
	v_exp_f32_e32 v105, v40
	global_load_dwordx4 v[40:43], v[88:89], off offset:192
	v_mul_f32_e32 v70, v70, v100
	v_mul_f32_e32 v71, v71, v100
	v_mul_f32_e32 v74, 0xbfb8aa3b, v73
	v_exp_f32_e32 v106, v74
	s_waitcnt vmcnt(0)
	v_mul_f32_e32 v40, v70, v40
	v_mul_f32_e32 v41, v71, v41
	v_mul_f32_e32 v70, 0xbfb8aa3b, v93
	v_exp_f32_e32 v107, v70
	s_nop 0
	v_add_f32_e32 v70, 1.0, v106
	v_add_f32_e32 v71, 1.0, v107
	s_nop 0
	v_rcp_f32_e32 v101, v71
	s_nop 0
	v_fma_f32 v103, -v71, v101, 1.0
	v_fmac_f32_e32 v101, v103, v101
	v_mul_f32_e32 v106, v93, v101
	v_fma_f32 v107, -v71, v106, v93
	v_fmac_f32_e32 v106, v107, v101
	v_fma_f32 v74, -v71, v106, v93
	v_fma_f32 v74, v74, v101, v106
	v_div_fixup_f32 v71, v74, v71, v93
	v_rcp_f32_e32 v93, v70
	s_nop 0
	v_fma_f32 v101, -v70, v93, 1.0
	v_fmac_f32_e32 v93, v101, v93
	v_mul_f32_e32 v103, v73, v93
	v_fma_f32 v106, -v70, v103, v73
	v_fmac_f32_e32 v103, v106, v93
	v_fma_f32 v74, -v70, v103, v73
	v_fma_f32 v74, v74, v93, v103
	v_div_fixup_f32 v70, v74, v70, v73
	v_mul_f32_e32 v40, v40, v70
	v_mul_f32_e32 v41, v41, v71
	v_add_f32_e32 v70, 1.0, v104
	v_add_f32_e32 v71, 1.0, v105
	s_nop 0
	v_rcp_f32_e32 v74, v71
	s_nop 0
	v_fma_f32 v93, -v71, v74, 1.0
	v_fmac_f32_e32 v74, v93, v74
	v_mov_b32_e64 v93, 1.0
	v_mul_f32_e32 v101, v93, v74
	v_fma_f32 v103, -v71, v101, v93
	v_fmac_f32_e32 v101, v103, v74
	v_fma_f32 v73, -v71, v101, v93
	v_fma_f32 v73, v73, v74, v101
	v_div_fixup_f32 v71, v73, v71, 1.0
	v_rcp_f32_e32 v74, v70
	s_nop 0
	v_fma_f32 v93, -v70, v74, 1.0
	v_fmac_f32_e32 v74, v93, v74
	v_mov_b32_e64 v93, 1.0
	v_mul_f32_e32 v101, v93, v74
	v_fma_f32 v103, -v70, v101, v93
	v_fmac_f32_e32 v101, v103, v74
	v_fma_f32 v73, -v70, v101, v93
	v_fma_f32 v73, v73, v74, v101
	v_div_fixup_f32 v70, v73, v70, 1.0
	v_mul_f32_e32 v40, v40, v70
	v_mul_f32_e32 v41, v41, v71
	v_lshlrev_b32_e32 v70, 16, v75
	v_mul_f32_e32 v70, 0xbfb8aa3b, v70
	v_exp_f32_e32 v70, v70
	v_cvt_pk_bf16_f32 v40, v40, v41
	v_add_f32_e32 v70, 1.0, v70
	v_rcp_f32_e32 v73, v70
	s_nop 0
	v_fma_f32 v74, -v70, v73, 1.0
	v_fmac_f32_e32 v73, v74, v73
	v_mov_b32_e64 v74, 1.0
	v_mul_f32_e32 v93, v74, v73
	v_fma_f32 v101, -v70, v93, v74
	v_fmac_f32_e32 v93, v101, v73
	v_fma_f32 v71, -v70, v93, v74
	v_fma_f32 v71, v71, v73, v93
	v_div_fixup_f32 v70, v71, v70, 1.0
	v_and_b32_e32 v71, 0xffff0000, v75
	v_mul_f32_e32 v71, 0xbfb8aa3b, v71
	v_exp_f32_e32 v103, v71
	s_nop 0
	v_add_f32_e32 v74, 1.0, v102
	v_add_f32_e32 v75, 1.0, v103
	s_nop 0
	v_rcp_f32_e32 v73, v75
	s_nop 0
	v_fma_f32 v93, -v75, v73, 1.0
	v_fmac_f32_e32 v73, v93, v73
	v_mov_b32_e64 v93, 1.0
	v_mul_f32_e32 v101, v93, v73
	v_fma_f32 v102, -v75, v101, v93
	v_fmac_f32_e32 v101, v102, v73
	v_fma_f32 v71, -v75, v101, v93
	v_fma_f32 v71, v71, v73, v101
	v_div_fixup_f32 v71, v71, v75, 1.0
	v_rcp_f32_e32 v75, v74
	s_mov_b64 s[0:1], 0
	v_fma_f32 v93, -v74, v75, 1.0
	v_fmac_f32_e32 v75, v93, v75
	v_mul_f32_e32 v101, v95, v75
	v_fma_f32 v102, -v74, v101, v95
	v_fmac_f32_e32 v101, v102, v75
	v_fma_f32 v73, -v74, v101, v95
	v_fma_f32 v73, v73, v75, v101
	v_mul_f32_e32 v68, v68, v100
	v_mul_f32_e32 v69, v69, v100
	v_div_fixup_f32 v73, v73, v74, v95
	v_mul_f32_e32 v42, v68, v42
	v_mul_f32_e32 v43, v69, v43
	v_mov_b32_e32 v95, v161
	v_mul_f32_e32 v42, v42, v72
	v_mul_f32_e32 v43, v43, v73
	v_lshl_add_u64 v[66:67], v[66:67], 0, v[94:95]
	v_mul_f32_e32 v42, v42, v70
	v_mul_f32_e32 v43, v43, v71
	global_store_dword v[66:67], v40, off

; #define MFMA16(a, b, c) __builtin_amdgcn_mfma_f32_16x16x32_bf16((a), (b), (c), 0, 0, 0)
; template <int MX, bool OUT>
; DI void rec_chunk(const Params& p, int l, int b, int h, int dir, int T0, unsigned char* smem, f32x4 (&St)[4], float& nst, float& dtot, int tid, const RecRaw& raw) {
;     ...
;   {
; #pragma unroll
;     for (int c = 0; c < 4; ++c) {
;       const float d = DEC[16 * c + col];
; #pragma unroll
;       for (int j = 0; j < 4; ++j) St[c][j] *= d;
;     }
; #pragma unroll
;     for (int ks = 0; ks < 2; ++ks) {
;       const bf16x8 fa = *(const bf16x8*)(smem + L_VT + swz(16 * w + col, ks * 4 + g));
; #pragma unroll
;       for (int c = 0; c < 4; ++c) {
;         const bf16x8 fb = *(const bf16x8*)(smem + L_KET + swz(16 * c + col, ks * 4 + g));
;         St[c] = MFMA16(fa, fb, St[c]);
;       }
;     }
;     if (tid < 64) {
;       const float d = DEC[tid];
;       dtot *= d;
;       if (MX == 1) {
;         float s = 0.f;
; #pragma unroll
;         for (int cc = 0; cc < 8; ++cc) {
;           const uint4 u = *(const uint4*)(smem + L_KET + swz(tid, cc));
;           s += __uint_as_float(u.x << 16) + __uint_as_float(u.x & 0xffff0000u) + __uint_as_float(u.y << 16) + __uint_as_float(u.y & 0xffff0000u)
;              + __uint_as_float(u.z << 16) + __uint_as_float(u.z & 0xffff0000u) + __uint_as_float(u.w << 16) + __uint_as_float(u.w & 0xffff0000u);
;         }
;         nst = d * nst + s;
;       }
.LBB0_932:
	v_cvt_pk_bf16_f32 v40, v42, v43
	global_store_dword v[66:67], v40, off offset:4
	ds_read2_b32 v[40:41], v153 offset1:16
	s_waitcnt lgkmcnt(0)
	v_mul_f32_e32 v0, v0, v40
	v_mul_f32_e32 v1, v1, v40
	v_mul_f32_e32 v2, v2, v40
	v_mul_f32_e32 v3, v3, v40
	v_mov_b32_e32 v40, v41
	v_mul_f32_e32 v4, v4, v40
	v_mul_f32_e32 v5, v5, v40
	v_mul_f32_e32 v6, v6, v40
	v_mul_f32_e32 v7, v7, v40
	ds_read2_b32 v[40:41], v153 offset0:32 offset1:48
	s_waitcnt lgkmcnt(0)
	v_mul_f32_e32 v8, v8, v40
	v_mul_f32_e32 v9, v9, v40
	v_mul_f32_e32 v10, v10, v40
	v_mul_f32_e32 v11, v11, v40
	v_mov_b32_e32 v40, v41
	v_mul_f32_e32 v12, v12, v40
	v_mul_f32_e32 v13, v13, v40
	v_mul_f32_e32 v14, v14, v40
	v_mul_f32_e32 v15, v15, v40
	ds_read_b128 v[40:43], v242 offset:49152
	ds_read_b128 v[44:47], v240 offset:40960
	s_waitcnt lgkmcnt(0)
	v_mfma_f32_16x16x32_bf16 v[0:3], v[40:43], v[44:47], v[0:3]
	ds_read_b128 v[44:47], v240 offset:43008
	s_waitcnt lgkmcnt(0)
	v_mfma_f32_16x16x32_bf16 v[4:7], v[40:43], v[44:47], v[4:7]
	ds_read_b128 v[44:47], v240 offset:45056
	s_waitcnt lgkmcnt(0)
	v_mfma_f32_16x16x32_bf16 v[8:11], v[40:43], v[44:47], v[8:11]
	ds_read_b128 v[44:47], v240 offset:47104
	s_waitcnt lgkmcnt(0)
	v_mfma_f32_16x16x32_bf16 v[12:15], v[40:43], v[44:47], v[12:15]
	ds_read_b128 v[40:43], v241 offset:49152
	ds_read_b128 v[44:47], v239 offset:40960
	s_waitcnt lgkmcnt(0)
	v_mfma_f32_16x16x32_bf16 v[0:3], v[40:43], v[44:47], v[0:3]
	ds_read_b128 v[44:47], v239 offset:43008
	s_waitcnt lgkmcnt(0)
	v_mfma_f32_16x16x32_bf16 v[4:7], v[40:43], v[44:47], v[4:7]
	ds_read_b128 v[44:47], v239 offset:45056
	s_waitcnt lgkmcnt(0)
	v_mfma_f32_16x16x32_bf16 v[8:11], v[40:43], v[44:47], v[8:11]
	ds_read_b128 v[44:47], v239 offset:47104
	s_waitcnt lgkmcnt(0)
	v_mfma_f32_16x16x32_bf16 v[12:15], v[40:43], v[44:47], v[12:15]
	s_and_saveexec_b64 s[0:1], s[10:11]
	s_cbranch_execz .LBB0_934
	v_add_u32_e32 v41, v156, v157
	ds_read_b32 v40, v155
	ds_read_b128 v[42:45], v41 offset:40960
	ds_read_b128 v[46:49], v217 offset:40960
	s_waitcnt lgkmcnt(0)
	v_lshlrev_b32_e32 v50, 16, v42
	v_lshlrev_b32_e32 v51, 16, v46
	v_and_b32_e32 v53, 0xffff0000, v46
	v_and_b32_e32 v52, 0xffff0000, v42
	v_add_f32_e32 v50, v50, v52
	v_add_f32_e32 v51, v51, v53
	v_lshlrev_b32_e32 v53, 16, v47
	v_lshlrev_b32_e32 v52, 16, v43
	v_add_f32_e32 v50, v50, v52
	v_add_f32_e32 v51, v51, v53
	v_and_b32_e32 v47, 0xffff0000, v47
	v_and_b32_e32 v46, 0xffff0000, v43
	v_add_f32_e32 v42, v50, v46
	v_add_f32_e32 v43, v51, v47
	v_lshlrev_b32_e32 v47, 16, v48
	v_lshlrev_b32_e32 v46, 16, v44
	v_add_f32_e32 v42, v42, v46
	v_add_f32_e32 v43, v43, v47
	v_and_b32_e32 v47, 0xffff0000, v48
	v_and_b32_e32 v46, 0xffff0000, v44
	v_add_f32_e32 v42, v42, v46
	v_add_f32_e32 v43, v43, v47
	v_lshlrev_b32_e32 v47, 16, v49
	v_lshlrev_b32_e32 v46, 16, v45
	v_add_f32_e32 v42, v42, v46
	v_add_f32_e32 v43, v43, v47
	v_and_b32_e32 v47, 0xffff0000, v49
	v_and_b32_e32 v46, 0xffff0000, v45
	v_add_f32_e32 v42, v42, v46
	v_add_f32_e32 v43, v43, v47
	s_nop 0
	v_add_f32_e32 v41, 0, v42
	v_add_f32_e32 v41, v41, v43
	ds_read_b128 v[42:45], v218 offset:40960
	ds_read_b128 v[46:49], v219 offset:40960
	s_waitcnt lgkmcnt(0)
	v_lshlrev_b32_e32 v50, 16, v42
	v_lshlrev_b32_e32 v51, 16, v46
	v_and_b32_e32 v53, 0xffff0000, v46
	v_and_b32_e32 v52, 0xffff0000, v42
	v_add_f32_e32 v50, v50, v52
	v_add_f32_e32 v51, v51, v53
	v_lshlrev_b32_e32 v53, 16, v47
	v_lshlrev_b32_e32 v52, 16, v43
	v_add_f32_e32 v50, v50, v52
	v_add_f32_e32 v51, v51, v53
	v_and_b32_e32 v47, 0xffff0000, v47
	v_and_b32_e32 v46, 0xffff0000, v43
	v_add_f32_e32 v42, v50, v46
	v_add_f32_e32 v43, v51, v47
	v_lshlrev_b32_e32 v47, 16, v48
	v_lshlrev_b32_e32 v46, 16, v44
	v_add_f32_e32 v42, v42, v46
	v_add_f32_e32 v43, v43, v47
	v_and_b32_e32 v47, 0xffff0000, v48
	v_and_b32_e32 v46, 0xffff0000, v44
	v_add_f32_e32 v42, v42, v46
	v_add_f32_e32 v43, v43, v47
	v_lshlrev_b32_e32 v47, 16, v49
	v_lshlrev_b32_e32 v46, 16, v45
	v_add_f32_e32 v42, v42, v46
	v_add_f32_e32 v43, v43, v47
	v_and_b32_e32 v47, 0xffff0000, v49
	v_and_b32_e32 v46, 0xffff0000, v45
	v_add_f32_e32 v42, v42, v46
	v_add_f32_e32 v43, v43, v47
	s_nop 0
	v_add_f32_e32 v41, v41, v42
	v_add_f32_e32 v41, v41, v43
	ds_read_b128 v[42:45], v220 offset:40960
	ds_read_b128 v[46:49], v221 offset:40960
	s_waitcnt lgkmcnt(0)
	v_lshlrev_b32_e32 v50, 16, v42
	v_lshlrev_b32_e32 v51, 16, v46
	v_and_b32_e32 v53, 0xffff0000, v46
	v_and_b32_e32 v52, 0xffff0000, v42
	v_add_f32_e32 v50, v50, v52
	v_add_f32_e32 v51, v51, v53
	v_lshlrev_b32_e32 v53, 16, v47
	v_lshlrev_b32_e32 v52, 16, v43
	v_add_f32_e32 v50, v50, v52
	v_add_f32_e32 v51, v51, v53
	v_and_b32_e32 v47, 0xffff0000, v47
	v_and_b32_e32 v46, 0xffff0000, v43
	v_add_f32_e32 v42, v50, v46
	v_add_f32_e32 v43, v51, v47
	v_lshlrev_b32_e32 v47, 16, v48
	v_lshlrev_b32_e32 v46, 16, v44
	v_add_f32_e32 v42, v42, v46
	v_add_f32_e32 v43, v43, v47
	v_and_b32_e32 v47, 0xffff0000, v48
	v_and_b32_e32 v46, 0xffff0000, v44
	v_add_f32_e32 v42, v42, v46
	v_add_f32_e32 v43, v43, v47
	v_lshlrev_b32_e32 v47, 16, v49
	v_lshlrev_b32_e32 v46, 16, v45
	v_add_f32_e32 v42, v42, v46
	v_add_f32_e32 v43, v43, v47
	v_and_b32_e32 v47, 0xffff0000, v49
	v_and_b32_e32 v46, 0xffff0000, v45
	v_add_f32_e32 v42, v42, v46
	v_add_f32_e32 v43, v43, v47
	s_nop 0
	v_add_f32_e32 v41, v41, v42
	v_add_f32_e32 v41, v41, v43
	ds_read_b128 v[42:45], v222 offset:40960
	ds_read_b128 v[46:49], v223 offset:40960
	s_waitcnt lgkmcnt(0)
	v_lshlrev_b32_e32 v50, 16, v42
	v_lshlrev_b32_e32 v51, 16, v46
	v_and_b32_e32 v53, 0xffff0000, v46
	v_and_b32_e32 v52, 0xffff0000, v42
	v_add_f32_e32 v50, v50, v52
	v_add_f32_e32 v51, v51, v53
	v_lshlrev_b32_e32 v53, 16, v47
	v_lshlrev_b32_e32 v52, 16, v43
	v_add_f32_e32 v50, v50, v52
	v_add_f32_e32 v51, v51, v53
	v_and_b32_e32 v47, 0xffff0000, v47
	v_and_b32_e32 v46, 0xffff0000, v43
	v_add_f32_e32 v42, v50, v46
	v_add_f32_e32 v43, v51, v47
	v_lshlrev_b32_e32 v47, 16, v48
	v_lshlrev_b32_e32 v46, 16, v44
	v_add_f32_e32 v42, v42, v46
	v_add_f32_e32 v43, v43, v47
	v_and_b32_e32 v47, 0xffff0000, v48
	v_and_b32_e32 v46, 0xffff0000, v44
	v_add_f32_e32 v42, v42, v46
	v_add_f32_e32 v43, v43, v47
	v_lshlrev_b32_e32 v47, 16, v49
	v_lshlrev_b32_e32 v46, 16, v45
	v_add_f32_e32 v42, v42, v46
	v_add_f32_e32 v43, v43, v47
	v_and_b32_e32 v47, 0xffff0000, v49
	v_and_b32_e32 v46, 0xffff0000, v45
	v_add_f32_e32 v42, v42, v46
	v_add_f32_e32 v43, v43, v47
	s_nop 0
	v_add_f32_e32 v41, v41, v42
	v_add_f32_e32 v41, v41, v43
	v_fmac_f32_e32 v41, v236, v40
	v_mov_b32_e32 v236, v41

; DI bf16_t f2bf(float f) { return (bf16_t)(pk2(f, 0.f) & 0xffffu); }
; template <int MX>
; DI SumRegs rec_ldsum(const Params& p, int b, int h, int dir, int i, int w, int g, int col, int tid) {
;   const int s2 = dir == 0 ? i : (i == 0 ? 0 : 9 - i);
;   const unsigned char* sp = summ_ptr(p, MX, b, h, dir, s2);
;   const float* E = (const float*)sp + (16 * w + 4 * g) * 64 + col;
;   const float* dd = (const float*)(sp + 16384);
;   SumRegs r;
;   r.d = f32x4{dd[col], dd[16 + col], dd[32 + col], dd[48 + col]};
;   r.E0 = f32x4{E[0], E[64], E[128], E[192]};
;   r.E1 = f32x4{E[16], E[64 + 16], E[128 + 16], E[192 + 16]};
;   r.E2 = f32x4{E[32], E[64 + 32], E[128 + 32], E[192 + 32]};
;   r.E3 = f32x4{E[48], E[64 + 48], E[128 + 48], E[192 + 48]};
;   r.nd = 0.f; r.nn = 0.f;
;   if (MX == 1 && tid < 64) { r.nd = dd[tid]; r.nn = ((const float*)(sp + 16640))[tid]; }
;   return r;
; }
; template <int MX>
; DI void rec_output(const Params& p, int l, int b, int h, int sc, unsigned char* smem) {
;   const int tid = ltid_w(p.wave);
;   const int lane = tid & 63, w = tid >> 6, col = lane & 15, g = lane >> 4;
;   if (MX == 0) rec_setup_lb(p, l, h, smem, tid);
; #pragma unroll 1
;   for (int dir = 0; dir < 2; ++dir) {
;     f32x4 St[4];
; #pragma unroll
;     for (int c = 0; c < 4; ++c) St[c] = f32x4{0.f, 0.f, 0.f, 0.f};
;     float nst = 0.f, dtot = 1.f;
;     const int npre = dir == 0 ? sc : (sc == 0 ? 0 : 1 + (8 - sc));
;     SumRegs cur = rec_ldsum<MX>(p, b, h, dir, 0, w, g, col, tid);
; #pragma unroll 1
;     for (int i = 0; i < npre; ++i) {
;       const SumRegs nxt = rec_ldsum<MX>(p, b, h, dir, (i + 1 < npre) ? i + 1 : i, w, g, col, tid);
;       St[0] = cur.d[0] * St[0] + cur.E0;
;       St[1] = cur.d[1] * St[1] + cur.E1;
;       St[2] = cur.d[2] * St[2] + cur.E2;
;       St[3] = cur.d[3] * St[3] + cur.E3;
;       if (MX == 1 && tid < 64) nst = cur.nd * nst + cur.nn;
;       cur = nxt;
;     }
;     __syncthreads();
; #pragma unroll
;     for (int c = 0; c < 4; ++c)
; #pragma unroll
;       for (int j = 0; j < 4; ++j) {
;         const int v = 16 * w + 4 * g + j, k = 16 * c + col;
;         *(bf16_t*)(smem + L_STT + swz(v, k >> 3) + (k & 7) * 2) = f2bf(St[c][j]);
;       }
;     if (MX == 1 && tid < 64) ((float*)(smem + L_N0))[tid] = nst;
;     RecRaw raw = rec_load<MX>(p, b, h, dir, sc * 256 + (dir == 0 ? 0 : 3) * 64, tid);
.LBB0_947:
	s_add_i32 s34, s26, 1
	s_cmp_lt_u32 s34, s20
	s_cselect_b32 s35, s34, s26
	s_sub_i32 s26, 9, s35
	s_cmp_lg_u32 s35, 0
	s_cselect_b32 s50, s26, 0
	s_and_b64 s[26:27], s[8:9], exec
	s_cselect_b32 s26, s35, s50
	s_add_i32 s26, s26, s21
	s_mul_hi_i32 s27, s26, 0x4200
	s_mulk_i32 s26, 0x4200
	s_add_u32 s26, s1, s26
	s_addc_u32 s27, s82, s27
	v_lshl_add_u64 v[42:43], s[26:27], 0, v[92:93]
	v_lshl_add_u64 v[40:41], v[76:77], 2, s[26:27]
	v_lshl_add_u64 v[44:45], v[42:43], 0, s[52:53]
	v_add_co_u32_e32 v42, vcc, s39, v42
	v_lshl_add_u64 v[40:41], v[40:41], 0, v[92:93]
	s_nop 0
	v_addc_co_u32_e32 v43, vcc, 0, v43, vcc
	global_load_dword v23, v[42:43], off
	global_load_dword v29, v[44:45], off offset:64
	global_load_dword v31, v[44:45], off offset:128
	global_load_dword v33, v[44:45], off offset:192
	s_nop 0
	global_load_dword v42, v[40:41], off offset:320
	global_load_dword v43, v[40:41], off offset:384
	global_load_dword v44, v[40:41], off offset:448
	global_load_dword v45, v[40:41], off offset:192
	global_load_dword v46, v[40:41], off offset:832
	global_load_dword v47, v[40:41], off offset:896
	global_load_dword v48, v[40:41], off offset:960
	global_load_dword v49, v[40:41], off offset:704
	global_load_dword v50, v[40:41], off offset:128
	global_load_dword v51, v[40:41], off offset:640
	global_load_dword v52, v[40:41], off offset:64
	global_load_dword v53, v[40:41], off offset:576
	global_load_dword v54, v[40:41], off
	global_load_dword v55, v[40:41], off offset:256
	global_load_dword v56, v[40:41], off offset:512
	s_nop 0
	global_load_dword v40, v[40:41], off offset:768
	s_mov_b32 s26, s34
	s_cmp_eq_u32 s20, s34
	s_waitcnt vmcnt(0) lgkmcnt(0)
	v_fma_f32 v14, v14, v22, v18
	v_fma_f32 v15, v15, v22, v19
	v_fma_f32 v10, v10, v28, v24
	v_fma_f32 v11, v11, v28, v25
	v_fma_f32 v2, v2, v30, v38
	v_fma_f32 v3, v3, v30, v39
	v_fma_f32 v0, v0, v30, v36
	v_fma_f32 v1, v1, v30, v37
	v_fma_f32 v6, v6, v32, v34
	v_fma_f32 v7, v7, v32, v35
	v_fma_f32 v4, v4, v32, v26
	v_fma_f32 v5, v5, v32, v27
	v_fma_f32 v8, v8, v28, v20
	v_fma_f32 v9, v9, v28, v21
	v_fma_f32 v12, v12, v22, v16
	v_fma_f32 v13, v13, v22, v17
	v_mov_b32_e32 v30, v23
	v_mov_b32_e32 v32, v29
	v_mov_b32_e32 v28, v31
	v_mov_b32_e32 v22, v33
	v_mov_b32_e32 v16, v45
	v_mov_b32_e32 v17, v44
	v_mov_b32_e32 v18, v49
	v_mov_b32_e32 v19, v48
	v_mov_b32_e32 v20, v50
	v_mov_b32_e32 v21, v43
	v_mov_b32_e32 v24, v51
	v_mov_b32_e32 v25, v47
	v_mov_b32_e32 v26, v52
	v_mov_b32_e32 v27, v42
	v_mov_b32_e32 v34, v53
	v_mov_b32_e32 v35, v46
	v_mov_b32_e32 v36, v54
	v_mov_b32_e32 v37, v55
	v_mov_b32_e32 v38, v56
	v_mov_b32_e32 v39, v40
	s_cbranch_scc0 .LBB0_947
	v_cvt_pk_bf16_f32 v16, v0, s0
	s_barrier
	ds_write_b16 v143, v16 offset:57344
	v_cvt_pk_bf16_f32 v16, v1, s0
	ds_write_b16 v143, v16 offset:57472
	v_cvt_pk_bf16_f32 v16, v2, s0
	ds_write_b16 v144, v16 offset:57344
	v_cvt_pk_bf16_f32 v16, v3, s0
	ds_write_b16 v145, v16 offset:57344
	v_cvt_pk_bf16_f32 v16, v4, s0
	ds_write_b16 v146, v16 offset:57344
	v_cvt_pk_bf16_f32 v16, v5, s0
	ds_write_b16 v146, v16 offset:57472
	v_cvt_pk_bf16_f32 v16, v6, s0
	ds_write_b16 v147, v16 offset:57344
	v_cvt_pk_bf16_f32 v16, v7, s0
	ds_write_b16 v148, v16 offset:57344
	v_cvt_pk_bf16_f32 v16, v8, s0
	ds_write_b16 v149, v16 offset:57344
	v_cvt_pk_bf16_f32 v16, v9, s0
	ds_write_b16 v149, v16 offset:57472
	v_cvt_pk_bf16_f32 v16, v10, s0
	ds_write_b16 v150, v16 offset:57344
	v_cvt_pk_bf16_f32 v16, v11, s0
	ds_write_b16 v151, v16 offset:57344
	v_cvt_pk_bf16_f32 v16, v12, s0
	ds_write_b16 v152, v16 offset:57344
	v_cvt_pk_bf16_f32 v16, v13, s0
	s_and_b64 s[20:21], s[8:9], exec
	ds_write_b16 v152, v16 offset:57472
	v_cvt_pk_bf16_f32 v16, v14, s0
	s_cselect_b32 s20, 0, 0xc0
	ds_write_b16 v153, v16 offset:57344
	v_cvt_pk_bf16_f32 v16, v15, s0
	s_or_b32 s20, s20, s81
	ds_write_b16 v154, v16 offset:57344
	v_add_u32_e32 v18, s20, v78
	v_mov_b64_e32 v[16:17], s[4:5]
	v_mad_i64_i32 v[16:17], s[20:21], v18, s33, v[16:17]
	s_and_b64 s[20:21], s[8:9], exec
	s_movk_i32 s20, 0x400
	s_cselect_b32 s20, s20, 0x500
	v_or_b32_e32 v18, s20, v142
	v_lshlrev_b32_e32 v160, 1, v18
	s_lshl_b32 s20, s0, 1
	s_mov_b32 s21, s3
	v_lshl_add_u64 v[20:21], v[16:17], 0, v[160:161]
	v_lshl_add_u64 v[16:17], v[16:17], 0, s[20:21]
	v_lshlrev_b32_e32 v98, 1, v80
	v_mov_b32_e32 v99, v161
	v_lshl_add_u64 v[16:17], v[16:17], 0, v[98:99]
	global_load_dwordx4 v[60:63], v[20:21], off
	global_load_dwordx4 v[56:59], v[20:21], off offset:16
	global_load_dwordx4 v[40:43], v[16:17], off offset:1536
	global_load_dwordx4 v[44:47], v[16:17], off offset:1552
	global_load_dwordx4 v[52:55], v[16:17], off offset:3072
	global_load_dwordx4 v[48:51], v[16:17], off offset:3088
	v_readlane_b32 s26, v253, 56
	v_readlane_b32 s27, v253, 57
	s_mov_b32 s83, 1
	s_mov_b32 s84, 2
	v_cndmask_b32_e64 v16, 0, 1, s[26:27]
	v_readlane_b32 s26, v253, 54
	v_readlane_b32 s27, v253, 55
	v_lshlrev_b32_e32 v160, 1, v18
	s_nop 0
	v_cndmask_b32_e64 v17, 0, 1, s[26:27]
	v_cndmask_b32_e64 v16, v16, v17, s[8:9]
	v_readlane_b32 s26, v254, 31
	v_and_b32_e32 v16, 1, v16
	v_readlane_b32 s27, v254, 32
	v_cmp_eq_u32_e64 s[50:51], 1, v16
	s_nop 0
	v_cndmask_b32_e64 v16, 0, 1, s[26:27]
	v_readlane_b32 s26, v253, 40
	v_readlane_b32 s27, v253, 41
	s_nop 1
	v_cndmask_b32_e64 v19, 0, 1, s[26:27]
	v_cndmask_b32_e64 v20, v16, v19, s[8:9]
	v_readlane_b32 s26, v254, 33
	v_and_b32_e32 v20, 1, v20
	v_readlane_b32 s27, v254, 34
	v_cmp_eq_u32_e64 s[52:53], 1, v20
	s_nop 0
	v_cndmask_b32_e64 v20, 0, 1, s[26:27]
	v_readlane_b32 s26, v254, 35
	v_readlane_b32 s27, v254, 36
	s_nop 1
	v_cndmask_b32_e64 v21, 0, 1, s[26:27]
; DI bf16_t f2bf(float f) { return (bf16_t)(pk2(f, 0.f) & 0xffffu); }
; #define MFMA16(a, b, c) __builtin_amdgcn_mfma_f32_16x16x32_bf16((a), (b), (c), 0, 0, 0)
; template <int MX, bool OUT>
; DI void rec_chunk(const Params& p, int l, int b, int h, int dir, int T0, unsigned char* smem, f32x4 (&St)[4], float& nst, float& dtot, int tid, const RecRaw& raw) {
;     ...
;   {
; #pragma unroll
;     for (int c = 0; c < 4; ++c) {
;       const float d = DEC[16 * c + col];
; #pragma unroll
;       for (int j = 0; j < 4; ++j) St[c][j] *= d;
;     }
; #pragma unroll
;     for (int ks = 0; ks < 2; ++ks) {
;       const bf16x8 fa = *(const bf16x8*)(smem + L_VT + swz(16 * w + col, ks * 4 + g));
; #pragma unroll
;       for (int c = 0; c < 4; ++c) {
;         const bf16x8 fb = *(const bf16x8*)(smem + L_KET + swz(16 * c + col, ks * 4 + g));
;         St[c] = MFMA16(fa, fb, St[c]);
;       }
;     }
;     if (tid < 64) {
;       const float d = DEC[tid];
;       dtot *= d;
;       if (MX == 1) {
;         float s = 0.f;
; #pragma unroll
;         for (int cc = 0; cc < 8; ++cc) {
;           const uint4 u = *(const uint4*)(smem + L_KET + swz(tid, cc));
;           s += __uint_as_float(u.x << 16) + __uint_as_float(u.x & 0xffff0000u) + __uint_as_float(u.y << 16) + __uint_as_float(u.y & 0xffff0000u)
;              + __uint_as_float(u.z << 16) + __uint_as_float(u.z & 0xffff0000u) + __uint_as_float(u.w << 16) + __uint_as_float(u.w & 0xffff0000u);
;         }
;         nst = d * nst + s;
;       }
;     }
;     __syncthreads();
;     if (OUT) {
; #pragma unroll
;       for (int c = 0; c < 4; ++c)
; #pragma unroll
;         for (int j = 0; j < 4; ++j) {
;           const int v = 16 * w + 4 * g + j, k = 16 * c + col;
;           *(bf16_t*)(smem + L_STT + swz(v, k >> 3) + (k & 7) * 2) = f2bf(St[c][j]);
;         }
;       if (MX == 1 && tid < 64) N0[tid] = nst;
	v_cndmask_b32_e64 v22, v21, v20, s[8:9]
	v_readlane_b32 s26, v254, 37
	v_and_b32_e32 v22, 1, v22
	v_readlane_b32 s27, v254, 38
	v_cmp_eq_u32_e64 s[54:55], 1, v22
	s_nop 0
	v_cndmask_b32_e64 v22, 0, 1, s[26:27]
	v_readlane_b32 s26, v254, 39
	v_readlane_b32 s27, v254, 40
	s_nop 1
	v_cndmask_b32_e64 v23, 0, 1, s[26:27]
	s_and_b64 s[26:27], s[8:9], exec
	s_movk_i32 s26, 0x1f00
	s_cselect_b32 s26, s26, 0x2000
	v_or_b32_e32 v93, s26, v79
	s_cselect_b32 s26, 0x3f00, 0
	v_cndmask_b32_e64 v22, v23, v22, s[8:9]
	v_or_b32_e32 v199, s26, v79
	v_readlane_b32 s26, v254, 41
	v_and_b32_e32 v22, 1, v22
	v_readlane_b32 s27, v254, 42
	v_cmp_eq_u32_e64 s[56:57], 1, v22
	s_nop 0
	v_cndmask_b32_e64 v22, 0, 1, s[26:27]
	v_cndmask_b32_e64 v16, v16, v22, s[8:9]
	v_and_b32_e32 v16, 1, v16
	v_cmp_eq_u32_e64 s[58:59], 1, v16
	v_cndmask_b32_e64 v16, v21, v17, s[8:9]
	v_and_b32_e32 v16, 1, v16
	v_cmp_eq_u32_e64 s[60:61], 1, v16
	v_cndmask_b32_e64 v16, v23, v19, s[8:9]
	v_and_b32_e32 v16, 1, v16
	v_cmp_eq_u32_e64 s[62:63], 1, v16
	v_cndmask_b32_e64 v16, 0, 1, s[22:23]
	v_cndmask_b32_e64 v17, v16, v20, s[8:9]
	v_and_b32_e32 v17, 1, v17
	v_cmp_eq_u32_e64 s[64:65], 1, v17
	v_cndmask_b32_e64 v17, v21, v22, s[8:9]
	v_cndmask_b32_e64 v16, v16, v19, s[8:9]
	v_and_b32_e32 v17, 1, v17
	v_and_b32_e32 v16, 1, v16
	v_cmp_eq_u32_e64 s[66:67], 1, v17
	v_cmp_eq_u32_e64 s[68:69], 1, v16
	v_cndmask_b32_e64 v16, 0, 1, s[86:87]
	v_cndmask_b32_e64 v17, 0, 1, s[88:89]
	v_cndmask_b32_e64 v16, v17, v16, s[8:9]
	v_and_b32_e32 v16, 1, v16
	v_cmp_eq_u32_e64 s[70:71], 1, v16
	v_cndmask_b32_e64 v16, 0, 1, s[90:91]
	v_cndmask_b32_e64 v17, 0, 1, s[92:93]
	v_cndmask_b32_e64 v16, v17, v16, s[8:9]
	v_and_b32_e32 v16, 1, v16
	v_cmp_eq_u32_e64 s[72:73], 1, v16
	v_cndmask_b32_e64 v16, 0, 1, s[94:95]
	v_cndmask_b32_e64 v17, 0, 1, s[96:97]
	v_cndmask_b32_e64 v16, v17, v16, s[8:9]
	v_and_b32_e32 v16, 1, v16
	v_cmp_eq_u32_e64 s[74:75], 1, v16
	v_cndmask_b32_e64 v16, 0, 1, s[40:41]
	v_cndmask_b32_e64 v17, 0, 1, s[12:13]
	v_cndmask_b32_e64 v16, v17, v16, s[8:9]
	v_and_b32_e32 v16, 1, v16
	v_cmp_eq_u32_e64 s[76:77], 1, v16
	s_branch .LBB0_950
.LBB0_949:
	v_cvt_pk_bf16_f32 v40, v56, v57
	global_store_dword v[58:59], v40, off offset:4
	ds_read2_b32 v[40:41], v141 offset1:16
	s_add_i32 s84, s84, -1
	s_add_i32 s83, s83, 1
	s_cmp_eq_u32 s84, -2
	s_waitcnt vmcnt(0)
	v_mov_b64_e32 v[60:61], v[20:21]
	s_waitcnt lgkmcnt(0)
	v_mul_f32_e32 v0, v0, v40
	v_mul_f32_e32 v1, v1, v40
	v_mul_f32_e32 v2, v2, v40
	v_mul_f32_e32 v3, v3, v40
	v_mov_b32_e32 v40, v41
	v_mul_f32_e32 v4, v4, v40
	v_mul_f32_e32 v5, v5, v40
	v_mul_f32_e32 v6, v6, v40
	v_mul_f32_e32 v7, v7, v40
	ds_read2_b32 v[40:41], v141 offset0:32 offset1:48
	v_mov_b64_e32 v[62:63], v[22:23]
	v_mov_b64_e32 v[56:57], v[16:17]
	v_mov_b64_e32 v[58:59], v[18:19]
	v_mov_b64_e32 v[52:53], v[28:29]
	s_waitcnt lgkmcnt(0)
	v_mul_f32_e32 v8, v8, v40
	v_mul_f32_e32 v9, v9, v40
	v_mul_f32_e32 v10, v10, v40
	v_mul_f32_e32 v11, v11, v40
	v_mov_b32_e32 v40, v41
	v_mul_f32_e32 v12, v12, v40
	v_mul_f32_e32 v13, v13, v40
	v_mul_f32_e32 v14, v14, v40
	v_mul_f32_e32 v15, v15, v40
	ds_read_b128 v[40:43], v203 offset:49152
	ds_read_b128 v[44:47], v201 offset:40960
	s_waitcnt lgkmcnt(0)
	v_mfma_f32_16x16x32_bf16 v[0:3], v[40:43], v[44:47], v[0:3]
	ds_read_b128 v[44:47], v201 offset:43008
	v_mov_b64_e32 v[54:55], v[30:31]
	v_mov_b64_e32 v[48:49], v[24:25]
	s_waitcnt lgkmcnt(0)
	v_mfma_f32_16x16x32_bf16 v[4:7], v[40:43], v[44:47], v[4:7]
	ds_read_b128 v[44:47], v201 offset:45056
	v_mov_b64_e32 v[50:51], v[26:27]
	s_waitcnt lgkmcnt(0)
	v_mfma_f32_16x16x32_bf16 v[8:11], v[40:43], v[44:47], v[8:11]
	ds_read_b128 v[44:47], v201 offset:47104
	s_waitcnt lgkmcnt(0)
	v_mfma_f32_16x16x32_bf16 v[12:15], v[40:43], v[44:47], v[12:15]
	ds_read_b128 v[40:43], v202 offset:49152
	ds_read_b128 v[44:47], v200 offset:40960
	s_waitcnt lgkmcnt(0)
	v_mfma_f32_16x16x32_bf16 v[0:3], v[40:43], v[44:47], v[0:3]
	ds_read_b128 v[44:47], v200 offset:43008
	s_waitcnt lgkmcnt(0)
	v_mfma_f32_16x16x32_bf16 v[4:7], v[40:43], v[44:47], v[4:7]
	ds_read_b128 v[44:47], v200 offset:45056
	s_waitcnt lgkmcnt(0)
	v_mfma_f32_16x16x32_bf16 v[8:11], v[40:43], v[44:47], v[8:11]
	ds_read_b128 v[44:47], v200 offset:47104
	s_waitcnt lgkmcnt(0)
	s_barrier
	v_mfma_f32_16x16x32_bf16 v[12:15], v[40:43], v[44:47], v[12:15]
	v_cvt_pk_bf16_f32 v40, v0, s0
	ds_write_b16 v159, v40 offset:57344
	v_cvt_pk_bf16_f32 v40, v1, s0
	ds_write_b16 v159, v40 offset:57472
	v_cvt_pk_bf16_f32 v40, v2, s0
	ds_write_b16 v164, v40 offset:57344
	v_cvt_pk_bf16_f32 v40, v3, s0
	ds_write_b16 v165, v40 offset:57344
	v_cvt_pk_bf16_f32 v40, v4, s0
	ds_write_b16 v166, v40 offset:57344
	v_cvt_pk_bf16_f32 v40, v5, s0
	ds_write_b16 v166, v40 offset:57472
	v_cvt_pk_bf16_f32 v40, v6, s0
	ds_write_b16 v167, v40 offset:57344
	v_cvt_pk_bf16_f32 v40, v7, s0
	ds_write_b16 v168, v40 offset:57344
	v_cvt_pk_bf16_f32 v40, v8, s0
	ds_write_b16 v169, v40 offset:57344
	v_cvt_pk_bf16_f32 v40, v9, s0
	ds_write_b16 v169, v40 offset:57472
	v_cvt_pk_bf16_f32 v40, v10, s0
	ds_write_b16 v170, v40 offset:57344
	v_cvt_pk_bf16_f32 v40, v11, s0
	ds_write_b16 v171, v40 offset:57344
	v_cvt_pk_bf16_f32 v40, v12, s0
	ds_write_b16 v196, v40 offset:57344
	v_cvt_pk_bf16_f32 v40, v13, s0
	ds_write_b16 v196, v40 offset:57472
	v_cvt_pk_bf16_f32 v40, v14, s0
	ds_write_b16 v197, v40 offset:57344
	v_cvt_pk_bf16_f32 v40, v15, s0
	ds_write_b16 v198, v40 offset:57344
	v_mov_b64_e32 v[40:41], v[36:37]
	v_mov_b64_e32 v[42:43], v[38:39]
	v_mov_b64_e32 v[44:45], v[32:33]
	v_mov_b64_e32 v[46:47], v[34:35]
	s_cbranch_scc1 .LBB0_945

; DI size_t kblk(int row, int col, int nrows) { return ((size_t)(col >> 5) * nrows + row) * 32 + (col & 31); }
; DI float siluf_(float z) { return z / (1.f + __expf(-z)); }
; template <int MX, bool OUT>
; DI void rec_chunk(const Params& p, int l, int b, int h, int dir, int T0, unsigned char* smem, f32x4 (&St)[4], float& nst, float& dtot, int tid, const RecRaw& raw) {
;     ...
; #pragma unroll
;     for (int ks = 0; ks < 2; ++ks) {
;       const bf16x8 fb = *(const bf16x8*)(smem + L_QS + swz(t, ks * 4 + g));
; #pragma unroll
;       for (int a = 0; a < 4; ++a) {
;         const bf16x8 fa = *(const bf16x8*)(smem + L_STT + swz(16 * a + col, ks * 4 + g));
;         O[a] = MFMA16(fa, fb, O[a]);
;       }
;     }
;     if (MX == 1) {
;       const float inv = 1.f / fmaxf(fabsf(den), 1.f);
; #pragma unroll
;       for (int a = 0; a < 4; ++a)
; #pragma unroll
;         for (int j = 0; j < 4; ++j) O[a][j] *= inv;
;     }
;     if (dir == 0) {
; #pragma unroll
;       for (int a = 0; a < 4; ++a) *(uint2*)(MIX + kblk((int)orow, cb + 16 * a + 4 * g, ROWS)) = make_uint2(pk2(O[a][0], O[a][1]), pk2(O[a][2], O[a][3]));
;     } else {
;       float ss = 0.f;
; #pragma unroll
;       for (int a = 0; a < 4; ++a) {
;         const uint2 u = *(const uint2*)(MIX + kblk((int)orow, cb + 16 * a + 4 * g, ROWS));
;         O[a][0] += __uint_as_float(u.x << 16); O[a][1] += __uint_as_float(u.x & 0xffff0000u);
;         O[a][2] += __uint_as_float(u.y << 16); O[a][3] += __uint_as_float(u.y & 0xffff0000u);
; #pragma unroll
;         for (int j = 0; j < 4; ++j) ss += O[a][j] * O[a][j];
;       }
;       ss += __shfl_xor(ss, 16);
;       ss += __shfl_xor(ss, 32);
;       const float rstd = rsqrtf(ss * (1.f / 64.f) + EPS);
;       const float* gvec = (MX ? p.ml_g : p.hg_g) + l * 64;
; #pragma unroll
;       for (int a = 0; a < 4; ++a) {
;         const int v0 = 16 * a + 4 * g;
;         const uint2 gt = *(const uint2*)(prow + GATE + cb + v0);
;         const float4 gg = *(const float4*)(gvec + v0);
;         float y0 = O[a][0] * rstd * gg.x * siluf_(__uint_as_float(gt.x << 16));
;         float y1 = O[a][1] * rstd * gg.y * siluf_(__uint_as_float(gt.x & 0xffff0000u));
;         float y2 = O[a][2] * rstd * gg.z * siluf_(__uint_as_float(gt.y << 16));
;         float y3 = O[a][3] * rstd * gg.w * siluf_(__uint_as_float(gt.y & 0xffff0000u));
.LBB0_1014:
	s_or_b64 exec, exec, s[26:27]
	s_add_i32 s26, s83, -1
	v_mov_b32_e32 v40, s26
	v_cndmask_b32_e64 v40, v95, v40, s[8:9]
	v_lshlrev_b32_e32 v40, 6, v40
	v_add_u32_e32 v40, s81, v40
	v_mov_b32_e32 v41, v161
	v_lshl_add_u64 v[68:69], v[40:41], 0, v[84:85]
	ds_read_b128 v[40:43], v203 offset:32768
	ds_read_b128 v[44:47], v201 offset:57344
	ds_read_b128 v[48:51], v201 offset:59392
	ds_read_b128 v[52:55], v201 offset:61440
	s_waitcnt lgkmcnt(0)
	v_mfma_f32_16x16x32_bf16 v[44:47], v[44:47], v[40:43], v[56:59]
	s_mov_b64 s[26:27], -1
	s_nop 1
	ds_read_b128 v[56:59], v201 offset:63488
	s_and_b64 vcc, exec, s[78:79]
	v_mfma_f32_16x16x32_bf16 v[48:51], v[48:51], v[40:43], v[60:63]
	v_ashrrev_i32_e32 v204, 31, v68
	v_mfma_f32_16x16x32_bf16 v[52:55], v[52:55], v[40:43], v[64:67]
	s_waitcnt lgkmcnt(0)
	v_mfma_f32_16x16x32_bf16 v[56:59], v[56:59], v[40:43], v[72:75]
	ds_read_b128 v[60:63], v202 offset:32768
	ds_read_b128 v[40:43], v200 offset:57344
	s_waitcnt lgkmcnt(0)
	v_mfma_f32_16x16x32_bf16 v[40:43], v[40:43], v[60:63], v[44:47]
	s_nop 2
	ds_read_b128 v[44:47], v200 offset:59392
	s_waitcnt lgkmcnt(0)
	v_mfma_f32_16x16x32_bf16 v[48:51], v[44:47], v[60:63], v[48:51]
	ds_read_b128 v[44:47], v200 offset:61440
	s_waitcnt lgkmcnt(0)
	v_mfma_f32_16x16x32_bf16 v[52:55], v[44:47], v[60:63], v[52:55]
	ds_read_b128 v[44:47], v200 offset:63488
	s_waitcnt lgkmcnt(0)
	v_mfma_f32_16x16x32_bf16 v[44:47], v[44:47], v[60:63], v[56:59]
	s_cbranch_vccnz .LBB0_1016
	s_nop 1
	v_mov_b64_e32 v[56:57], s[14:15]
	v_mad_u64_u32 v[56:57], s[26:27], v68, s33, v[56:57]
	v_mad_i32_i24 v57, v69, s33, v57
	v_mov_b32_e32 v69, v204
	v_lshl_add_u64 v[60:61], v[68:69], 0, s[30:31]
	v_lshlrev_b64 v[60:61], 6, v[60:61]
	v_lshl_add_u64 v[70:71], v[90:91], 0, v[60:61]
	global_load_dwordx2 v[60:61], v[70:71], off
	v_lshl_add_u64 v[58:59], v[68:69], 0, s[28:29]
	v_lshlrev_b64 v[58:59], 6, v[58:59]
	v_mov_b32_e32 v95, v161
	v_lshl_add_u64 v[100:101], v[86:87], 0, v[58:59]
	global_load_dwordx2 v[58:59], v[100:101], off
	s_mov_b64 s[26:27], 0x41c7a20
	v_lshl_add_u64 v[56:57], v[56:57], 0, s[26:27]
	v_lshl_add_u64 v[72:73], v[56:57], 0, s[2:3]
	v_lshl_add_u64 v[56:57], v[56:57], 0, v[94:95]
	v_lshl_add_u64 v[56:57], v[56:57], 0, s[2:3]
	v_cmp_lt_i32_e32 vcc, v183, v178
	v_lshl_add_u64 v[72:73], v[72:73], 0, v[94:95]
	global_load_dwordx2 v[56:57], v[56:57], off
	s_waitcnt vmcnt(0) lgkmcnt(0)
	v_lshlrev_b32_e32 v74, 16, v60
	v_and_b32_e32 v75, 0xffff0000, v60
	v_lshlrev_b32_e32 v102, 16, v61
	v_and_b32_e32 v103, 0xffff0000, v61
	v_lshl_add_u64 v[60:61], v[68:69], 0, s[42:43]
	v_lshlrev_b64 v[60:61], 6, v[60:61]
	v_lshl_add_u64 v[60:61], s[6:7], 0, v[60:61]
	v_lshl_add_u64 v[66:67], v[60:61], 0, v[94:95]
	global_load_dwordx2 v[62:63], v[66:67], off
	v_cndmask_b32_e32 v69, v177, v183, vcc
	v_cmp_lt_i32_e32 vcc, v184, v178
	v_lshlrev_b32_e32 v97, 2, v69
	v_lshlrev_b32_e32 v116, 16, v58
	v_cndmask_b32_e32 v69, v177, v184, vcc
	v_and_b32_e32 v117, 0xffff0000, v58
	v_lshlrev_b32_e32 v58, 16, v59
	v_and_b32_e32 v59, 0xffff0000, v59
	v_add_f32_e32 v112, v42, v58
	v_add_f32_e32 v113, v43, v59
	v_add_f32_e32 v116, v40, v116
	v_add_f32_e32 v117, v41, v117
	v_mul_f32_e32 v114, v112, v112
	v_mul_f32_e32 v115, v113, v113
	v_mul_f32_e32 v120, v116, v116
	v_mul_f32_e32 v121, v117, v117
	v_lshlrev_b32_e32 v69, 2, v69
	v_add_f32_e32 v95, v120, v121
	v_add_f32_e32 v95, v95, v114
	v_add_f32_e32 v95, v115, v95
	v_lshlrev_b32_e32 v205, 16, v56
	v_and_b32_e32 v206, 0xffff0000, v56
	v_lshlrev_b32_e32 v208, 16, v57
	v_and_b32_e32 v209, 0xffff0000, v57
	global_load_dwordx4 v[56:59], v[88:89], off
	v_mul_f32_e32 v118, 0xbfb8aa3b, v205
	v_mul_f32_e32 v119, 0xbfb8aa3b, v206
	v_exp_f32_e32 v118, v118
	v_exp_f32_e32 v119, v119
	s_waitcnt vmcnt(0) lgkmcnt(0)
	v_lshlrev_b32_e32 v108, 16, v62
	v_and_b32_e32 v109, 0xffff0000, v62
	v_lshlrev_b32_e32 v110, 16, v63
	v_and_b32_e32 v111, 0xffff0000, v63
	global_load_dwordx2 v[62:63], v[66:67], off offset:32
	v_add_f32_e32 v118, 1.0, v118
	v_add_f32_e32 v119, 1.0, v119
	v_add_f32_e32 v108, v52, v108
	v_add_f32_e32 v109, v53, v109
	v_rcp_f32_e32 v210, v119
	v_mul_f32_e32 v214, v108, v108
	v_mul_f32_e32 v215, v109, v109
	v_fma_f32 v211, -v119, v210, 1.0
	v_fmac_f32_e32 v210, v211, v210
	v_mul_f32_e32 v212, v206, v210
	v_fma_f32 v213, -v119, v212, v206
	v_fmac_f32_e32 v212, v213, v210
	v_fma_f32 v207, -v119, v212, v206
	v_fma_f32 v207, v207, v210, v212
	v_div_fixup_f32 v119, v207, v119, v206
	v_rcp_f32_e32 v207, v118
	s_waitcnt vmcnt(0) lgkmcnt(0)
	v_lshlrev_b32_e32 v64, 16, v62
	v_fma_f32 v210, -v118, v207, 1.0
	v_fmac_f32_e32 v207, v210, v207
	v_mul_f32_e32 v211, v205, v207
	v_fma_f32 v212, -v118, v211, v205
	v_fmac_f32_e32 v211, v212, v207
	v_fma_f32 v206, -v118, v211, v205
	v_fma_f32 v206, v206, v207, v211
	v_div_fixup_f32 v118, v206, v118, v205
	v_mul_f32_e32 v205, 0xbfb8aa3b, v208
	v_exp_f32_e32 v206, v205
	v_mul_f32_e32 v205, 0xbfb8aa3b, v209
	v_exp_f32_e32 v207, v205
	v_and_b32_e32 v65, 0xffff0000, v62
	v_add_f32_e32 v64, v44, v64
	v_add_f32_e32 v65, v45, v65
	v_lshlrev_b32_e32 v62, 16, v63
	v_add_f32_e32 v206, 1.0, v206
	v_add_f32_e32 v207, 1.0, v207
	v_and_b32_e32 v63, 0xffff0000, v63
	v_rcp_f32_e32 v210, v207
	v_mul_f32_e32 v104, v64, v64
	v_mul_f32_e32 v105, v65, v65
	v_add_f32_e32 v62, v46, v62
	v_add_f32_e32 v63, v47, v63
	v_fma_f32 v211, -v207, v210, 1.0
	v_fmac_f32_e32 v210, v211, v210
	v_mul_f32_e32 v212, v209, v210
	v_fma_f32 v213, -v207, v212, v209
	v_fmac_f32_e32 v212, v213, v210
	v_fma_f32 v205, -v207, v212, v209
	v_fma_f32 v205, v205, v210, v212
	v_div_fixup_f32 v207, v205, v207, v209
	v_rcp_f32_e32 v209, v206
	v_mul_f32_e32 v106, v62, v62
	v_mul_f32_e32 v107, v63, v63
	v_fma_f32 v210, -v206, v209, 1.0
	v_fmac_f32_e32 v209, v210, v209
	v_mul_f32_e32 v211, v208, v209
	v_fma_f32 v212, -v206, v211, v208
	v_fmac_f32_e32 v211, v212, v209
	v_fma_f32 v205, -v206, v211, v208
	v_add_f32_e32 v212, v48, v74
	v_add_f32_e32 v213, v49, v75
	v_fma_f32 v205, v205, v209, v211
	v_mul_f32_e32 v74, v212, v212
	v_mul_f32_e32 v75, v213, v213
	v_div_fixup_f32 v206, v205, v206, v208
	v_add_f32_e32 v208, v50, v102
	v_add_f32_e32 v209, v51, v103
	v_add_f32_e32 v74, v74, v95
	v_mul_f32_e32 v210, v208, v208
	v_mul_f32_e32 v211, v209, v209
	v_add_f32_e32 v74, v75, v74
	v_add_f32_e32 v74, v210, v74
	v_add_f32_e32 v74, v211, v74
	v_add_f32_e32 v102, v54, v110
	v_add_f32_e32 v103, v55, v111
	v_add_f32_e32 v74, v214, v74
	v_mul_f32_e32 v110, v102, v102
	v_mul_f32_e32 v111, v103, v103
	v_add_f32_e32 v74, v215, v74
	v_add_f32_e32 v74, v110, v74
	v_add_f32_e32 v74, v111, v74
	v_add_f32_e32 v74, v104, v74
	v_add_f32_e32 v74, v105, v74
	v_add_f32_e32 v74, v106, v74
	v_add_f32_e32 v74, v107, v74
	ds_bpermute_b32 v75, v97, v74
	s_waitcnt lgkmcnt(0)
; DI size_t kblk(int row, int col, int nrows) { return ((size_t)(col >> 5) * nrows + row) * 32 + (col & 31); }
; DI unsigned pk2(float a, float b) { hwf32x2 f = {a, b}; hwbf16x2 r = __builtin_convertvector(f, hwbf16x2); return __builtin_bit_cast(unsigned, r); }
; DI float sigmoidf_(float z) { return 1.f / (1.f + __expf(-z)); }
; DI float siluf_(float z) { return z / (1.f + __expf(-z)); }
; template <int MX, bool OUT>
; DI void rec_chunk(const Params& p, int l, int b, int h, int dir, int T0, unsigned char* smem, f32x4 (&St)[4], float& nst, float& dtot, int tid, const RecRaw& raw) {
;     ...
;       ss += __shfl_xor(ss, 16);
;       ss += __shfl_xor(ss, 32);
;       const float rstd = rsqrtf(ss * (1.f / 64.f) + EPS);
;       const float* gvec = (MX ? p.ml_g : p.hg_g) + l * 64;
; #pragma unroll
;       for (int a = 0; a < 4; ++a) {
;         const int v0 = 16 * a + 4 * g;
;         const uint2 gt = *(const uint2*)(prow + GATE + cb + v0);
;         const float4 gg = *(const float4*)(gvec + v0);
;         float y0 = O[a][0] * rstd * gg.x * siluf_(__uint_as_float(gt.x << 16));
;         float y1 = O[a][1] * rstd * gg.y * siluf_(__uint_as_float(gt.x & 0xffff0000u));
;         float y2 = O[a][2] * rstd * gg.z * siluf_(__uint_as_float(gt.y << 16));
;         float y3 = O[a][3] * rstd * gg.w * siluf_(__uint_as_float(gt.y & 0xffff0000u));
;         if (MX == 1) {
;           const uint2 og = *(const uint2*)(prow + D_OG + h * 64 + v0);
;           y0 *= sigmoidf_(__uint_as_float(og.x << 16)); y1 *= sigmoidf_(__uint_as_float(og.x & 0xffff0000u));
;           y2 *= sigmoidf_(__uint_as_float(og.y << 16)); y3 *= sigmoidf_(__uint_as_float(og.y & 0xffff0000u));
;         }
;         *(uint2*)(MIX + kblk((int)orow, cb + v0, ROWS)) = make_uint2(pk2(y0, y1), pk2(y2, y3));
	v_add_f32_e32 v74, v74, v75
	ds_bpermute_b32 v69, v69, v74
	s_waitcnt lgkmcnt(0)
	v_add_f32_e32 v69, v74, v69
	v_fmamk_f32 v69, v69, 0x3c800000, v162
	v_cmp_gt_f32_e32 vcc, s38, v69
	v_mul_f32_e32 v74, 0x4b800000, v69
	s_nop 0
	v_cndmask_b32_e32 v69, v69, v74, vcc
	v_rsq_f32_e32 v69, v69
	s_nop 0
	v_mul_f32_e32 v74, 0x45800000, v69
	v_cndmask_b32_e32 v74, v69, v74, vcc
	v_mul_f32_e32 v104, v116, v74
	v_mul_f32_e32 v105, v117, v74
	s_nop 0
	v_mul_f32_e32 v56, v56, v104
	v_mul_f32_e32 v57, v57, v105
	v_mul_f32_e32 v104, v112, v74
	v_mul_f32_e32 v105, v113, v74
	v_mul_f32_e32 v56, v118, v56
	v_mul_f32_e32 v57, v119, v57
	v_mul_f32_e32 v58, v58, v104
	v_mul_f32_e32 v59, v59, v105
	v_cvt_pk_bf16_f32 v56, v56, v57
	v_mul_f32_e32 v58, v206, v58
	v_mul_f32_e32 v59, v207, v59
	s_nop 0
	v_cvt_pk_bf16_f32 v57, v58, v59
	global_store_dwordx2 v[100:101], v[56:57], off
	global_load_dwordx2 v[100:101], v[72:73], off offset:32
	s_nop 0
	global_load_dwordx4 v[56:59], v[88:89], off offset:64
	s_waitcnt vmcnt(0) lgkmcnt(0)
	v_lshlrev_b32_e32 v69, 16, v100
	v_and_b32_e32 v75, 0xffff0000, v100
	v_mul_f32_e32 v95, 0xbfb8aa3b, v69
	v_exp_f32_e32 v104, v95
	v_mul_f32_e32 v95, 0xbfb8aa3b, v75
	v_exp_f32_e32 v105, v95
	v_mul_f32_e32 v106, v212, v74
	v_mul_f32_e32 v107, v213, v74
	v_add_f32_e32 v104, 1.0, v104
	v_add_f32_e32 v105, 1.0, v105
	s_nop 0
	v_rcp_f32_e32 v97, v105
	v_mul_f32_e32 v56, v56, v106
	v_mul_f32_e32 v57, v57, v107
	v_fma_f32 v100, -v105, v97, 1.0
	v_fmac_f32_e32 v97, v100, v97
	v_mul_f32_e32 v106, v75, v97
	v_fma_f32 v107, -v105, v106, v75
	v_fmac_f32_e32 v106, v107, v97
	v_fma_f32 v95, -v105, v106, v75
	v_fma_f32 v95, v95, v97, v106
	v_div_fixup_f32 v105, v95, v105, v75
	v_rcp_f32_e32 v95, v104
	s_nop 0
	v_fma_f32 v97, -v104, v95, 1.0
	v_fmac_f32_e32 v95, v97, v95
	v_mul_f32_e32 v100, v69, v95
	v_fma_f32 v106, -v104, v100, v69
	v_fmac_f32_e32 v100, v106, v95
	v_fma_f32 v75, -v104, v100, v69
	v_fma_f32 v75, v75, v95, v100
	v_div_fixup_f32 v104, v75, v104, v69
	v_lshlrev_b32_e32 v69, 16, v101
	v_and_b32_e32 v75, 0xffff0000, v101
	v_mul_f32_e32 v95, 0xbfb8aa3b, v69
	v_exp_f32_e32 v100, v95
	v_mul_f32_e32 v95, 0xbfb8aa3b, v75
	v_exp_f32_e32 v101, v95
	v_mul_f32_e32 v56, v104, v56
	v_mul_f32_e32 v57, v105, v57
	v_mul_f32_e32 v104, v208, v74
	v_mul_f32_e32 v105, v209, v74
	v_cvt_pk_bf16_f32 v56, v56, v57
	v_add_f32_e32 v100, 1.0, v100
	v_add_f32_e32 v101, 1.0, v101
	v_mul_f32_e32 v58, v58, v104
	v_mul_f32_e32 v59, v59, v105
	v_rcp_f32_e32 v97, v101
	s_nop 0
	v_fma_f32 v104, -v101, v97, 1.0
	v_fmac_f32_e32 v97, v104, v97
	v_mul_f32_e32 v105, v75, v97
	v_fma_f32 v106, -v101, v105, v75
	v_fmac_f32_e32 v105, v106, v97
	v_fma_f32 v95, -v101, v105, v75
	v_fma_f32 v95, v95, v97, v105
	v_div_fixup_f32 v101, v95, v101, v75
	v_rcp_f32_e32 v95, v100
	s_nop 0
	v_fma_f32 v97, -v100, v95, 1.0
	v_fmac_f32_e32 v95, v97, v95
	v_mul_f32_e32 v104, v69, v95
	v_fma_f32 v105, -v100, v104, v69
	v_fmac_f32_e32 v104, v105, v95
	v_fma_f32 v75, -v100, v104, v69
	v_fma_f32 v75, v75, v95, v104
	v_div_fixup_f32 v100, v75, v100, v69
	v_mul_f32_e32 v58, v100, v58
	v_mul_f32_e32 v59, v101, v59
	s_nop 0
	v_cvt_pk_bf16_f32 v57, v58, v59
	global_store_dwordx2 v[70:71], v[56:57], off
	global_load_dwordx2 v[70:71], v[72:73], off offset:64
	s_nop 0
	global_load_dwordx4 v[56:59], v[88:89], off offset:128
	s_waitcnt vmcnt(0) lgkmcnt(0)
; DI size_t kblk(int row, int col, int nrows) { return ((size_t)(col >> 5) * nrows + row) * 32 + (col & 31); }
; DI unsigned pk2(float a, float b) { hwf32x2 f = {a, b}; hwbf16x2 r = __builtin_convertvector(f, hwbf16x2); return __builtin_bit_cast(unsigned, r); }
; DI float sigmoidf_(float z) { return 1.f / (1.f + __expf(-z)); }
; DI float siluf_(float z) { return z / (1.f + __expf(-z)); }
; template <int MX, bool OUT>
; DI void rec_chunk(const Params& p, int l, int b, int h, int dir, int T0, unsigned char* smem, f32x4 (&St)[4], float& nst, float& dtot, int tid, const RecRaw& raw) {
;     ...
; #pragma unroll
;       for (int a = 0; a < 4; ++a) {
;         const int v0 = 16 * a + 4 * g;
;         const uint2 gt = *(const uint2*)(prow + GATE + cb + v0);
;         const float4 gg = *(const float4*)(gvec + v0);
;         float y0 = O[a][0] * rstd * gg.x * siluf_(__uint_as_float(gt.x << 16));
;         float y1 = O[a][1] * rstd * gg.y * siluf_(__uint_as_float(gt.x & 0xffff0000u));
;         float y2 = O[a][2] * rstd * gg.z * siluf_(__uint_as_float(gt.y << 16));
;         float y3 = O[a][3] * rstd * gg.w * siluf_(__uint_as_float(gt.y & 0xffff0000u));
;         if (MX == 1) {
;           const uint2 og = *(const uint2*)(prow + D_OG + h * 64 + v0);
;           y0 *= sigmoidf_(__uint_as_float(og.x << 16)); y1 *= sigmoidf_(__uint_as_float(og.x & 0xffff0000u));
;           y2 *= sigmoidf_(__uint_as_float(og.y << 16)); y3 *= sigmoidf_(__uint_as_float(og.y & 0xffff0000u));
;         }
;         *(uint2*)(MIX + kblk((int)orow, cb + v0, ROWS)) = make_uint2(pk2(y0, y1), pk2(y2, y3));
	v_lshlrev_b32_e32 v69, 16, v70
	v_and_b32_e32 v70, 0xffff0000, v70
	v_mul_f32_e32 v75, 0xbfb8aa3b, v69
	v_exp_f32_e32 v100, v75
	v_mul_f32_e32 v104, v108, v74
	v_mul_f32_e32 v105, v109, v74
	v_mul_f32_e32 v75, 0xbfb8aa3b, v70
	v_exp_f32_e32 v101, v75
	v_mul_f32_e32 v56, v104, v56
	v_mul_f32_e32 v57, v105, v57
	v_add_f32_e32 v100, 1.0, v100
	v_add_f32_e32 v101, 1.0, v101
	s_nop 0
	v_rcp_f32_e32 v95, v101
	s_nop 0
	v_fma_f32 v97, -v101, v95, 1.0
	v_fmac_f32_e32 v95, v97, v95
	v_mul_f32_e32 v104, v70, v95
	v_fma_f32 v105, -v101, v104, v70
	v_fmac_f32_e32 v104, v105, v95
	v_fma_f32 v75, -v101, v104, v70
	v_fma_f32 v75, v75, v95, v104
	v_div_fixup_f32 v101, v75, v101, v70
	v_rcp_f32_e32 v75, v100
	s_nop 0
	v_fma_f32 v95, -v100, v75, 1.0
	v_fmac_f32_e32 v75, v95, v75
	v_mul_f32_e32 v97, v69, v75
	v_fma_f32 v104, -v100, v97, v69
	v_fmac_f32_e32 v97, v104, v75
	v_fma_f32 v70, -v100, v97, v69
	v_fma_f32 v70, v70, v75, v97
	v_div_fixup_f32 v100, v70, v100, v69
	v_lshlrev_b32_e32 v69, 16, v71
	v_and_b32_e32 v75, 0xffff0000, v71
	v_mul_f32_e32 v70, 0xbfb8aa3b, v69
	v_mul_f32_e32 v71, 0xbfb8aa3b, v75
	v_exp_f32_e32 v70, v70
	v_exp_f32_e32 v71, v71
	v_mul_f32_e32 v56, v56, v100
	v_mul_f32_e32 v57, v57, v101
	v_mul_f32_e32 v100, v102, v74
	v_mul_f32_e32 v101, v103, v74
	v_cvt_pk_bf16_f32 v56, v56, v57
	v_add_f32_e32 v70, 1.0, v70
	v_add_f32_e32 v71, 1.0, v71
	v_mul_f32_e32 v58, v100, v58
	v_mul_f32_e32 v59, v101, v59
	v_rcp_f32_e32 v97, v71
	s_nop 0
	v_fma_f32 v100, -v71, v97, 1.0
	v_fmac_f32_e32 v97, v100, v97
	v_mul_f32_e32 v101, v75, v97
	v_fma_f32 v102, -v71, v101, v75
	v_fmac_f32_e32 v101, v102, v97
	v_fma_f32 v95, -v71, v101, v75
	v_fma_f32 v95, v95, v97, v101
	v_div_fixup_f32 v71, v95, v71, v75
	v_rcp_f32_e32 v95, v70
	s_nop 0
	v_fma_f32 v97, -v70, v95, 1.0
	v_fmac_f32_e32 v95, v97, v95
	v_mul_f32_e32 v100, v69, v95
	v_fma_f32 v101, -v70, v100, v69
	v_fmac_f32_e32 v100, v101, v95
	v_fma_f32 v75, -v70, v100, v69
	v_fma_f32 v75, v75, v95, v100
	v_div_fixup_f32 v70, v75, v70, v69
	v_mul_f32_e32 v58, v58, v70
	v_mul_f32_e32 v59, v59, v71
	v_mul_f32_e32 v64, v64, v74
	v_mul_f32_e32 v65, v65, v74
	v_cvt_pk_bf16_f32 v57, v58, v59
	global_store_dwordx2 v[66:67], v[56:57], off
	global_load_dwordx2 v[66:67], v[72:73], off offset:96
	v_mov_b32_e32 v97, v161
	global_load_dwordx4 v[56:59], v[88:89], off offset:192
	s_waitcnt vmcnt(0) lgkmcnt(0)
	v_lshlrev_b32_e32 v69, 16, v66
	v_and_b32_e32 v66, 0xffff0000, v66
	v_mul_f32_e32 v70, 0xbfb8aa3b, v69
	v_mul_f32_e32 v56, v64, v56
	v_mul_f32_e32 v57, v65, v57
	v_mul_f32_e32 v64, 0xbfb8aa3b, v66
	v_exp_f32_e32 v70, v70
	v_exp_f32_e32 v71, v64
	s_nop 0
	v_add_f32_e32 v64, 1.0, v70
	v_add_f32_e32 v65, 1.0, v71
	s_nop 0
	v_rcp_f32_e32 v71, v65
	s_nop 0
	v_fma_f32 v72, -v65, v71, 1.0
	v_fmac_f32_e32 v71, v72, v71
	v_mul_f32_e32 v73, v66, v71
	v_fma_f32 v75, -v65, v73, v66
	v_fmac_f32_e32 v73, v75, v71
	v_fma_f32 v70, -v65, v73, v66
	v_fma_f32 v70, v70, v71, v73
	v_div_fixup_f32 v65, v70, v65, v66
	v_rcp_f32_e32 v70, v64
	v_mul_f32_e32 v62, v62, v74
	v_mul_f32_e32 v63, v63, v74
	v_fma_f32 v71, -v64, v70, 1.0
	v_fmac_f32_e32 v70, v71, v70
	v_mul_f32_e32 v72, v69, v70
	v_fma_f32 v73, -v64, v72, v69
	v_fmac_f32_e32 v72, v73, v70
	v_fma_f32 v66, -v64, v72, v69
	v_fma_f32 v66, v66, v70, v72
	v_div_fixup_f32 v64, v66, v64, v69
	v_lshlrev_b32_e32 v66, 16, v67
	v_and_b32_e32 v67, 0xffff0000, v67
	v_mul_f32_e32 v64, v56, v64
	v_mul_f32_e32 v65, v57, v65
	v_mul_f32_e32 v56, 0xbfb8aa3b, v66
	v_mul_f32_e32 v57, 0xbfb8aa3b, v67
	v_exp_f32_e32 v56, v56
	v_exp_f32_e32 v57, v57
	v_mul_f32_e32 v58, v62, v58
	v_mul_f32_e32 v59, v63, v59
	v_add_f32_e32 v56, 1.0, v56
	v_add_f32_e32 v57, 1.0, v57
	s_nop 0
	v_rcp_f32_e32 v63, v57
	s_nop 0
	v_fma_f32 v69, -v57, v63, 1.0
	v_fmac_f32_e32 v63, v69, v63
	v_mul_f32_e32 v70, v67, v63
	v_fma_f32 v71, -v57, v70, v67
	v_fmac_f32_e32 v70, v71, v63
	v_fma_f32 v62, -v57, v70, v67
	v_fma_f32 v62, v62, v63, v70
	v_div_fixup_f32 v57, v62, v57, v67
	v_rcp_f32_e32 v63, v56
	s_mov_b64 s[26:27], 0
	v_fma_f32 v67, -v56, v63, 1.0
	v_fmac_f32_e32 v63, v67, v63
	v_mul_f32_e32 v69, v66, v63
	v_fma_f32 v70, -v56, v69, v66
	v_fmac_f32_e32 v69, v70, v63
	v_fma_f32 v62, -v56, v69, v66
	v_fma_f32 v62, v62, v63, v69
	v_div_fixup_f32 v56, v62, v56, v66
	v_mul_f32_e32 v56, v58, v56
	v_mul_f32_e32 v57, v59, v57
	v_cvt_pk_bf16_f32 v62, v64, v65
	v_lshl_add_u64 v[58:59], v[60:61], 0, v[96:97]
	global_store_dword v[58:59], v62, off
